# GEMM mainloops: issue first 2 MFMAs of each compute segment before the pre-compute barrier (hide barrier handoff bubble)
# speedup vs baseline: 1.0031x; 1.0031x over previous
; #define PG8_STAGE(bufoff, gbase, voff) do { _Pragma("unroll") for (int _i = 0; _i < 2; ++_i) \
;         __builtin_amdgcn_global_load_lds((const unsigned*)((const char*)(gbase) + (voff)[_i]), (PG8_LAS unsigned*)(lds + (bufoff) + ldsw + _i * 8192), 16, 0, 0); } while (0)
; #define PG8_LDA(dst, b, h) do { _Pragma("unroll") for (int m = 0; m < 4; ++m) _Pragma("unroll") for (int k = 0; k < 2; ++k) dst[m][k] = *(const PG8_LAS bf16x8*)(lds + PG8_SA(b, h) + aoff + m * 2048 + k * 1024); } while (0)
; #define PG8_LDB(dst, b, h) do { _Pragma("unroll") for (int n = 0; n < 2; ++n) _Pragma("unroll") for (int k = 0; k < 2; ++k) dst[n][k] = *(const PG8_LAS bf16x8*)(lds + PG8_SB(b, h) + boff + n * 2048 + k * 1024); } while (0)
; #define PG8_MMA(ai, bj, At, Bt) do { __builtin_amdgcn_s_setprio(1); _Pragma("unroll") for (int m = 0; m < 4; ++m) _Pragma("unroll") for (int n = 0; n < 2; ++n) _Pragma("unroll") for (int k = 0; k < 2; ++k) \
;         acc[ai][bj][m][n] = __builtin_amdgcn_mfma_f32_16x16x32_bf16(Bt[n][k], At[m][k], acc[ai][bj][m][n], 0, 0, 0); __builtin_amdgcn_s_setprio(0); } while (0)
; #define PG8_WAIT_V(n) asm volatile("s_waitcnt vmcnt(" #n ")" ::: "memory")
; #define PG8_WAIT_L(n) asm volatile("s_waitcnt lgkmcnt(" #n ")" ::: "memory")
; #define PG8_BAR __builtin_amdgcn_s_barrier()
; template <class Epi, class Sched, bool ALIGN_EPI = false, bool SP2 = false>
; __device__ __forceinline__ void gemm_phase(PG8_LAS unsigned char* lds, const Gemm g, const Sched& S, const Epi& E) {
;     ...
;         for (int t = 0; t < nt; t += 2) {
;             const bool last = (t == nt - 2);
;             const char* a1 = cA + (size_t)(t + 1) * kstep;
;             const char* a2 = last ? nA : cA + (size_t)(t + 2) * kstep; const char* b2 = last ? nB : cB + (size_t)(t + 2) * kstep;
;             const char* a3 = a2 + kstep; const char* b3 = b2 + kstep;
;             if (last && has_next) S.a_ready(nxt);
;             if (last) E.pre(lds, cur, wid, tid);
;             if constexpr (SP2) {
;             PG8_LDB(B0, 0, 0); PG8_LDB(B1, 0, 1); PG8_SCHED; PG8_LDA(At, 0, 0); PG8_STAGE(PG8_SA(1, 1), a1 + hstep, voffA);
;             PG8_WAIT_V(8); PG8_WAIT_L(0); PG8_BAR; PG8_MMA(0, 0, At, B0); PG8_MMA(0, 1, At, B1); PG8_BAR; PG8_SCHED;
;             PG8_LDA(At, 0, 1); PG8_STAGE(PG8_SB(0, 0), b2, voffB); PG8_STAGE(PG8_SB(0, 1), b2 + hstepB, voffB); PG8_STAGE(PG8_SA(0, 0), a2, voffA);
.LBB0_135:
	ds_read_b128 v[28:31], v200
	ds_read_b128 v[36:39], v200 offset:1024
	ds_read_b128 v[40:43], v200 offset:2048
	ds_read_b128 v[44:47], v200 offset:3072
	ds_read_b128 v[48:51], v201
	ds_read_b128 v[52:55], v201 offset:1024
	ds_read_b128 v[152:155], v201 offset:2048
	ds_read_b128 v[156:159], v201 offset:3072
	s_add_u32 s12, s10, 0xfffc0080
	s_addc_u32 s13, s11, -1
	s_cmp_eq_u32 s19, 12
	s_cselect_b32 s71, s9, s13
	s_cselect_b32 s70, s14, s12
	s_cselect_b32 s13, s15, s18
	s_cselect_b32 s12, s16, s17
	v_lshl_add_u64 v[190:191], s[10:11], 0, v[180:181]
	s_add_i32 m0, s37, 0xc000
	ds_read_b128 v[160:163], v202
	ds_read_b128 v[164:167], v202 offset:1024
	ds_read_b128 v[210:213], v202 offset:2048
	ds_read_b128 v[216:219], v202 offset:3072
	ds_read_b128 v[220:223], v202 offset:4096
	ds_read_b128 v[224:227], v202 offset:5120
	ds_read_b128 v[228:231], v202 offset:6144
	ds_read_b128 v[232:235], v202 offset:7168
	global_load_lds_dwordx4 v[190:191], off
	v_lshl_add_u64 v[190:191], s[10:11], 0, v[182:183]
	s_add_i32 m0, s37, 0xe000
	s_nop 0
	global_load_lds_dwordx4 v[190:191], off
	s_waitcnt vmcnt(8)
	s_waitcnt lgkmcnt(0)
	v_mfma_f32_16x16x32_bf16 v[148:151], v[28:31], v[160:163], v[148:151]
	v_mfma_f32_16x16x32_bf16 v[144:147], v[40:43], v[160:163], v[144:147]
	s_barrier
	s_setprio 1
	s_waitcnt lgkmcnt(0)
	v_mfma_f32_16x16x32_bf16 v[132:135], v[28:31], v[210:213], v[132:135]
	v_mfma_f32_16x16x32_bf16 v[128:131], v[40:43], v[210:213], v[128:131]
	v_mfma_f32_16x16x32_bf16 v[116:119], v[28:31], v[220:223], v[116:119]
	v_mfma_f32_16x16x32_bf16 v[112:115], v[40:43], v[220:223], v[112:115]
	v_mfma_f32_16x16x32_bf16 v[100:103], v[28:31], v[228:231], v[100:103]
	v_mfma_f32_16x16x32_bf16 v[96:99], v[40:43], v[228:231], v[96:99]
	v_mfma_f32_16x16x32_bf16 v[148:151], v[36:39], v[164:167], v[148:151]
	v_mfma_f32_16x16x32_bf16 v[144:147], v[44:47], v[164:167], v[144:147]
	v_mfma_f32_16x16x32_bf16 v[132:135], v[36:39], v[216:219], v[132:135]
	v_mfma_f32_16x16x32_bf16 v[128:131], v[44:47], v[216:219], v[128:131]
	v_mfma_f32_16x16x32_bf16 v[116:119], v[36:39], v[224:227], v[116:119]
	v_mfma_f32_16x16x32_bf16 v[112:115], v[44:47], v[224:227], v[112:115]
	v_mfma_f32_16x16x32_bf16 v[100:103], v[36:39], v[232:235], v[100:103]
	v_mfma_f32_16x16x32_bf16 v[96:99], v[44:47], v[232:235], v[96:99]
	s_setprio 0
	s_setprio 1
	v_mfma_f32_16x16x32_bf16 v[140:143], v[48:51], v[160:163], v[140:143]
	v_mfma_f32_16x16x32_bf16 v[136:139], v[152:155], v[160:163], v[136:139]
	v_mfma_f32_16x16x32_bf16 v[124:127], v[48:51], v[210:213], v[124:127]
	v_mfma_f32_16x16x32_bf16 v[120:123], v[152:155], v[210:213], v[120:123]
	v_mfma_f32_16x16x32_bf16 v[108:111], v[48:51], v[220:223], v[108:111]
	v_mfma_f32_16x16x32_bf16 v[104:107], v[152:155], v[220:223], v[104:107]
	v_mfma_f32_16x16x32_bf16 v[92:95], v[48:51], v[228:231], v[92:95]
	v_mfma_f32_16x16x32_bf16 v[88:91], v[152:155], v[228:231], v[88:91]
	v_mfma_f32_16x16x32_bf16 v[140:143], v[52:55], v[164:167], v[140:143]
	v_mfma_f32_16x16x32_bf16 v[136:139], v[156:159], v[164:167], v[136:139]
	v_mfma_f32_16x16x32_bf16 v[124:127], v[52:55], v[216:219], v[124:127]
	v_mfma_f32_16x16x32_bf16 v[120:123], v[156:159], v[216:219], v[120:123]
	v_mfma_f32_16x16x32_bf16 v[108:111], v[52:55], v[224:227], v[108:111]
	v_mfma_f32_16x16x32_bf16 v[104:107], v[156:159], v[224:227], v[104:107]
	v_mfma_f32_16x16x32_bf16 v[92:95], v[52:55], v[232:235], v[92:95]
	v_mfma_f32_16x16x32_bf16 v[88:91], v[156:159], v[232:235], v[88:91]
	s_setprio 0
	s_barrier
	s_add_i32 s20, s93, s80
	v_lshl_add_u64 v[190:191], s[12:13], 0, v[170:171]
	s_mov_b32 m0, s20
	ds_read_b128 v[160:163], v202 offset:16384
	ds_read_b128 v[164:167], v202 offset:17408
	ds_read_b128 v[210:213], v202 offset:18432
	ds_read_b128 v[216:219], v202 offset:19456
	ds_read_b128 v[220:223], v202 offset:20480
	ds_read_b128 v[224:227], v202 offset:21504
	ds_read_b128 v[228:231], v202 offset:22528
	ds_read_b128 v[232:235], v202 offset:23552
	global_load_lds_dwordx4 v[190:191], off
	s_add_i32 m0, s20, 0x2000
	s_add_u32 s20, s12, 0x10000
	v_lshl_add_u64 v[240:241], s[12:13], 0, v[174:175]
	s_addc_u32 s21, s13, 0
	s_add_i32 s22, s94, s80
	global_load_lds_dwordx4 v[240:241], off
	v_lshl_add_u64 v[236:237], s[20:21], 0, v[170:171]
	s_mov_b32 m0, s22
	v_lshl_add_u64 v[242:243], s[70:71], 0, v[168:169]
	global_load_lds_dwordx4 v[236:237], off
	v_lshl_add_u64 v[236:237], s[20:21], 0, v[174:175]
	s_add_i32 m0, s22, 0x2000
	v_lshl_add_u64 v[244:245], s[70:71], 0, v[172:173]
	global_load_lds_dwordx4 v[236:237], off
	s_mov_b32 m0, s37
	s_nop 0
	global_load_lds_dwordx4 v[242:243], off
	s_mov_b32 m0, s81
	s_nop 0
	global_load_lds_dwordx4 v[244:245], off
	s_waitcnt vmcnt(8)
	s_waitcnt lgkmcnt(0)
	v_mfma_f32_16x16x32_bf16 v[84:87], v[28:31], v[160:163], v[84:87]
	v_mfma_f32_16x16x32_bf16 v[80:83], v[40:43], v[160:163], v[80:83]
	s_barrier
; #define PG8_STAGE(bufoff, gbase, voff) do { _Pragma("unroll") for (int _i = 0; _i < 2; ++_i) \
;         __builtin_amdgcn_global_load_lds((const unsigned*)((const char*)(gbase) + (voff)[_i]), (PG8_LAS unsigned*)(lds + (bufoff) + ldsw + _i * 8192), 16, 0, 0); } while (0)
; #define PG8_LDA(dst, b, h) do { _Pragma("unroll") for (int m = 0; m < 4; ++m) _Pragma("unroll") for (int k = 0; k < 2; ++k) dst[m][k] = *(const PG8_LAS bf16x8*)(lds + PG8_SA(b, h) + aoff + m * 2048 + k * 1024); } while (0)
; #define PG8_LDB(dst, b, h) do { _Pragma("unroll") for (int n = 0; n < 2; ++n) _Pragma("unroll") for (int k = 0; k < 2; ++k) dst[n][k] = *(const PG8_LAS bf16x8*)(lds + PG8_SB(b, h) + boff + n * 2048 + k * 1024); } while (0)
; #define PG8_MMA(ai, bj, At, Bt) do { __builtin_amdgcn_s_setprio(1); _Pragma("unroll") for (int m = 0; m < 4; ++m) _Pragma("unroll") for (int n = 0; n < 2; ++n) _Pragma("unroll") for (int k = 0; k < 2; ++k) \
;         acc[ai][bj][m][n] = __builtin_amdgcn_mfma_f32_16x16x32_bf16(Bt[n][k], At[m][k], acc[ai][bj][m][n], 0, 0, 0); __builtin_amdgcn_s_setprio(0); } while (0)
; #define PG8_WAIT_V(n) asm volatile("s_waitcnt vmcnt(" #n ")" ::: "memory")
; #define PG8_WAIT_L(n) asm volatile("s_waitcnt lgkmcnt(" #n ")" ::: "memory")
; #define PG8_BAR __builtin_amdgcn_s_barrier()
; #define PG8_SCHED __builtin_amdgcn_sched_barrier(0)
; template <class Epi, class Sched, bool ALIGN_EPI = false, bool SP2 = false>
; __device__ __forceinline__ void gemm_phase(PG8_LAS unsigned char* lds, const Gemm g, const Sched& S, const Epi& E) {
;     ...
;             PG8_WAIT_V(8); PG8_WAIT_L(0); PG8_BAR; PG8_MMA(1, 0, At, B0); PG8_MMA(1, 1, At, B1); PG8_BAR; PG8_SCHED;
;             PG8_LDB(B0, 1, 0); PG8_LDB(B1, 1, 1); PG8_SCHED; PG8_LDA(At, 1, 0); PG8_STAGE(PG8_SA(0, 1), a2 + hstep, voffA);
;             PG8_WAIT_V(8); PG8_WAIT_L(0); PG8_BAR; PG8_MMA(0, 0, At, B0); PG8_MMA(0, 1, At, B1); PG8_BAR; PG8_SCHED;
	s_setprio 1
	s_waitcnt lgkmcnt(0)
	v_mfma_f32_16x16x32_bf16 v[68:71], v[28:31], v[210:213], v[68:71]
	v_mfma_f32_16x16x32_bf16 v[64:67], v[40:43], v[210:213], v[64:67]
	v_mfma_f32_16x16x32_bf16 v[32:35], v[28:31], v[220:223], v[32:35]
	v_mfma_f32_16x16x32_bf16 v[24:27], v[40:43], v[220:223], v[24:27]
	v_mfma_f32_16x16x32_bf16 v[12:15], v[28:31], v[228:231], v[12:15]
	v_mfma_f32_16x16x32_bf16 v[8:11], v[40:43], v[228:231], v[8:11]
	v_mfma_f32_16x16x32_bf16 v[84:87], v[36:39], v[164:167], v[84:87]
	v_mfma_f32_16x16x32_bf16 v[80:83], v[44:47], v[164:167], v[80:83]
	v_mfma_f32_16x16x32_bf16 v[68:71], v[36:39], v[216:219], v[68:71]
	v_mfma_f32_16x16x32_bf16 v[64:67], v[44:47], v[216:219], v[64:67]
	v_mfma_f32_16x16x32_bf16 v[32:35], v[36:39], v[224:227], v[32:35]
	v_mfma_f32_16x16x32_bf16 v[24:27], v[44:47], v[224:227], v[24:27]
	v_mfma_f32_16x16x32_bf16 v[12:15], v[36:39], v[232:235], v[12:15]
	v_mfma_f32_16x16x32_bf16 v[8:11], v[44:47], v[232:235], v[8:11]
	s_setprio 0
	s_setprio 1
	v_mfma_f32_16x16x32_bf16 v[20:23], v[48:51], v[220:223], v[20:23]
	v_mfma_f32_16x16x32_bf16 v[16:19], v[152:155], v[220:223], v[16:19]
	v_mfma_f32_16x16x32_bf16 v[4:7], v[48:51], v[228:231], v[4:7]
	v_mfma_f32_16x16x32_bf16 v[0:3], v[152:155], v[228:231], v[0:3]
	v_mfma_f32_16x16x32_bf16 v[28:31], v[48:51], v[160:163], v[76:79]
	v_mfma_f32_16x16x32_bf16 v[36:39], v[152:155], v[160:163], v[72:75]
	v_mfma_f32_16x16x32_bf16 v[40:43], v[48:51], v[210:213], v[60:63]
	v_mfma_f32_16x16x32_bf16 v[44:47], v[152:155], v[210:213], v[56:59]
	v_mfma_f32_16x16x32_bf16 v[20:23], v[52:55], v[224:227], v[20:23]
	v_mfma_f32_16x16x32_bf16 v[16:19], v[156:159], v[224:227], v[16:19]
	v_mfma_f32_16x16x32_bf16 v[4:7], v[52:55], v[232:235], v[4:7]
	v_mfma_f32_16x16x32_bf16 v[0:3], v[156:159], v[232:235], v[0:3]
	v_mfma_f32_16x16x32_bf16 v[28:31], v[52:55], v[164:167], v[28:31]
	v_mfma_f32_16x16x32_bf16 v[36:39], v[156:159], v[164:167], v[36:39]
	v_mfma_f32_16x16x32_bf16 v[40:43], v[52:55], v[216:219], v[40:43]
	v_mfma_f32_16x16x32_bf16 v[44:47], v[156:159], v[216:219], v[44:47]
	s_setprio 0
	s_barrier
	s_add_i32 s22, 0, 0x18000
	s_add_i32 s23, 0, 0x1c000
	v_add_u32_e32 v60, s22, v192
	v_add_u32_e32 v72, s23, v192
	ds_read_b128 v[48:51], v60
	ds_read_b128 v[52:55], v60 offset:1024
	ds_read_b128 v[56:59], v60 offset:2048
	ds_read_b128 v[60:63], v60 offset:3072
	ds_read_b128 v[152:155], v72
	ds_read_b128 v[156:159], v72 offset:1024
	ds_read_b128 v[160:163], v72 offset:2048
	ds_read_b128 v[164:167], v72 offset:3072
	s_add_u32 s20, s70, 0x40000
	s_addc_u32 s21, s71, 0
	s_mov_b32 m0, s82
	v_lshl_add_u64 v[236:237], s[20:21], 0, v[168:169]
	ds_read_b128 v[72:75], v202 offset:32768
	ds_read_b128 v[76:79], v202 offset:33792
	ds_read_b128 v[210:213], v202 offset:34816
	ds_read_b128 v[216:219], v202 offset:35840
	ds_read_b128 v[220:223], v202 offset:36864
	ds_read_b128 v[224:227], v202 offset:37888
	ds_read_b128 v[228:231], v202 offset:38912
	ds_read_b128 v[232:235], v202 offset:39936
	global_load_lds_dwordx4 v[236:237], off
	v_lshl_add_u64 v[236:237], s[20:21], 0, v[172:173]
	s_mov_b32 m0, s83
	s_nop 0
	global_load_lds_dwordx4 v[236:237], off
	s_waitcnt vmcnt(8)
	s_waitcnt lgkmcnt(0)
	v_mfma_f32_16x16x32_bf16 v[148:151], v[48:51], v[72:75], v[148:151]
	v_mfma_f32_16x16x32_bf16 v[144:147], v[56:59], v[72:75], v[144:147]
	s_barrier
	s_setprio 1
	s_waitcnt lgkmcnt(0)
	v_mfma_f32_16x16x32_bf16 v[132:135], v[48:51], v[210:213], v[132:135]
	v_mfma_f32_16x16x32_bf16 v[128:131], v[56:59], v[210:213], v[128:131]
	v_mfma_f32_16x16x32_bf16 v[116:119], v[48:51], v[220:223], v[116:119]
	v_mfma_f32_16x16x32_bf16 v[112:115], v[56:59], v[220:223], v[112:115]
	v_mfma_f32_16x16x32_bf16 v[100:103], v[48:51], v[228:231], v[100:103]
	v_mfma_f32_16x16x32_bf16 v[96:99], v[56:59], v[228:231], v[96:99]
	v_mfma_f32_16x16x32_bf16 v[148:151], v[52:55], v[76:79], v[148:151]
	v_mfma_f32_16x16x32_bf16 v[144:147], v[60:63], v[76:79], v[144:147]
	v_mfma_f32_16x16x32_bf16 v[132:135], v[52:55], v[216:219], v[132:135]
	v_mfma_f32_16x16x32_bf16 v[128:131], v[60:63], v[216:219], v[128:131]
	v_mfma_f32_16x16x32_bf16 v[116:119], v[52:55], v[224:227], v[116:119]
	v_mfma_f32_16x16x32_bf16 v[112:115], v[60:63], v[224:227], v[112:115]
	v_mfma_f32_16x16x32_bf16 v[100:103], v[52:55], v[232:235], v[100:103]
	v_mfma_f32_16x16x32_bf16 v[96:99], v[60:63], v[232:235], v[96:99]
	s_setprio 0
	s_setprio 1
	v_mfma_f32_16x16x32_bf16 v[140:143], v[152:155], v[72:75], v[140:143]
	v_mfma_f32_16x16x32_bf16 v[72:75], v[160:163], v[72:75], v[136:139]
	v_mfma_f32_16x16x32_bf16 v[136:139], v[164:167], v[76:79], v[72:75]
	v_mfma_f32_16x16x32_bf16 v[72:75], v[152:155], v[210:213], v[124:127]
	v_mfma_f32_16x16x32_bf16 v[124:127], v[156:159], v[216:219], v[72:75]
	v_mfma_f32_16x16x32_bf16 v[72:75], v[160:163], v[210:213], v[120:123]
	v_mfma_f32_16x16x32_bf16 v[120:123], v[164:167], v[216:219], v[72:75]
	v_mfma_f32_16x16x32_bf16 v[72:75], v[152:155], v[220:223], v[108:111]
	v_mfma_f32_16x16x32_bf16 v[108:111], v[156:159], v[224:227], v[72:75]
	v_mfma_f32_16x16x32_bf16 v[72:75], v[160:163], v[220:223], v[104:107]
	v_mfma_f32_16x16x32_bf16 v[104:107], v[164:167], v[224:227], v[72:75]
	v_mfma_f32_16x16x32_bf16 v[72:75], v[152:155], v[228:231], v[92:95]
	v_mfma_f32_16x16x32_bf16 v[92:95], v[156:159], v[232:235], v[72:75]
	v_mfma_f32_16x16x32_bf16 v[72:75], v[160:163], v[228:231], v[88:91]
	v_mfma_f32_16x16x32_bf16 v[140:143], v[156:159], v[76:79], v[140:143]
	v_mfma_f32_16x16x32_bf16 v[88:91], v[164:167], v[232:235], v[72:75]
	s_setprio 0
	s_barrier
; #define PG8_STAGE(bufoff, gbase, voff) do { _Pragma("unroll") for (int _i = 0; _i < 2; ++_i) \
;         __builtin_amdgcn_global_load_lds((const unsigned*)((const char*)(gbase) + (voff)[_i]), (PG8_LAS unsigned*)(lds + (bufoff) + ldsw + _i * 8192), 16, 0, 0); } while (0)
; #define PG8_LDA(dst, b, h) do { _Pragma("unroll") for (int m = 0; m < 4; ++m) _Pragma("unroll") for (int k = 0; k < 2; ++k) dst[m][k] = *(const PG8_LAS bf16x8*)(lds + PG8_SA(b, h) + aoff + m * 2048 + k * 1024); } while (0)
; #define PG8_MMA(ai, bj, At, Bt) do { __builtin_amdgcn_s_setprio(1); _Pragma("unroll") for (int m = 0; m < 4; ++m) _Pragma("unroll") for (int n = 0; n < 2; ++n) _Pragma("unroll") for (int k = 0; k < 2; ++k) \
;         acc[ai][bj][m][n] = __builtin_amdgcn_mfma_f32_16x16x32_bf16(Bt[n][k], At[m][k], acc[ai][bj][m][n], 0, 0, 0); __builtin_amdgcn_s_setprio(0); } while (0)
; #define PG8_WAIT_V(n) asm volatile("s_waitcnt vmcnt(" #n ")" ::: "memory")
; #define PG8_WAIT_L(n) asm volatile("s_waitcnt lgkmcnt(" #n ")" ::: "memory")
; #define PG8_BAR __builtin_amdgcn_s_barrier()
; #define PG8_SCHED __builtin_amdgcn_sched_barrier(0)
; template <class Epi, class Sched, bool ALIGN_EPI = false, bool SP2 = false>
; __device__ __forceinline__ void gemm_phase(PG8_LAS unsigned char* lds, const Gemm g, const Sched& S, const Epi& E) {
;     ...
;             PG8_LDA(At, 1, 1); PG8_STAGE(PG8_SB(1, 0), b3, voffB); PG8_STAGE(PG8_SB(1, 1), b3 + hstepB, voffB); PG8_STAGE(PG8_SA(1, 0), a3, voffA);
;             PG8_WAIT_V(8); PG8_WAIT_L(0); PG8_BAR; PG8_MMA(1, 0, At, B0); PG8_MMA(1, 1, At, B1); PG8_BAR; PG8_SCHED;
;     ...
;         if constexpr (ALIGN_EPI) { if (wr == 0) PG8_BAR; }
	s_add_i32 s20, s22, s80
	v_lshl_add_u64 v[76:77], v[190:191], 0, s[40:41]
	s_mov_b32 m0, s20
	s_nop 0
	ds_read_b128 v[72:75], v202 offset:49152
	ds_read_b128 v[210:213], v202 offset:50176
	ds_read_b128 v[216:219], v202 offset:51200
	ds_read_b128 v[220:223], v202 offset:52224
	ds_read_b128 v[224:227], v202 offset:53248
	ds_read_b128 v[228:231], v202 offset:54272
	ds_read_b128 v[232:235], v202 offset:55296
	ds_read_b128 v[236:239], v202 offset:56320
	global_load_lds_dwordx4 v[76:77], off
	s_add_i32 m0, s20, 0x2000
	s_add_u32 s12, s12, 0x10080
	v_lshl_add_u64 v[76:77], v[240:241], 0, s[40:41]
	s_addc_u32 s13, s13, 0
	s_add_i32 s20, s23, s80
	global_load_lds_dwordx4 v[76:77], off
	v_lshl_add_u64 v[76:77], s[12:13], 0, v[170:171]
	s_mov_b32 m0, s20
	s_nop 0
	global_load_lds_dwordx4 v[76:77], off
	v_lshl_add_u64 v[76:77], s[12:13], 0, v[174:175]
	s_add_i32 m0, s20, 0x2000
	s_nop 0
	global_load_lds_dwordx4 v[76:77], off
	v_lshl_add_u64 v[76:77], v[242:243], 0, s[40:41]
	s_mov_b32 m0, s86
	s_nop 0
	global_load_lds_dwordx4 v[76:77], off
	v_lshl_add_u64 v[76:77], v[244:245], 0, s[40:41]
	s_mov_b32 m0, s87
	s_nop 0
	global_load_lds_dwordx4 v[76:77], off
	s_waitcnt vmcnt(8)
	s_waitcnt lgkmcnt(0)
	v_mfma_f32_16x16x32_bf16 v[76:79], v[48:51], v[72:75], v[84:87]
	v_mfma_f32_16x16x32_bf16 v[84:87], v[52:55], v[210:213], v[76:79]
	s_barrier
	s_setprio 1
	s_waitcnt lgkmcnt(0)
	v_mfma_f32_16x16x32_bf16 v[76:79], v[56:59], v[72:75], v[80:83]
	v_mfma_f32_16x16x32_bf16 v[68:71], v[48:51], v[216:219], v[68:71]
	v_mfma_f32_16x16x32_bf16 v[64:67], v[56:59], v[216:219], v[64:67]
	v_mfma_f32_16x16x32_bf16 v[32:35], v[48:51], v[224:227], v[32:35]
	v_mfma_f32_16x16x32_bf16 v[24:27], v[56:59], v[224:227], v[24:27]
	v_mfma_f32_16x16x32_bf16 v[12:15], v[48:51], v[232:235], v[12:15]
	v_mfma_f32_16x16x32_bf16 v[8:11], v[56:59], v[232:235], v[8:11]
	v_mfma_f32_16x16x32_bf16 v[80:83], v[60:63], v[210:213], v[76:79]
	v_mfma_f32_16x16x32_bf16 v[68:71], v[52:55], v[220:223], v[68:71]
	v_mfma_f32_16x16x32_bf16 v[64:67], v[60:63], v[220:223], v[64:67]
	v_mfma_f32_16x16x32_bf16 v[32:35], v[52:55], v[228:231], v[32:35]
	v_mfma_f32_16x16x32_bf16 v[24:27], v[60:63], v[228:231], v[24:27]
	v_mfma_f32_16x16x32_bf16 v[12:15], v[52:55], v[236:239], v[12:15]
	v_mfma_f32_16x16x32_bf16 v[8:11], v[60:63], v[236:239], v[8:11]
	s_setprio 0
	s_setprio 1
	v_mfma_f32_16x16x32_bf16 v[28:31], v[152:155], v[72:75], v[28:31]
	v_mfma_f32_16x16x32_bf16 v[76:79], v[156:159], v[210:213], v[28:31]
	v_mfma_f32_16x16x32_bf16 v[28:31], v[160:163], v[72:75], v[36:39]
	v_mfma_f32_16x16x32_bf16 v[72:75], v[164:167], v[210:213], v[28:31]
	v_mfma_f32_16x16x32_bf16 v[28:31], v[152:155], v[216:219], v[40:43]
	v_mfma_f32_16x16x32_bf16 v[60:63], v[156:159], v[220:223], v[28:31]
	v_mfma_f32_16x16x32_bf16 v[28:31], v[160:163], v[216:219], v[44:47]
	v_mfma_f32_16x16x32_bf16 v[20:23], v[152:155], v[224:227], v[20:23]
	v_mfma_f32_16x16x32_bf16 v[16:19], v[160:163], v[224:227], v[16:19]
	v_mfma_f32_16x16x32_bf16 v[4:7], v[152:155], v[232:235], v[4:7]
	v_mfma_f32_16x16x32_bf16 v[0:3], v[160:163], v[232:235], v[0:3]
	v_mfma_f32_16x16x32_bf16 v[56:59], v[164:167], v[220:223], v[28:31]
	v_mfma_f32_16x16x32_bf16 v[20:23], v[156:159], v[228:231], v[20:23]
	v_mfma_f32_16x16x32_bf16 v[16:19], v[164:167], v[228:231], v[16:19]
	v_mfma_f32_16x16x32_bf16 v[4:7], v[156:159], v[236:239], v[4:7]
	v_mfma_f32_16x16x32_bf16 v[0:3], v[164:167], v[236:239], v[0:3]
	s_setprio 0
	s_barrier
	s_add_i32 s19, s19, 2
	s_add_u32 s10, s10, 0x100
	s_addc_u32 s11, s11, 0
	s_add_u32 s17, s17, 0x100
	s_addc_u32 s18, s18, 0
	s_cmp_gt_u32 s19, 13
	s_cbranch_scc0 .LBB0_135
	s_and_b64 vcc, exec, s[42:43]
	s_cbranch_vccz .LBB0_138
	s_barrier

; #define PG8_STAGE(bufoff, gbase, voff) do { _Pragma("unroll") for (int _i = 0; _i < 2; ++_i) \
;         __builtin_amdgcn_global_load_lds((const unsigned*)((const char*)(gbase) + (voff)[_i]), (PG8_LAS unsigned*)(lds + (bufoff) + ldsw + _i * 8192), 16, 0, 0); } while (0)
; #define PG8_LDA(dst, b, h) do { _Pragma("unroll") for (int m = 0; m < 4; ++m) _Pragma("unroll") for (int k = 0; k < 2; ++k) dst[m][k] = *(const PG8_LAS bf16x8*)(lds + PG8_SA(b, h) + aoff + m * 2048 + k * 1024); } while (0)
; #define PG8_LDB(dst, b, h) do { _Pragma("unroll") for (int n = 0; n < 2; ++n) _Pragma("unroll") for (int k = 0; k < 2; ++k) dst[n][k] = *(const PG8_LAS bf16x8*)(lds + PG8_SB(b, h) + boff + n * 2048 + k * 1024); } while (0)
; #define PG8_MMA(ai, bj, At, Bt) do { __builtin_amdgcn_s_setprio(1); _Pragma("unroll") for (int m = 0; m < 4; ++m) _Pragma("unroll") for (int n = 0; n < 2; ++n) _Pragma("unroll") for (int k = 0; k < 2; ++k) \
;         acc[ai][bj][m][n] = __builtin_amdgcn_mfma_f32_16x16x32_bf16(Bt[n][k], At[m][k], acc[ai][bj][m][n], 0, 0, 0); __builtin_amdgcn_s_setprio(0); } while (0)
; #define PG8_WAIT_V(n) asm volatile("s_waitcnt vmcnt(" #n ")" ::: "memory")
; #define PG8_WAIT_L(n) asm volatile("s_waitcnt lgkmcnt(" #n ")" ::: "memory")
; #define PG8_BAR __builtin_amdgcn_s_barrier()
; template <class Epi, class Sched, bool ALIGN_EPI = false, bool SP2 = false>
; __device__ __forceinline__ void gemm_phase(PG8_LAS unsigned char* lds, const Gemm g, const Sched& S, const Epi& E) {
;     ...
;         for (int t = 0; t < nt; t += 2) {
;             const bool last = (t == nt - 2);
;             const char* a1 = cA + (size_t)(t + 1) * kstep;
;             const char* a2 = last ? nA : cA + (size_t)(t + 2) * kstep; const char* b2 = last ? nB : cB + (size_t)(t + 2) * kstep;
;             const char* a3 = a2 + kstep; const char* b3 = b2 + kstep;
;             if (last && has_next) S.a_ready(nxt);
;             if (last) E.pre(lds, cur, wid, tid);
;             if constexpr (SP2) {
;             PG8_LDB(B0, 0, 0); PG8_LDB(B1, 0, 1); PG8_SCHED; PG8_LDA(At, 0, 0); PG8_STAGE(PG8_SA(1, 1), a1 + hstep, voffA);
;             PG8_WAIT_V(8); PG8_WAIT_L(0); PG8_BAR; PG8_MMA(0, 0, At, B0); PG8_MMA(0, 1, At, B1); PG8_BAR; PG8_SCHED;
;             PG8_LDA(At, 0, 1); PG8_STAGE(PG8_SB(0, 0), b2, voffB); PG8_STAGE(PG8_SB(0, 1), b2 + hstepB, voffB); PG8_STAGE(PG8_SA(0, 0), a2, voffA);
.LBB0_433:
	ds_read_b128 v[144:147], v163
	ds_read_b128 v[148:151], v163 offset:1024
	ds_read_b128 v[152:155], v163 offset:2048
	ds_read_b128 v[156:159], v163 offset:3072
	ds_read_b128 v[168:171], v164
	ds_read_b128 v[172:175], v164 offset:1024
	ds_read_b128 v[176:179], v164 offset:2048
	ds_read_b128 v[180:183], v164 offset:3072
	s_add_u32 s74, s72, 0x100
	s_addc_u32 s75, s73, 0
	s_cmp_eq_u32 s71, 12
	s_cselect_b32 s79, s45, s75
	s_cselect_b32 s78, s61, s74
	s_cselect_b32 s77, s43, s69
	s_cselect_b32 s76, s62, s63
	v_lshl_add_u64 v[212:213], s[72:73], 0, v[134:135]
	s_add_i32 m0, s16, 0xc000
	ds_read_b128 v[184:187], v165
	ds_read_b128 v[188:191], v165 offset:1024
	ds_read_b128 v[192:195], v165 offset:2048
	ds_read_b128 v[196:199], v165 offset:3072
	ds_read_b128 v[200:203], v165 offset:4096
	ds_read_b128 v[204:207], v165 offset:5120
	ds_read_b128 v[208:211], v165 offset:6144
	ds_read_b128 v[216:219], v165 offset:7168
	global_load_lds_dwordx4 v[212:213], off
	v_lshl_add_u64 v[212:213], s[72:73], 0, v[136:137]
	s_add_i32 m0, s16, 0xe000
	s_nop 0
	global_load_lds_dwordx4 v[212:213], off
	s_waitcnt vmcnt(8)
	s_waitcnt lgkmcnt(0)
	v_mfma_f32_16x16x32_bf16 v[124:127], v[144:147], v[184:187], v[124:127]
	v_mfma_f32_16x16x32_bf16 v[120:123], v[152:155], v[184:187], v[120:123]
	s_barrier
	s_setprio 1
	s_waitcnt lgkmcnt(0)
	v_mfma_f32_16x16x32_bf16 v[108:111], v[144:147], v[192:195], v[108:111]
	v_mfma_f32_16x16x32_bf16 v[104:107], v[152:155], v[192:195], v[104:107]
	v_mfma_f32_16x16x32_bf16 v[92:95], v[144:147], v[200:203], v[92:95]
	v_mfma_f32_16x16x32_bf16 v[88:91], v[152:155], v[200:203], v[88:91]
	v_mfma_f32_16x16x32_bf16 v[76:79], v[144:147], v[208:211], v[76:79]
	v_mfma_f32_16x16x32_bf16 v[72:75], v[152:155], v[208:211], v[72:75]
	v_mfma_f32_16x16x32_bf16 v[124:127], v[148:151], v[188:191], v[124:127]
	v_mfma_f32_16x16x32_bf16 v[120:123], v[156:159], v[188:191], v[120:123]
	v_mfma_f32_16x16x32_bf16 v[108:111], v[148:151], v[196:199], v[108:111]
	v_mfma_f32_16x16x32_bf16 v[104:107], v[156:159], v[196:199], v[104:107]
	v_mfma_f32_16x16x32_bf16 v[92:95], v[148:151], v[204:207], v[92:95]
	v_mfma_f32_16x16x32_bf16 v[88:91], v[156:159], v[204:207], v[88:91]
	v_mfma_f32_16x16x32_bf16 v[76:79], v[148:151], v[216:219], v[76:79]
	v_mfma_f32_16x16x32_bf16 v[72:75], v[156:159], v[216:219], v[72:75]
	s_setprio 0
	s_setprio 1
	v_mfma_f32_16x16x32_bf16 v[116:119], v[168:171], v[184:187], v[116:119]
	v_mfma_f32_16x16x32_bf16 v[112:115], v[176:179], v[184:187], v[112:115]
	v_mfma_f32_16x16x32_bf16 v[100:103], v[168:171], v[192:195], v[100:103]
	v_mfma_f32_16x16x32_bf16 v[96:99], v[176:179], v[192:195], v[96:99]
	v_mfma_f32_16x16x32_bf16 v[84:87], v[168:171], v[200:203], v[84:87]
	v_mfma_f32_16x16x32_bf16 v[80:83], v[176:179], v[200:203], v[80:83]
	v_mfma_f32_16x16x32_bf16 v[68:71], v[168:171], v[208:211], v[68:71]
	v_mfma_f32_16x16x32_bf16 v[64:67], v[176:179], v[208:211], v[64:67]
	v_mfma_f32_16x16x32_bf16 v[116:119], v[172:175], v[188:191], v[116:119]
	v_mfma_f32_16x16x32_bf16 v[112:115], v[180:183], v[188:191], v[112:115]
	v_mfma_f32_16x16x32_bf16 v[100:103], v[172:175], v[196:199], v[100:103]
	v_mfma_f32_16x16x32_bf16 v[96:99], v[180:183], v[196:199], v[96:99]
	v_mfma_f32_16x16x32_bf16 v[84:87], v[172:175], v[204:207], v[84:87]
	v_mfma_f32_16x16x32_bf16 v[80:83], v[180:183], v[204:207], v[80:83]
	v_mfma_f32_16x16x32_bf16 v[68:71], v[172:175], v[216:219], v[68:71]
	v_mfma_f32_16x16x32_bf16 v[64:67], v[180:183], v[216:219], v[64:67]
	s_setprio 0
	s_barrier
	s_add_i32 s72, s31, s15
	v_lshl_add_u64 v[212:213], s[76:77], 0, v[128:129]
	s_mov_b32 m0, s72
	ds_read_b128 v[184:187], v165 offset:16384
	ds_read_b128 v[188:191], v165 offset:17408
	ds_read_b128 v[192:195], v165 offset:18432
	ds_read_b128 v[196:199], v165 offset:19456
	ds_read_b128 v[200:203], v165 offset:20480
	ds_read_b128 v[204:207], v165 offset:21504
	ds_read_b128 v[208:211], v165 offset:22528
	ds_read_b128 v[216:219], v165 offset:23552
	global_load_lds_dwordx4 v[212:213], off
	s_add_i32 m0, s72, 0x2000
	s_add_u32 s72, s76, 0x40000
	v_lshl_add_u64 v[220:221], s[76:77], 0, v[130:131]
	s_addc_u32 s73, s77, 0
	s_add_i32 s80, s35, s15
	global_load_lds_dwordx4 v[220:221], off
	v_lshl_add_u64 v[222:223], s[72:73], 0, v[128:129]
	s_mov_b32 m0, s80
	v_lshl_add_u64 v[224:225], s[78:79], 0, v[130:131]
	global_load_lds_dwordx4 v[222:223], off
	v_lshl_add_u64 v[222:223], s[72:73], 0, v[130:131]
	s_add_i32 m0, s80, 0x2000
	s_nop 0
	global_load_lds_dwordx4 v[222:223], off
	v_lshl_add_u64 v[222:223], s[78:79], 0, v[128:129]
	s_mov_b32 m0, s16
	s_nop 0
	global_load_lds_dwordx4 v[222:223], off
	s_mov_b32 m0, s17
	s_nop 0
	global_load_lds_dwordx4 v[224:225], off
	s_waitcnt vmcnt(8)
	s_waitcnt lgkmcnt(0)
	v_mfma_f32_16x16x32_bf16 v[60:63], v[144:147], v[184:187], v[60:63]
	v_mfma_f32_16x16x32_bf16 v[56:59], v[152:155], v[184:187], v[56:59]
	s_barrier
; #define PG8_STAGE(bufoff, gbase, voff) do { _Pragma("unroll") for (int _i = 0; _i < 2; ++_i) \
;         __builtin_amdgcn_global_load_lds((const unsigned*)((const char*)(gbase) + (voff)[_i]), (PG8_LAS unsigned*)(lds + (bufoff) + ldsw + _i * 8192), 16, 0, 0); } while (0)
; #define PG8_LDA(dst, b, h) do { _Pragma("unroll") for (int m = 0; m < 4; ++m) _Pragma("unroll") for (int k = 0; k < 2; ++k) dst[m][k] = *(const PG8_LAS bf16x8*)(lds + PG8_SA(b, h) + aoff + m * 2048 + k * 1024); } while (0)
; #define PG8_LDB(dst, b, h) do { _Pragma("unroll") for (int n = 0; n < 2; ++n) _Pragma("unroll") for (int k = 0; k < 2; ++k) dst[n][k] = *(const PG8_LAS bf16x8*)(lds + PG8_SB(b, h) + boff + n * 2048 + k * 1024); } while (0)
; #define PG8_MMA(ai, bj, At, Bt) do { __builtin_amdgcn_s_setprio(1); _Pragma("unroll") for (int m = 0; m < 4; ++m) _Pragma("unroll") for (int n = 0; n < 2; ++n) _Pragma("unroll") for (int k = 0; k < 2; ++k) \
;         acc[ai][bj][m][n] = __builtin_amdgcn_mfma_f32_16x16x32_bf16(Bt[n][k], At[m][k], acc[ai][bj][m][n], 0, 0, 0); __builtin_amdgcn_s_setprio(0); } while (0)
; #define PG8_WAIT_V(n) asm volatile("s_waitcnt vmcnt(" #n ")" ::: "memory")
; #define PG8_WAIT_L(n) asm volatile("s_waitcnt lgkmcnt(" #n ")" ::: "memory")
; #define PG8_BAR __builtin_amdgcn_s_barrier()
; #define PG8_SCHED __builtin_amdgcn_sched_barrier(0)
; template <class Epi, class Sched, bool ALIGN_EPI = false, bool SP2 = false>
; __device__ __forceinline__ void gemm_phase(PG8_LAS unsigned char* lds, const Gemm g, const Sched& S, const Epi& E) {
;     ...
;             PG8_WAIT_V(8); PG8_WAIT_L(0); PG8_BAR; PG8_MMA(1, 0, At, B0); PG8_MMA(1, 1, At, B1); PG8_BAR; PG8_SCHED;
;             PG8_LDB(B0, 1, 0); PG8_LDB(B1, 1, 1); PG8_SCHED; PG8_LDA(At, 1, 0); PG8_STAGE(PG8_SA(0, 1), a2 + hstep, voffA);
;             PG8_WAIT_V(8); PG8_WAIT_L(0); PG8_BAR; PG8_MMA(0, 0, At, B0); PG8_MMA(0, 1, At, B1); PG8_BAR; PG8_SCHED;
	s_setprio 1
	s_waitcnt lgkmcnt(0)
	v_mfma_f32_16x16x32_bf16 v[44:47], v[144:147], v[192:195], v[44:47]
	v_mfma_f32_16x16x32_bf16 v[40:43], v[152:155], v[192:195], v[40:43]
	v_mfma_f32_16x16x32_bf16 v[28:31], v[144:147], v[200:203], v[28:31]
	v_mfma_f32_16x16x32_bf16 v[24:27], v[152:155], v[200:203], v[24:27]
	v_mfma_f32_16x16x32_bf16 v[12:15], v[144:147], v[208:211], v[12:15]
	v_mfma_f32_16x16x32_bf16 v[8:11], v[152:155], v[208:211], v[8:11]
	v_mfma_f32_16x16x32_bf16 v[60:63], v[148:151], v[188:191], v[60:63]
	v_mfma_f32_16x16x32_bf16 v[56:59], v[156:159], v[188:191], v[56:59]
	v_mfma_f32_16x16x32_bf16 v[44:47], v[148:151], v[196:199], v[44:47]
	v_mfma_f32_16x16x32_bf16 v[40:43], v[156:159], v[196:199], v[40:43]
	v_mfma_f32_16x16x32_bf16 v[28:31], v[148:151], v[204:207], v[28:31]
	v_mfma_f32_16x16x32_bf16 v[24:27], v[156:159], v[204:207], v[24:27]
	v_mfma_f32_16x16x32_bf16 v[12:15], v[148:151], v[216:219], v[12:15]
	v_mfma_f32_16x16x32_bf16 v[8:11], v[156:159], v[216:219], v[8:11]
	s_setprio 0
	s_setprio 1
	v_mfma_f32_16x16x32_bf16 v[52:55], v[168:171], v[184:187], v[52:55]
	v_mfma_f32_16x16x32_bf16 v[48:51], v[176:179], v[184:187], v[48:51]
	v_mfma_f32_16x16x32_bf16 v[36:39], v[168:171], v[192:195], v[36:39]
	v_mfma_f32_16x16x32_bf16 v[32:35], v[176:179], v[192:195], v[32:35]
	v_mfma_f32_16x16x32_bf16 v[20:23], v[168:171], v[200:203], v[20:23]
	v_mfma_f32_16x16x32_bf16 v[16:19], v[176:179], v[200:203], v[16:19]
	v_mfma_f32_16x16x32_bf16 v[4:7], v[168:171], v[208:211], v[4:7]
	v_mfma_f32_16x16x32_bf16 v[0:3], v[176:179], v[208:211], v[0:3]
	v_mfma_f32_16x16x32_bf16 v[52:55], v[172:175], v[188:191], v[52:55]
	v_mfma_f32_16x16x32_bf16 v[48:51], v[180:183], v[188:191], v[48:51]
	v_mfma_f32_16x16x32_bf16 v[36:39], v[172:175], v[196:199], v[36:39]
	v_mfma_f32_16x16x32_bf16 v[32:35], v[180:183], v[196:199], v[32:35]
	v_mfma_f32_16x16x32_bf16 v[20:23], v[172:175], v[204:207], v[20:23]
	v_mfma_f32_16x16x32_bf16 v[16:19], v[180:183], v[204:207], v[16:19]
	v_mfma_f32_16x16x32_bf16 v[4:7], v[172:175], v[216:219], v[4:7]
	v_mfma_f32_16x16x32_bf16 v[0:3], v[180:183], v[216:219], v[0:3]
	s_setprio 0
	s_barrier
	s_add_i32 s80, 0, 0x18000
	v_add_u32_e32 v143, s80, v161
	s_add_i32 s81, 0, 0x1c000
	ds_read_b128 v[144:147], v143
	ds_read_b128 v[148:151], v143 offset:1024
	ds_read_b128 v[152:155], v143 offset:2048
	ds_read_b128 v[156:159], v143 offset:3072
	v_add_u32_e32 v143, s81, v161
	ds_read_b128 v[168:171], v143
	ds_read_b128 v[172:175], v143 offset:1024
	ds_read_b128 v[176:179], v143 offset:2048
	ds_read_b128 v[180:183], v143 offset:3072
	s_add_u32 s72, s78, 0x40000
	s_addc_u32 s73, s79, 0
	s_mov_b32 m0, s18
	v_lshl_add_u64 v[226:227], s[72:73], 0, v[128:129]
	ds_read_b128 v[184:187], v165 offset:32768
	ds_read_b128 v[188:191], v165 offset:33792
	ds_read_b128 v[192:195], v165 offset:34816
	ds_read_b128 v[196:199], v165 offset:35840
	ds_read_b128 v[200:203], v165 offset:36864
	ds_read_b128 v[204:207], v165 offset:37888
	ds_read_b128 v[208:211], v165 offset:38912
	ds_read_b128 v[216:219], v165 offset:39936
	global_load_lds_dwordx4 v[226:227], off
	v_lshl_add_u64 v[226:227], s[72:73], 0, v[130:131]
	s_mov_b32 m0, s19
	s_nop 0
	global_load_lds_dwordx4 v[226:227], off
	s_waitcnt vmcnt(8)
	s_waitcnt lgkmcnt(0)
	v_mfma_f32_16x16x32_bf16 v[124:127], v[144:147], v[184:187], v[124:127]
	v_mfma_f32_16x16x32_bf16 v[120:123], v[152:155], v[184:187], v[120:123]
	s_barrier
	s_setprio 1
	s_waitcnt lgkmcnt(0)
	v_mfma_f32_16x16x32_bf16 v[108:111], v[144:147], v[192:195], v[108:111]
	v_mfma_f32_16x16x32_bf16 v[104:107], v[152:155], v[192:195], v[104:107]
	v_mfma_f32_16x16x32_bf16 v[92:95], v[144:147], v[200:203], v[92:95]
	v_mfma_f32_16x16x32_bf16 v[88:91], v[152:155], v[200:203], v[88:91]
	v_mfma_f32_16x16x32_bf16 v[76:79], v[144:147], v[208:211], v[76:79]
	v_mfma_f32_16x16x32_bf16 v[72:75], v[152:155], v[208:211], v[72:75]
	v_mfma_f32_16x16x32_bf16 v[124:127], v[148:151], v[188:191], v[124:127]
	v_mfma_f32_16x16x32_bf16 v[120:123], v[156:159], v[188:191], v[120:123]
	v_mfma_f32_16x16x32_bf16 v[108:111], v[148:151], v[196:199], v[108:111]
	v_mfma_f32_16x16x32_bf16 v[104:107], v[156:159], v[196:199], v[104:107]
	v_mfma_f32_16x16x32_bf16 v[92:95], v[148:151], v[204:207], v[92:95]
	v_mfma_f32_16x16x32_bf16 v[88:91], v[156:159], v[204:207], v[88:91]
	v_mfma_f32_16x16x32_bf16 v[76:79], v[148:151], v[216:219], v[76:79]
	v_mfma_f32_16x16x32_bf16 v[72:75], v[156:159], v[216:219], v[72:75]
	s_setprio 0
	s_setprio 1
	v_mfma_f32_16x16x32_bf16 v[116:119], v[168:171], v[184:187], v[116:119]
	v_mfma_f32_16x16x32_bf16 v[112:115], v[176:179], v[184:187], v[112:115]
	v_mfma_f32_16x16x32_bf16 v[100:103], v[168:171], v[192:195], v[100:103]
	v_mfma_f32_16x16x32_bf16 v[96:99], v[176:179], v[192:195], v[96:99]
	v_mfma_f32_16x16x32_bf16 v[84:87], v[168:171], v[200:203], v[84:87]
	v_mfma_f32_16x16x32_bf16 v[80:83], v[176:179], v[200:203], v[80:83]
	v_mfma_f32_16x16x32_bf16 v[68:71], v[168:171], v[208:211], v[68:71]
	v_mfma_f32_16x16x32_bf16 v[64:67], v[176:179], v[208:211], v[64:67]
	v_mfma_f32_16x16x32_bf16 v[116:119], v[172:175], v[188:191], v[116:119]
	v_mfma_f32_16x16x32_bf16 v[112:115], v[180:183], v[188:191], v[112:115]
	v_mfma_f32_16x16x32_bf16 v[100:103], v[172:175], v[196:199], v[100:103]
	v_mfma_f32_16x16x32_bf16 v[96:99], v[180:183], v[196:199], v[96:99]
	v_mfma_f32_16x16x32_bf16 v[84:87], v[172:175], v[204:207], v[84:87]
	v_mfma_f32_16x16x32_bf16 v[80:83], v[180:183], v[204:207], v[80:83]
	v_mfma_f32_16x16x32_bf16 v[68:71], v[172:175], v[216:219], v[68:71]
	v_mfma_f32_16x16x32_bf16 v[64:67], v[180:183], v[216:219], v[64:67]
	s_setprio 0
	s_barrier
; #define PG8_STAGE(bufoff, gbase, voff) do { _Pragma("unroll") for (int _i = 0; _i < 2; ++_i) \
;         __builtin_amdgcn_global_load_lds((const unsigned*)((const char*)(gbase) + (voff)[_i]), (PG8_LAS unsigned*)(lds + (bufoff) + ldsw + _i * 8192), 16, 0, 0); } while (0)
; #define PG8_LDA(dst, b, h) do { _Pragma("unroll") for (int m = 0; m < 4; ++m) _Pragma("unroll") for (int k = 0; k < 2; ++k) dst[m][k] = *(const PG8_LAS bf16x8*)(lds + PG8_SA(b, h) + aoff + m * 2048 + k * 1024); } while (0)
; #define PG8_MMA(ai, bj, At, Bt) do { __builtin_amdgcn_s_setprio(1); _Pragma("unroll") for (int m = 0; m < 4; ++m) _Pragma("unroll") for (int n = 0; n < 2; ++n) _Pragma("unroll") for (int k = 0; k < 2; ++k) \
;         acc[ai][bj][m][n] = __builtin_amdgcn_mfma_f32_16x16x32_bf16(Bt[n][k], At[m][k], acc[ai][bj][m][n], 0, 0, 0); __builtin_amdgcn_s_setprio(0); } while (0)
; #define PG8_WAIT_V(n) asm volatile("s_waitcnt vmcnt(" #n ")" ::: "memory")
; #define PG8_WAIT_L(n) asm volatile("s_waitcnt lgkmcnt(" #n ")" ::: "memory")
; #define PG8_BAR __builtin_amdgcn_s_barrier()
; #define PG8_SCHED __builtin_amdgcn_sched_barrier(0)
; template <class Epi, class Sched, bool ALIGN_EPI = false, bool SP2 = false>
; __device__ __forceinline__ void gemm_phase(PG8_LAS unsigned char* lds, const Gemm g, const Sched& S, const Epi& E) {
;     ...
;             PG8_LDA(At, 1, 1); PG8_STAGE(PG8_SB(1, 0), b3, voffB); PG8_STAGE(PG8_SB(1, 1), b3 + hstepB, voffB); PG8_STAGE(PG8_SA(1, 0), a3, voffA);
;             PG8_WAIT_V(8); PG8_WAIT_L(0); PG8_BAR; PG8_MMA(1, 0, At, B0); PG8_MMA(1, 1, At, B1); PG8_BAR; PG8_SCHED;
;     ...
;         if constexpr (ALIGN_EPI) { if (wr == 0) PG8_BAR; }
	s_add_i32 s72, s80, s15
	v_lshl_add_u64 v[212:213], v[212:213], 0, s[38:39]
	s_mov_b32 m0, s72
	ds_read_b128 v[184:187], v165 offset:49152
	ds_read_b128 v[188:191], v165 offset:50176
	ds_read_b128 v[192:195], v165 offset:51200
	ds_read_b128 v[196:199], v165 offset:52224
	ds_read_b128 v[200:203], v165 offset:53248
	ds_read_b128 v[204:207], v165 offset:54272
	ds_read_b128 v[208:211], v165 offset:55296
	ds_read_b128 v[216:219], v165 offset:56320
	global_load_lds_dwordx4 v[212:213], off
	s_add_i32 m0, s72, 0x2000
	s_add_u32 s72, s76, 0x40080
	v_lshl_add_u64 v[212:213], v[220:221], 0, s[38:39]
	s_addc_u32 s73, s77, 0
	s_add_i32 s76, s81, s15
	global_load_lds_dwordx4 v[212:213], off
	v_lshl_add_u64 v[212:213], s[72:73], 0, v[128:129]
	s_mov_b32 m0, s76
	s_nop 0
	global_load_lds_dwordx4 v[212:213], off
	v_lshl_add_u64 v[212:213], s[72:73], 0, v[130:131]
	s_add_i32 m0, s76, 0x2000
	s_nop 0
	global_load_lds_dwordx4 v[212:213], off
	v_lshl_add_u64 v[212:213], v[222:223], 0, s[38:39]
	s_mov_b32 m0, s20
	s_nop 0
	global_load_lds_dwordx4 v[212:213], off
	v_lshl_add_u64 v[212:213], v[224:225], 0, s[38:39]
	s_mov_b32 m0, s21
	s_nop 0
	global_load_lds_dwordx4 v[212:213], off
	s_waitcnt vmcnt(8)
	s_waitcnt lgkmcnt(0)
	v_mfma_f32_16x16x32_bf16 v[60:63], v[144:147], v[184:187], v[60:63]
	v_mfma_f32_16x16x32_bf16 v[56:59], v[152:155], v[184:187], v[56:59]
	s_barrier
	s_setprio 1
	s_waitcnt lgkmcnt(0)
	v_mfma_f32_16x16x32_bf16 v[44:47], v[144:147], v[192:195], v[44:47]
	v_mfma_f32_16x16x32_bf16 v[40:43], v[152:155], v[192:195], v[40:43]
	v_mfma_f32_16x16x32_bf16 v[28:31], v[144:147], v[200:203], v[28:31]
	v_mfma_f32_16x16x32_bf16 v[24:27], v[152:155], v[200:203], v[24:27]
	v_mfma_f32_16x16x32_bf16 v[12:15], v[144:147], v[208:211], v[12:15]
	v_mfma_f32_16x16x32_bf16 v[8:11], v[152:155], v[208:211], v[8:11]
	v_mfma_f32_16x16x32_bf16 v[60:63], v[148:151], v[188:191], v[60:63]
	v_mfma_f32_16x16x32_bf16 v[56:59], v[156:159], v[188:191], v[56:59]
	v_mfma_f32_16x16x32_bf16 v[44:47], v[148:151], v[196:199], v[44:47]
	v_mfma_f32_16x16x32_bf16 v[40:43], v[156:159], v[196:199], v[40:43]
	v_mfma_f32_16x16x32_bf16 v[28:31], v[148:151], v[204:207], v[28:31]
	v_mfma_f32_16x16x32_bf16 v[24:27], v[156:159], v[204:207], v[24:27]
	v_mfma_f32_16x16x32_bf16 v[12:15], v[148:151], v[216:219], v[12:15]
	v_mfma_f32_16x16x32_bf16 v[8:11], v[156:159], v[216:219], v[8:11]
	s_setprio 0
	s_setprio 1
	v_mfma_f32_16x16x32_bf16 v[52:55], v[168:171], v[184:187], v[52:55]
	v_mfma_f32_16x16x32_bf16 v[48:51], v[176:179], v[184:187], v[48:51]
	v_mfma_f32_16x16x32_bf16 v[36:39], v[168:171], v[192:195], v[36:39]
	v_mfma_f32_16x16x32_bf16 v[32:35], v[176:179], v[192:195], v[32:35]
	v_mfma_f32_16x16x32_bf16 v[20:23], v[168:171], v[200:203], v[20:23]
	v_mfma_f32_16x16x32_bf16 v[16:19], v[176:179], v[200:203], v[16:19]
	v_mfma_f32_16x16x32_bf16 v[4:7], v[168:171], v[208:211], v[4:7]
	v_mfma_f32_16x16x32_bf16 v[0:3], v[176:179], v[208:211], v[0:3]
	v_mfma_f32_16x16x32_bf16 v[52:55], v[172:175], v[188:191], v[52:55]
	v_mfma_f32_16x16x32_bf16 v[48:51], v[180:183], v[188:191], v[48:51]
	v_mfma_f32_16x16x32_bf16 v[36:39], v[172:175], v[196:199], v[36:39]
	v_mfma_f32_16x16x32_bf16 v[32:35], v[180:183], v[196:199], v[32:35]
	v_mfma_f32_16x16x32_bf16 v[20:23], v[172:175], v[204:207], v[20:23]
	v_mfma_f32_16x16x32_bf16 v[16:19], v[180:183], v[204:207], v[16:19]
	v_mfma_f32_16x16x32_bf16 v[4:7], v[172:175], v[216:219], v[4:7]
	v_mfma_f32_16x16x32_bf16 v[0:3], v[180:183], v[216:219], v[0:3]
	s_setprio 0
	s_barrier
	s_add_i32 s71, s71, 2
	s_add_u32 s63, s63, 0x100
	s_addc_u32 s69, s69, 0
	s_cmp_gt_u32 s71, 13
	s_mov_b64 s[72:73], s[74:75]
	s_cbranch_scc0 .LBB0_433
	s_and_b64 vcc, exec, s[40:41]
	s_cbranch_vccz .LBB0_436
	s_barrier

; #define PG8_STAGE(bufoff, gbase, voff) do { _Pragma("unroll") for (int _i = 0; _i < 2; ++_i) \
;         __builtin_amdgcn_global_load_lds((const unsigned*)((const char*)(gbase) + (voff)[_i]), (PG8_LAS unsigned*)(lds + (bufoff) + ldsw + _i * 8192), 16, 0, 0); } while (0)
; #define PG8_LDA(dst, b, h) do { _Pragma("unroll") for (int m = 0; m < 4; ++m) _Pragma("unroll") for (int k = 0; k < 2; ++k) dst[m][k] = *(const PG8_LAS bf16x8*)(lds + PG8_SA(b, h) + aoff + m * 2048 + k * 1024); } while (0)
; #define PG8_LDB(dst, b, h) do { _Pragma("unroll") for (int n = 0; n < 2; ++n) _Pragma("unroll") for (int k = 0; k < 2; ++k) dst[n][k] = *(const PG8_LAS bf16x8*)(lds + PG8_SB(b, h) + boff + n * 2048 + k * 1024); } while (0)
; #define PG8_MMA(ai, bj, At, Bt) do { __builtin_amdgcn_s_setprio(1); _Pragma("unroll") for (int m = 0; m < 4; ++m) _Pragma("unroll") for (int n = 0; n < 2; ++n) _Pragma("unroll") for (int k = 0; k < 2; ++k) \
;         acc[ai][bj][m][n] = __builtin_amdgcn_mfma_f32_16x16x32_bf16(Bt[n][k], At[m][k], acc[ai][bj][m][n], 0, 0, 0); __builtin_amdgcn_s_setprio(0); } while (0)
; #define PG8_WAIT_V(n) asm volatile("s_waitcnt vmcnt(" #n ")" ::: "memory")
; #define PG8_WAIT_L(n) asm volatile("s_waitcnt lgkmcnt(" #n ")" ::: "memory")
; #define PG8_BAR __builtin_amdgcn_s_barrier()
; template <class Epi, class Sched, bool ALIGN_EPI = false, bool SP2 = false>
; __device__ __forceinline__ void gemm_phase(PG8_LAS unsigned char* lds, const Gemm g, const Sched& S, const Epi& E) {
;     ...
;         for (int t = 0; t < nt; t += 2) {
;             const bool last = (t == nt - 2);
;             const char* a1 = cA + (size_t)(t + 1) * kstep;
;             const char* a2 = last ? nA : cA + (size_t)(t + 2) * kstep; const char* b2 = last ? nB : cB + (size_t)(t + 2) * kstep;
;             const char* a3 = a2 + kstep; const char* b3 = b2 + kstep;
;             if (last && has_next) S.a_ready(nxt);
;             if (last) E.pre(lds, cur, wid, tid);
;             if constexpr (SP2) {
;             PG8_LDB(B0, 0, 0); PG8_LDB(B1, 0, 1); PG8_SCHED; PG8_LDA(At, 0, 0); PG8_STAGE(PG8_SA(1, 1), a1 + hstep, voffA);
;             PG8_WAIT_V(8); PG8_WAIT_L(0); PG8_BAR; PG8_MMA(0, 0, At, B0); PG8_MMA(0, 1, At, B1); PG8_BAR; PG8_SCHED;
;             PG8_LDA(At, 0, 1); PG8_STAGE(PG8_SB(0, 0), b2, voffB); PG8_STAGE(PG8_SB(0, 1), b2 + hstepB, voffB); PG8_STAGE(PG8_SA(0, 0), a2, voffA);
.LBB0_520:
	v_add_u32_e32 v166, s60, v149
	v_add_u32_e32 v182, s61, v149
	ds_read_b128 v[154:157], v166
	ds_read_b128 v[158:161], v166 offset:1024
	ds_read_b128 v[162:165], v166 offset:2048
	ds_read_b128 v[166:169], v166 offset:3072
	ds_read_b128 v[170:173], v182
	ds_read_b128 v[174:177], v182 offset:1024
	ds_read_b128 v[178:181], v182 offset:2048
	ds_read_b128 v[182:185], v182 offset:3072
	s_add_u32 s68, s64, 0xfffc0080
	s_addc_u32 s69, s65, -1
	s_and_b64 s[66:67], s[66:67], exec
	s_cselect_b32 s69, s39, s69
	s_cselect_b32 s68, s70, s68
	s_cselect_b32 s67, s13, s72
	s_cselect_b32 s66, s71, s45
	v_lshl_add_u64 v[220:221], s[64:65], 0, v[138:139]
	s_add_i32 m0, s18, 0xc000
	ds_read_b128 v[186:189], v151
	ds_read_b128 v[190:193], v151 offset:1024
	ds_read_b128 v[194:197], v151 offset:2048
	ds_read_b128 v[198:201], v151 offset:3072
	ds_read_b128 v[202:205], v151 offset:4096
	ds_read_b128 v[206:209], v151 offset:5120
	ds_read_b128 v[210:213], v151 offset:6144
	ds_read_b128 v[216:219], v151 offset:7168
	global_load_lds_dwordx4 v[220:221], off
	v_lshl_add_u64 v[220:221], s[64:65], 0, v[140:141]
	s_add_i32 m0, s18, 0xe000
	s_nop 0
	global_load_lds_dwordx4 v[220:221], off
	s_waitcnt vmcnt(8)
	s_waitcnt lgkmcnt(0)
	v_mfma_f32_16x16x32_bf16 v[124:127], v[154:157], v[186:189], v[124:127]
	v_mfma_f32_16x16x32_bf16 v[116:119], v[162:165], v[186:189], v[116:119]
	s_barrier
	s_setprio 1
	s_waitcnt lgkmcnt(0)
	v_mfma_f32_16x16x32_bf16 v[108:111], v[154:157], v[194:197], v[108:111]
	v_mfma_f32_16x16x32_bf16 v[100:103], v[162:165], v[194:197], v[100:103]
	v_mfma_f32_16x16x32_bf16 v[92:95], v[154:157], v[202:205], v[92:95]
	v_mfma_f32_16x16x32_bf16 v[84:87], v[162:165], v[202:205], v[84:87]
	v_mfma_f32_16x16x32_bf16 v[76:79], v[154:157], v[210:213], v[76:79]
	v_mfma_f32_16x16x32_bf16 v[68:71], v[162:165], v[210:213], v[68:71]
	v_mfma_f32_16x16x32_bf16 v[124:127], v[158:161], v[190:193], v[124:127]
	v_mfma_f32_16x16x32_bf16 v[116:119], v[166:169], v[190:193], v[116:119]
	v_mfma_f32_16x16x32_bf16 v[108:111], v[158:161], v[198:201], v[108:111]
	v_mfma_f32_16x16x32_bf16 v[100:103], v[166:169], v[198:201], v[100:103]
	v_mfma_f32_16x16x32_bf16 v[92:95], v[158:161], v[206:209], v[92:95]
	v_mfma_f32_16x16x32_bf16 v[84:87], v[166:169], v[206:209], v[84:87]
	v_mfma_f32_16x16x32_bf16 v[76:79], v[158:161], v[216:219], v[76:79]
	v_mfma_f32_16x16x32_bf16 v[68:71], v[166:169], v[216:219], v[68:71]
	s_setprio 0
	s_setprio 1
	v_mfma_f32_16x16x32_bf16 v[120:123], v[170:173], v[186:189], v[120:123]
	v_mfma_f32_16x16x32_bf16 v[112:115], v[178:181], v[186:189], v[112:115]
	v_mfma_f32_16x16x32_bf16 v[104:107], v[170:173], v[194:197], v[104:107]
	v_mfma_f32_16x16x32_bf16 v[96:99], v[178:181], v[194:197], v[96:99]
	v_mfma_f32_16x16x32_bf16 v[88:91], v[170:173], v[202:205], v[88:91]
	v_mfma_f32_16x16x32_bf16 v[80:83], v[178:181], v[202:205], v[80:83]
	v_mfma_f32_16x16x32_bf16 v[72:75], v[170:173], v[210:213], v[72:75]
	v_mfma_f32_16x16x32_bf16 v[64:67], v[178:181], v[210:213], v[64:67]
	v_mfma_f32_16x16x32_bf16 v[120:123], v[174:177], v[190:193], v[120:123]
	v_mfma_f32_16x16x32_bf16 v[112:115], v[182:185], v[190:193], v[112:115]
	v_mfma_f32_16x16x32_bf16 v[104:107], v[174:177], v[198:201], v[104:107]
	v_mfma_f32_16x16x32_bf16 v[96:99], v[182:185], v[198:201], v[96:99]
	v_mfma_f32_16x16x32_bf16 v[88:91], v[174:177], v[206:209], v[88:91]
	v_mfma_f32_16x16x32_bf16 v[80:83], v[182:185], v[206:209], v[80:83]
	v_mfma_f32_16x16x32_bf16 v[72:75], v[174:177], v[216:219], v[72:75]
	v_mfma_f32_16x16x32_bf16 v[64:67], v[182:185], v[216:219], v[64:67]
	s_setprio 0
	s_barrier
	s_add_i32 s74, s60, s15
	v_lshl_add_u64 v[220:221], s[66:67], 0, v[132:133]
	s_mov_b32 m0, s74
	ds_read_b128 v[186:189], v151 offset:16384
	ds_read_b128 v[190:193], v151 offset:17408
	ds_read_b128 v[194:197], v151 offset:18432
	ds_read_b128 v[198:201], v151 offset:19456
	ds_read_b128 v[202:205], v151 offset:20480
	ds_read_b128 v[206:209], v151 offset:21504
	ds_read_b128 v[210:213], v151 offset:22528
	ds_read_b128 v[216:219], v151 offset:23552
	global_load_lds_dwordx4 v[220:221], off
	s_add_i32 m0, s74, 0x2000
	s_add_u32 s74, s66, 0x580000
	v_lshl_add_u64 v[222:223], s[66:67], 0, v[128:129]
	s_addc_u32 s75, s67, 0
	s_add_i32 s76, s61, s15
	global_load_lds_dwordx4 v[222:223], off
	v_lshl_add_u64 v[224:225], s[74:75], 0, v[132:133]
	s_mov_b32 m0, s76
	v_lshl_add_u64 v[226:227], s[68:69], 0, v[130:131]
	global_load_lds_dwordx4 v[224:225], off
	v_lshl_add_u64 v[224:225], s[74:75], 0, v[128:129]
	s_add_i32 m0, s76, 0x2000
	s_nop 0
	global_load_lds_dwordx4 v[224:225], off
	v_lshl_add_u64 v[224:225], s[68:69], 0, v[134:135]
	s_mov_b32 m0, s18
	s_nop 0
	global_load_lds_dwordx4 v[224:225], off
	s_mov_b32 m0, s19
	s_nop 0
	global_load_lds_dwordx4 v[226:227], off
	s_waitcnt vmcnt(8)
	s_waitcnt lgkmcnt(0)
	v_mfma_f32_16x16x32_bf16 v[60:63], v[154:157], v[186:189], v[60:63]
	v_mfma_f32_16x16x32_bf16 v[52:55], v[162:165], v[186:189], v[52:55]
	s_barrier
; #define PG8_STAGE(bufoff, gbase, voff) do { _Pragma("unroll") for (int _i = 0; _i < 2; ++_i) \
;         __builtin_amdgcn_global_load_lds((const unsigned*)((const char*)(gbase) + (voff)[_i]), (PG8_LAS unsigned*)(lds + (bufoff) + ldsw + _i * 8192), 16, 0, 0); } while (0)
; #define PG8_LDA(dst, b, h) do { _Pragma("unroll") for (int m = 0; m < 4; ++m) _Pragma("unroll") for (int k = 0; k < 2; ++k) dst[m][k] = *(const PG8_LAS bf16x8*)(lds + PG8_SA(b, h) + aoff + m * 2048 + k * 1024); } while (0)
; #define PG8_LDB(dst, b, h) do { _Pragma("unroll") for (int n = 0; n < 2; ++n) _Pragma("unroll") for (int k = 0; k < 2; ++k) dst[n][k] = *(const PG8_LAS bf16x8*)(lds + PG8_SB(b, h) + boff + n * 2048 + k * 1024); } while (0)
; #define PG8_MMA(ai, bj, At, Bt) do { __builtin_amdgcn_s_setprio(1); _Pragma("unroll") for (int m = 0; m < 4; ++m) _Pragma("unroll") for (int n = 0; n < 2; ++n) _Pragma("unroll") for (int k = 0; k < 2; ++k) \
;         acc[ai][bj][m][n] = __builtin_amdgcn_mfma_f32_16x16x32_bf16(Bt[n][k], At[m][k], acc[ai][bj][m][n], 0, 0, 0); __builtin_amdgcn_s_setprio(0); } while (0)
; #define PG8_WAIT_V(n) asm volatile("s_waitcnt vmcnt(" #n ")" ::: "memory")
; #define PG8_WAIT_L(n) asm volatile("s_waitcnt lgkmcnt(" #n ")" ::: "memory")
; #define PG8_BAR __builtin_amdgcn_s_barrier()
; #define PG8_SCHED __builtin_amdgcn_sched_barrier(0)
; template <class Epi, class Sched, bool ALIGN_EPI = false, bool SP2 = false>
; __device__ __forceinline__ void gemm_phase(PG8_LAS unsigned char* lds, const Gemm g, const Sched& S, const Epi& E) {
;     ...
;             PG8_WAIT_V(8); PG8_WAIT_L(0); PG8_BAR; PG8_MMA(1, 0, At, B0); PG8_MMA(1, 1, At, B1); PG8_BAR; PG8_SCHED;
;             PG8_LDB(B0, 1, 0); PG8_LDB(B1, 1, 1); PG8_SCHED; PG8_LDA(At, 1, 0); PG8_STAGE(PG8_SA(0, 1), a2 + hstep, voffA);
;             PG8_WAIT_V(8); PG8_WAIT_L(0); PG8_BAR; PG8_MMA(0, 0, At, B0); PG8_MMA(0, 1, At, B1); PG8_BAR; PG8_SCHED;
	s_setprio 1
	s_waitcnt lgkmcnt(0)
	v_mfma_f32_16x16x32_bf16 v[44:47], v[154:157], v[194:197], v[44:47]
	v_mfma_f32_16x16x32_bf16 v[36:39], v[162:165], v[194:197], v[36:39]
	v_mfma_f32_16x16x32_bf16 v[28:31], v[154:157], v[202:205], v[28:31]
	v_mfma_f32_16x16x32_bf16 v[20:23], v[162:165], v[202:205], v[20:23]
	v_mfma_f32_16x16x32_bf16 v[12:15], v[154:157], v[210:213], v[12:15]
	v_mfma_f32_16x16x32_bf16 v[4:7], v[162:165], v[210:213], v[4:7]
	v_mfma_f32_16x16x32_bf16 v[60:63], v[158:161], v[190:193], v[60:63]
	v_mfma_f32_16x16x32_bf16 v[52:55], v[166:169], v[190:193], v[52:55]
	v_mfma_f32_16x16x32_bf16 v[44:47], v[158:161], v[198:201], v[44:47]
	v_mfma_f32_16x16x32_bf16 v[36:39], v[166:169], v[198:201], v[36:39]
	v_mfma_f32_16x16x32_bf16 v[28:31], v[158:161], v[206:209], v[28:31]
	v_mfma_f32_16x16x32_bf16 v[20:23], v[166:169], v[206:209], v[20:23]
	v_mfma_f32_16x16x32_bf16 v[12:15], v[158:161], v[216:219], v[12:15]
	v_mfma_f32_16x16x32_bf16 v[4:7], v[166:169], v[216:219], v[4:7]
	s_setprio 0
	s_setprio 1
	v_mfma_f32_16x16x32_bf16 v[56:59], v[170:173], v[186:189], v[56:59]
	v_mfma_f32_16x16x32_bf16 v[48:51], v[178:181], v[186:189], v[48:51]
	v_mfma_f32_16x16x32_bf16 v[40:43], v[170:173], v[194:197], v[40:43]
	v_mfma_f32_16x16x32_bf16 v[32:35], v[178:181], v[194:197], v[32:35]
	v_mfma_f32_16x16x32_bf16 v[24:27], v[170:173], v[202:205], v[24:27]
	v_mfma_f32_16x16x32_bf16 v[16:19], v[178:181], v[202:205], v[16:19]
	v_mfma_f32_16x16x32_bf16 v[8:11], v[170:173], v[210:213], v[8:11]
	v_mfma_f32_16x16x32_bf16 v[0:3], v[178:181], v[210:213], v[0:3]
	v_mfma_f32_16x16x32_bf16 v[56:59], v[174:177], v[190:193], v[56:59]
	v_mfma_f32_16x16x32_bf16 v[48:51], v[182:185], v[190:193], v[48:51]
	v_mfma_f32_16x16x32_bf16 v[40:43], v[174:177], v[198:201], v[40:43]
	v_mfma_f32_16x16x32_bf16 v[32:35], v[182:185], v[198:201], v[32:35]
	v_mfma_f32_16x16x32_bf16 v[24:27], v[174:177], v[206:209], v[24:27]
	v_mfma_f32_16x16x32_bf16 v[16:19], v[182:185], v[206:209], v[16:19]
	v_mfma_f32_16x16x32_bf16 v[8:11], v[174:177], v[216:219], v[8:11]
	v_mfma_f32_16x16x32_bf16 v[0:3], v[182:185], v[216:219], v[0:3]
	s_setprio 0
	s_barrier
	s_add_i32 s74, 0, 0x18000
	s_add_i32 s75, 0, 0x1c000
	v_add_u32_e32 v166, s74, v149
	v_add_u32_e32 v182, s75, v149
	ds_read_b128 v[154:157], v166
	ds_read_b128 v[158:161], v166 offset:1024
	ds_read_b128 v[162:165], v166 offset:2048
	ds_read_b128 v[166:169], v166 offset:3072
	ds_read_b128 v[170:173], v182
	ds_read_b128 v[174:177], v182 offset:1024
	ds_read_b128 v[178:181], v182 offset:2048
	ds_read_b128 v[182:185], v182 offset:3072
	s_add_u32 s68, s68, 0x40000
	s_addc_u32 s69, s69, 0
	s_mov_b32 m0, s20
	v_lshl_add_u64 v[228:229], s[68:69], 0, v[134:135]
	ds_read_b128 v[186:189], v151 offset:32768
	ds_read_b128 v[190:193], v151 offset:33792
	ds_read_b128 v[194:197], v151 offset:34816
	ds_read_b128 v[198:201], v151 offset:35840
	ds_read_b128 v[202:205], v151 offset:36864
	ds_read_b128 v[206:209], v151 offset:37888
	ds_read_b128 v[210:213], v151 offset:38912
	ds_read_b128 v[216:219], v151 offset:39936
	global_load_lds_dwordx4 v[228:229], off
	v_lshl_add_u64 v[228:229], s[68:69], 0, v[130:131]
	s_mov_b32 m0, s21
	s_nop 0
	global_load_lds_dwordx4 v[228:229], off
	s_waitcnt vmcnt(8)
	s_waitcnt lgkmcnt(0)
	v_mfma_f32_16x16x32_bf16 v[124:127], v[154:157], v[186:189], v[124:127]
	v_mfma_f32_16x16x32_bf16 v[116:119], v[162:165], v[186:189], v[116:119]
	s_barrier
	s_setprio 1
	s_waitcnt lgkmcnt(0)
	v_mfma_f32_16x16x32_bf16 v[108:111], v[154:157], v[194:197], v[108:111]
	v_mfma_f32_16x16x32_bf16 v[100:103], v[162:165], v[194:197], v[100:103]
	v_mfma_f32_16x16x32_bf16 v[92:95], v[154:157], v[202:205], v[92:95]
	v_mfma_f32_16x16x32_bf16 v[84:87], v[162:165], v[202:205], v[84:87]
	v_mfma_f32_16x16x32_bf16 v[76:79], v[154:157], v[210:213], v[76:79]
	v_mfma_f32_16x16x32_bf16 v[68:71], v[162:165], v[210:213], v[68:71]
	v_mfma_f32_16x16x32_bf16 v[124:127], v[158:161], v[190:193], v[124:127]
	v_mfma_f32_16x16x32_bf16 v[116:119], v[166:169], v[190:193], v[116:119]
	v_mfma_f32_16x16x32_bf16 v[108:111], v[158:161], v[198:201], v[108:111]
	v_mfma_f32_16x16x32_bf16 v[100:103], v[166:169], v[198:201], v[100:103]
	v_mfma_f32_16x16x32_bf16 v[92:95], v[158:161], v[206:209], v[92:95]
	v_mfma_f32_16x16x32_bf16 v[84:87], v[166:169], v[206:209], v[84:87]
	v_mfma_f32_16x16x32_bf16 v[76:79], v[158:161], v[216:219], v[76:79]
	v_mfma_f32_16x16x32_bf16 v[68:71], v[166:169], v[216:219], v[68:71]
	s_setprio 0
	s_setprio 1
	v_mfma_f32_16x16x32_bf16 v[120:123], v[170:173], v[186:189], v[120:123]
	v_mfma_f32_16x16x32_bf16 v[112:115], v[178:181], v[186:189], v[112:115]
	v_mfma_f32_16x16x32_bf16 v[104:107], v[170:173], v[194:197], v[104:107]
	v_mfma_f32_16x16x32_bf16 v[96:99], v[178:181], v[194:197], v[96:99]
	v_mfma_f32_16x16x32_bf16 v[88:91], v[170:173], v[202:205], v[88:91]
	v_mfma_f32_16x16x32_bf16 v[80:83], v[178:181], v[202:205], v[80:83]
	v_mfma_f32_16x16x32_bf16 v[72:75], v[170:173], v[210:213], v[72:75]
	v_mfma_f32_16x16x32_bf16 v[64:67], v[178:181], v[210:213], v[64:67]
	v_mfma_f32_16x16x32_bf16 v[120:123], v[174:177], v[190:193], v[120:123]
	v_mfma_f32_16x16x32_bf16 v[112:115], v[182:185], v[190:193], v[112:115]
	v_mfma_f32_16x16x32_bf16 v[104:107], v[174:177], v[198:201], v[104:107]
	v_mfma_f32_16x16x32_bf16 v[96:99], v[182:185], v[198:201], v[96:99]
	v_mfma_f32_16x16x32_bf16 v[88:91], v[174:177], v[206:209], v[88:91]
	v_mfma_f32_16x16x32_bf16 v[80:83], v[182:185], v[206:209], v[80:83]
	v_mfma_f32_16x16x32_bf16 v[72:75], v[174:177], v[216:219], v[72:75]
	v_mfma_f32_16x16x32_bf16 v[64:67], v[182:185], v[216:219], v[64:67]
	s_setprio 0
	s_barrier
; #define PG8_STAGE(bufoff, gbase, voff) do { _Pragma("unroll") for (int _i = 0; _i < 2; ++_i) \
;         __builtin_amdgcn_global_load_lds((const unsigned*)((const char*)(gbase) + (voff)[_i]), (PG8_LAS unsigned*)(lds + (bufoff) + ldsw + _i * 8192), 16, 0, 0); } while (0)
; #define PG8_LDA(dst, b, h) do { _Pragma("unroll") for (int m = 0; m < 4; ++m) _Pragma("unroll") for (int k = 0; k < 2; ++k) dst[m][k] = *(const PG8_LAS bf16x8*)(lds + PG8_SA(b, h) + aoff + m * 2048 + k * 1024); } while (0)
; #define PG8_MMA(ai, bj, At, Bt) do { __builtin_amdgcn_s_setprio(1); _Pragma("unroll") for (int m = 0; m < 4; ++m) _Pragma("unroll") for (int n = 0; n < 2; ++n) _Pragma("unroll") for (int k = 0; k < 2; ++k) \
;         acc[ai][bj][m][n] = __builtin_amdgcn_mfma_f32_16x16x32_bf16(Bt[n][k], At[m][k], acc[ai][bj][m][n], 0, 0, 0); __builtin_amdgcn_s_setprio(0); } while (0)
; #define PG8_WAIT_V(n) asm volatile("s_waitcnt vmcnt(" #n ")" ::: "memory")
; #define PG8_WAIT_L(n) asm volatile("s_waitcnt lgkmcnt(" #n ")" ::: "memory")
; #define PG8_BAR __builtin_amdgcn_s_barrier()
; #define PG8_SCHED __builtin_amdgcn_sched_barrier(0)
; template <class Epi, class Sched, bool ALIGN_EPI = false, bool SP2 = false>
; __device__ __forceinline__ void gemm_phase(PG8_LAS unsigned char* lds, const Gemm g, const Sched& S, const Epi& E) {
;     ...
;             PG8_LDA(At, 1, 1); PG8_STAGE(PG8_SB(1, 0), b3, voffB); PG8_STAGE(PG8_SB(1, 1), b3 + hstepB, voffB); PG8_STAGE(PG8_SA(1, 0), a3, voffA);
;             PG8_WAIT_V(8); PG8_WAIT_L(0); PG8_BAR; PG8_MMA(1, 0, At, B0); PG8_MMA(1, 1, At, B1); PG8_BAR; PG8_SCHED;
	s_add_i32 s68, s74, s15
	v_lshl_add_u64 v[220:221], v[220:221], 0, s[8:9]
	s_mov_b32 m0, s68
	ds_read_b128 v[186:189], v151 offset:49152
	ds_read_b128 v[190:193], v151 offset:50176
	ds_read_b128 v[194:197], v151 offset:51200
	ds_read_b128 v[198:201], v151 offset:52224
	ds_read_b128 v[202:205], v151 offset:53248
	ds_read_b128 v[206:209], v151 offset:54272
	ds_read_b128 v[210:213], v151 offset:55296
	ds_read_b128 v[216:219], v151 offset:56320
	global_load_lds_dwordx4 v[220:221], off
	s_add_i32 m0, s68, 0x2000
	s_add_u32 s66, s66, 0x580080
	v_lshl_add_u64 v[220:221], v[222:223], 0, s[8:9]
	s_addc_u32 s67, s67, 0
	s_add_i32 s68, s75, s15
	global_load_lds_dwordx4 v[220:221], off
	v_lshl_add_u64 v[220:221], s[66:67], 0, v[132:133]
	s_mov_b32 m0, s68
	s_nop 0
	global_load_lds_dwordx4 v[220:221], off
	v_lshl_add_u64 v[220:221], s[66:67], 0, v[128:129]
	s_add_i32 m0, s68, 0x2000
	s_nop 0
	global_load_lds_dwordx4 v[220:221], off
	v_lshl_add_u64 v[220:221], v[224:225], 0, s[8:9]
	s_mov_b32 m0, s23
	s_nop 0
	global_load_lds_dwordx4 v[220:221], off
	v_lshl_add_u64 v[220:221], v[226:227], 0, s[8:9]
	s_mov_b32 m0, s30
	s_nop 0
	global_load_lds_dwordx4 v[220:221], off
	s_waitcnt vmcnt(8)
	s_waitcnt lgkmcnt(0)
	v_mfma_f32_16x16x32_bf16 v[60:63], v[154:157], v[186:189], v[60:63]
	v_mfma_f32_16x16x32_bf16 v[52:55], v[162:165], v[186:189], v[52:55]
	s_barrier
	s_setprio 1
	s_waitcnt lgkmcnt(0)
	v_mfma_f32_16x16x32_bf16 v[44:47], v[154:157], v[194:197], v[44:47]
	v_mfma_f32_16x16x32_bf16 v[36:39], v[162:165], v[194:197], v[36:39]
	v_mfma_f32_16x16x32_bf16 v[28:31], v[154:157], v[202:205], v[28:31]
	v_mfma_f32_16x16x32_bf16 v[20:23], v[162:165], v[202:205], v[20:23]
	v_mfma_f32_16x16x32_bf16 v[12:15], v[154:157], v[210:213], v[12:15]
	v_mfma_f32_16x16x32_bf16 v[4:7], v[162:165], v[210:213], v[4:7]
	v_mfma_f32_16x16x32_bf16 v[60:63], v[158:161], v[190:193], v[60:63]
	v_mfma_f32_16x16x32_bf16 v[52:55], v[166:169], v[190:193], v[52:55]
	v_mfma_f32_16x16x32_bf16 v[44:47], v[158:161], v[198:201], v[44:47]
	v_mfma_f32_16x16x32_bf16 v[36:39], v[166:169], v[198:201], v[36:39]
	v_mfma_f32_16x16x32_bf16 v[28:31], v[158:161], v[206:209], v[28:31]
	v_mfma_f32_16x16x32_bf16 v[20:23], v[166:169], v[206:209], v[20:23]
	v_mfma_f32_16x16x32_bf16 v[12:15], v[158:161], v[216:219], v[12:15]
	v_mfma_f32_16x16x32_bf16 v[4:7], v[166:169], v[216:219], v[4:7]
	s_setprio 0
	s_setprio 1
	v_mfma_f32_16x16x32_bf16 v[56:59], v[170:173], v[186:189], v[56:59]
	v_mfma_f32_16x16x32_bf16 v[48:51], v[178:181], v[186:189], v[48:51]
	v_mfma_f32_16x16x32_bf16 v[40:43], v[170:173], v[194:197], v[40:43]
	v_mfma_f32_16x16x32_bf16 v[32:35], v[178:181], v[194:197], v[32:35]
	v_mfma_f32_16x16x32_bf16 v[24:27], v[170:173], v[202:205], v[24:27]
	v_mfma_f32_16x16x32_bf16 v[16:19], v[178:181], v[202:205], v[16:19]
	v_mfma_f32_16x16x32_bf16 v[8:11], v[170:173], v[210:213], v[8:11]
	v_mfma_f32_16x16x32_bf16 v[0:3], v[178:181], v[210:213], v[0:3]
	v_mfma_f32_16x16x32_bf16 v[56:59], v[174:177], v[190:193], v[56:59]
	v_mfma_f32_16x16x32_bf16 v[48:51], v[182:185], v[190:193], v[48:51]
	v_mfma_f32_16x16x32_bf16 v[40:43], v[174:177], v[198:201], v[40:43]
	v_mfma_f32_16x16x32_bf16 v[32:35], v[182:185], v[198:201], v[32:35]
	v_mfma_f32_16x16x32_bf16 v[24:27], v[174:177], v[206:209], v[24:27]
	v_mfma_f32_16x16x32_bf16 v[16:19], v[182:185], v[206:209], v[16:19]
	v_mfma_f32_16x16x32_bf16 v[8:11], v[174:177], v[216:219], v[8:11]
	v_mfma_f32_16x16x32_bf16 v[0:3], v[182:185], v[216:219], v[0:3]
	s_setprio 0
	s_barrier
	s_add_i32 s73, s73, 2
	s_add_u32 s64, s64, 0x100
	s_addc_u32 s65, s65, 0
	s_add_u32 s45, s45, 0x100
	s_addc_u32 s72, s72, 0
	s_cmp_gt_u32 s73, 13
	s_cbranch_scc1 .LBB0_523

; #define PG8_STAGE(bufoff, gbase, voff) do { _Pragma("unroll") for (int _i = 0; _i < 2; ++_i) \
;         __builtin_amdgcn_global_load_lds((const unsigned*)((const char*)(gbase) + (voff)[_i]), (PG8_LAS unsigned*)(lds + (bufoff) + ldsw + _i * 8192), 16, 0, 0); } while (0)
; #define PG8_LDA(dst, b, h) do { _Pragma("unroll") for (int m = 0; m < 4; ++m) _Pragma("unroll") for (int k = 0; k < 2; ++k) dst[m][k] = *(const PG8_LAS bf16x8*)(lds + PG8_SA(b, h) + aoff + m * 2048 + k * 1024); } while (0)
; #define PG8_LDB(dst, b, h) do { _Pragma("unroll") for (int n = 0; n < 2; ++n) _Pragma("unroll") for (int k = 0; k < 2; ++k) dst[n][k] = *(const PG8_LAS bf16x8*)(lds + PG8_SB(b, h) + boff + n * 2048 + k * 1024); } while (0)
; #define PG8_MMA(ai, bj, At, Bt) do { __builtin_amdgcn_s_setprio(1); _Pragma("unroll") for (int m = 0; m < 4; ++m) _Pragma("unroll") for (int n = 0; n < 2; ++n) _Pragma("unroll") for (int k = 0; k < 2; ++k) \
;         acc[ai][bj][m][n] = __builtin_amdgcn_mfma_f32_16x16x32_bf16(Bt[n][k], At[m][k], acc[ai][bj][m][n], 0, 0, 0); __builtin_amdgcn_s_setprio(0); } while (0)
; #define PG8_WAIT_V(n) asm volatile("s_waitcnt vmcnt(" #n ")" ::: "memory")
; #define PG8_WAIT_L(n) asm volatile("s_waitcnt lgkmcnt(" #n ")" ::: "memory")
; #define PG8_BAR __builtin_amdgcn_s_barrier()
; template <class Epi, class Sched, bool ALIGN_EPI = false, bool SP2 = false>
; __device__ __forceinline__ void gemm_phase(PG8_LAS unsigned char* lds, const Gemm g, const Sched& S, const Epi& E) {
;     ...
;         for (int t = 0; t < nt; t += 2) {
;             const bool last = (t == nt - 2);
;             const char* a1 = cA + (size_t)(t + 1) * kstep;
;             const char* a2 = last ? nA : cA + (size_t)(t + 2) * kstep; const char* b2 = last ? nB : cB + (size_t)(t + 2) * kstep;
;             const char* a3 = a2 + kstep; const char* b3 = b2 + kstep;
;             if (last && has_next) S.a_ready(nxt);
;             if (last) E.pre(lds, cur, wid, tid);
;             if constexpr (SP2) {
;             PG8_LDB(B0, 0, 0); PG8_LDB(B1, 0, 1); PG8_SCHED; PG8_LDA(At, 0, 0); PG8_STAGE(PG8_SA(1, 1), a1 + hstep, voffA);
;             PG8_WAIT_V(8); PG8_WAIT_L(0); PG8_BAR; PG8_MMA(0, 0, At, B0); PG8_MMA(0, 1, At, B1); PG8_BAR; PG8_SCHED;
;             PG8_LDA(At, 0, 1); PG8_STAGE(PG8_SB(0, 0), b2, voffB); PG8_STAGE(PG8_SB(0, 1), b2 + hstepB, voffB); PG8_STAGE(PG8_SA(0, 0), a2, voffA);
.LBB0_599:
	ds_read_b128 v[144:147], v163
	ds_read_b128 v[148:151], v163 offset:1024
	ds_read_b128 v[152:155], v163 offset:2048
	ds_read_b128 v[156:159], v163 offset:3072
	ds_read_b128 v[168:171], v164
	ds_read_b128 v[172:175], v164 offset:1024
	ds_read_b128 v[176:179], v164 offset:2048
	ds_read_b128 v[180:183], v164 offset:3072
	s_add_u32 s66, s64, 0x100
	s_addc_u32 s67, s65, 0
	s_cmp_eq_u32 s75, 40
	s_cselect_b32 s71, s1, s67
	s_cselect_b32 s70, s0, s66
	s_cselect_b32 s69, s45, s74
	s_cselect_b32 s68, s44, s73
	v_lshl_add_u64 v[212:213], s[64:65], 0, v[134:135]
	s_add_i32 m0, s16, 0xc000
	ds_read_b128 v[184:187], v165
	ds_read_b128 v[188:191], v165 offset:1024
	ds_read_b128 v[192:195], v165 offset:2048
	ds_read_b128 v[196:199], v165 offset:3072
	ds_read_b128 v[200:203], v165 offset:4096
	ds_read_b128 v[204:207], v165 offset:5120
	ds_read_b128 v[208:211], v165 offset:6144
	ds_read_b128 v[216:219], v165 offset:7168
	global_load_lds_dwordx4 v[212:213], off
	v_lshl_add_u64 v[212:213], s[64:65], 0, v[136:137]
	s_add_i32 m0, s16, 0xe000
	s_nop 0
	global_load_lds_dwordx4 v[212:213], off
	s_waitcnt vmcnt(8)
	s_waitcnt lgkmcnt(0)
	v_mfma_f32_16x16x32_bf16 v[124:127], v[144:147], v[184:187], v[124:127]
	v_mfma_f32_16x16x32_bf16 v[120:123], v[152:155], v[184:187], v[120:123]
	s_barrier
	s_setprio 1
	s_waitcnt lgkmcnt(0)
	v_mfma_f32_16x16x32_bf16 v[108:111], v[144:147], v[192:195], v[108:111]
	v_mfma_f32_16x16x32_bf16 v[104:107], v[152:155], v[192:195], v[104:107]
	v_mfma_f32_16x16x32_bf16 v[92:95], v[144:147], v[200:203], v[92:95]
	v_mfma_f32_16x16x32_bf16 v[88:91], v[152:155], v[200:203], v[88:91]
	v_mfma_f32_16x16x32_bf16 v[76:79], v[144:147], v[208:211], v[76:79]
	v_mfma_f32_16x16x32_bf16 v[72:75], v[152:155], v[208:211], v[72:75]
	v_mfma_f32_16x16x32_bf16 v[124:127], v[148:151], v[188:191], v[124:127]
	v_mfma_f32_16x16x32_bf16 v[120:123], v[156:159], v[188:191], v[120:123]
	v_mfma_f32_16x16x32_bf16 v[108:111], v[148:151], v[196:199], v[108:111]
	v_mfma_f32_16x16x32_bf16 v[104:107], v[156:159], v[196:199], v[104:107]
	v_mfma_f32_16x16x32_bf16 v[92:95], v[148:151], v[204:207], v[92:95]
	v_mfma_f32_16x16x32_bf16 v[88:91], v[156:159], v[204:207], v[88:91]
	v_mfma_f32_16x16x32_bf16 v[76:79], v[148:151], v[216:219], v[76:79]
	v_mfma_f32_16x16x32_bf16 v[72:75], v[156:159], v[216:219], v[72:75]
	s_setprio 0
	s_setprio 1
	v_mfma_f32_16x16x32_bf16 v[116:119], v[168:171], v[184:187], v[116:119]
	v_mfma_f32_16x16x32_bf16 v[112:115], v[176:179], v[184:187], v[112:115]
	v_mfma_f32_16x16x32_bf16 v[100:103], v[168:171], v[192:195], v[100:103]
	v_mfma_f32_16x16x32_bf16 v[96:99], v[176:179], v[192:195], v[96:99]
	v_mfma_f32_16x16x32_bf16 v[84:87], v[168:171], v[200:203], v[84:87]
	v_mfma_f32_16x16x32_bf16 v[80:83], v[176:179], v[200:203], v[80:83]
	v_mfma_f32_16x16x32_bf16 v[68:71], v[168:171], v[208:211], v[68:71]
	v_mfma_f32_16x16x32_bf16 v[64:67], v[176:179], v[208:211], v[64:67]
	v_mfma_f32_16x16x32_bf16 v[116:119], v[172:175], v[188:191], v[116:119]
	v_mfma_f32_16x16x32_bf16 v[112:115], v[180:183], v[188:191], v[112:115]
	v_mfma_f32_16x16x32_bf16 v[100:103], v[172:175], v[196:199], v[100:103]
	v_mfma_f32_16x16x32_bf16 v[96:99], v[180:183], v[196:199], v[96:99]
	v_mfma_f32_16x16x32_bf16 v[84:87], v[172:175], v[204:207], v[84:87]
	v_mfma_f32_16x16x32_bf16 v[80:83], v[180:183], v[204:207], v[80:83]
	v_mfma_f32_16x16x32_bf16 v[68:71], v[172:175], v[216:219], v[68:71]
	v_mfma_f32_16x16x32_bf16 v[64:67], v[180:183], v[216:219], v[64:67]
	s_setprio 0
	s_barrier
	s_add_i32 s64, s31, s15
	v_lshl_add_u64 v[212:213], s[68:69], 0, v[128:129]
	s_mov_b32 m0, s64
	ds_read_b128 v[184:187], v165 offset:16384
	ds_read_b128 v[188:191], v165 offset:17408
	ds_read_b128 v[192:195], v165 offset:18432
	ds_read_b128 v[196:199], v165 offset:19456
	ds_read_b128 v[200:203], v165 offset:20480
	ds_read_b128 v[204:207], v165 offset:21504
	ds_read_b128 v[208:211], v165 offset:22528
	ds_read_b128 v[216:219], v165 offset:23552
	global_load_lds_dwordx4 v[212:213], off
	s_add_i32 m0, s64, 0x2000
	s_add_u32 s64, s68, 0xb0000
	v_lshl_add_u64 v[220:221], s[68:69], 0, v[130:131]
	s_addc_u32 s65, s69, 0
	s_add_i32 s76, s35, s15
	global_load_lds_dwordx4 v[220:221], off
	v_lshl_add_u64 v[222:223], s[64:65], 0, v[128:129]
	s_mov_b32 m0, s76
	v_lshl_add_u64 v[224:225], s[70:71], 0, v[130:131]
	global_load_lds_dwordx4 v[222:223], off
	v_lshl_add_u64 v[222:223], s[64:65], 0, v[130:131]
	s_add_i32 m0, s76, 0x2000
	s_nop 0
	global_load_lds_dwordx4 v[222:223], off
	v_lshl_add_u64 v[222:223], s[70:71], 0, v[128:129]
	s_mov_b32 m0, s16
	s_nop 0
	global_load_lds_dwordx4 v[222:223], off
	s_mov_b32 m0, s17
	s_nop 0
	global_load_lds_dwordx4 v[224:225], off
	s_waitcnt vmcnt(8)
	s_waitcnt lgkmcnt(0)
	v_mfma_f32_16x16x32_bf16 v[60:63], v[144:147], v[184:187], v[60:63]
	v_mfma_f32_16x16x32_bf16 v[56:59], v[152:155], v[184:187], v[56:59]
	s_barrier
; #define PG8_STAGE(bufoff, gbase, voff) do { _Pragma("unroll") for (int _i = 0; _i < 2; ++_i) \
;         __builtin_amdgcn_global_load_lds((const unsigned*)((const char*)(gbase) + (voff)[_i]), (PG8_LAS unsigned*)(lds + (bufoff) + ldsw + _i * 8192), 16, 0, 0); } while (0)
; #define PG8_LDA(dst, b, h) do { _Pragma("unroll") for (int m = 0; m < 4; ++m) _Pragma("unroll") for (int k = 0; k < 2; ++k) dst[m][k] = *(const PG8_LAS bf16x8*)(lds + PG8_SA(b, h) + aoff + m * 2048 + k * 1024); } while (0)
; #define PG8_LDB(dst, b, h) do { _Pragma("unroll") for (int n = 0; n < 2; ++n) _Pragma("unroll") for (int k = 0; k < 2; ++k) dst[n][k] = *(const PG8_LAS bf16x8*)(lds + PG8_SB(b, h) + boff + n * 2048 + k * 1024); } while (0)
; #define PG8_MMA(ai, bj, At, Bt) do { __builtin_amdgcn_s_setprio(1); _Pragma("unroll") for (int m = 0; m < 4; ++m) _Pragma("unroll") for (int n = 0; n < 2; ++n) _Pragma("unroll") for (int k = 0; k < 2; ++k) \
;         acc[ai][bj][m][n] = __builtin_amdgcn_mfma_f32_16x16x32_bf16(Bt[n][k], At[m][k], acc[ai][bj][m][n], 0, 0, 0); __builtin_amdgcn_s_setprio(0); } while (0)
; #define PG8_WAIT_V(n) asm volatile("s_waitcnt vmcnt(" #n ")" ::: "memory")
; #define PG8_WAIT_L(n) asm volatile("s_waitcnt lgkmcnt(" #n ")" ::: "memory")
; #define PG8_BAR __builtin_amdgcn_s_barrier()
; #define PG8_SCHED __builtin_amdgcn_sched_barrier(0)
; template <class Epi, class Sched, bool ALIGN_EPI = false, bool SP2 = false>
; __device__ __forceinline__ void gemm_phase(PG8_LAS unsigned char* lds, const Gemm g, const Sched& S, const Epi& E) {
;     ...
;             PG8_WAIT_V(8); PG8_WAIT_L(0); PG8_BAR; PG8_MMA(1, 0, At, B0); PG8_MMA(1, 1, At, B1); PG8_BAR; PG8_SCHED;
;             PG8_LDB(B0, 1, 0); PG8_LDB(B1, 1, 1); PG8_SCHED; PG8_LDA(At, 1, 0); PG8_STAGE(PG8_SA(0, 1), a2 + hstep, voffA);
;             PG8_WAIT_V(8); PG8_WAIT_L(0); PG8_BAR; PG8_MMA(0, 0, At, B0); PG8_MMA(0, 1, At, B1); PG8_BAR; PG8_SCHED;
	s_setprio 1
	s_waitcnt lgkmcnt(0)
	v_mfma_f32_16x16x32_bf16 v[44:47], v[144:147], v[192:195], v[44:47]
	v_mfma_f32_16x16x32_bf16 v[40:43], v[152:155], v[192:195], v[40:43]
	v_mfma_f32_16x16x32_bf16 v[28:31], v[144:147], v[200:203], v[28:31]
	v_mfma_f32_16x16x32_bf16 v[24:27], v[152:155], v[200:203], v[24:27]
	v_mfma_f32_16x16x32_bf16 v[12:15], v[144:147], v[208:211], v[12:15]
	v_mfma_f32_16x16x32_bf16 v[8:11], v[152:155], v[208:211], v[8:11]
	v_mfma_f32_16x16x32_bf16 v[60:63], v[148:151], v[188:191], v[60:63]
	v_mfma_f32_16x16x32_bf16 v[56:59], v[156:159], v[188:191], v[56:59]
	v_mfma_f32_16x16x32_bf16 v[44:47], v[148:151], v[196:199], v[44:47]
	v_mfma_f32_16x16x32_bf16 v[40:43], v[156:159], v[196:199], v[40:43]
	v_mfma_f32_16x16x32_bf16 v[28:31], v[148:151], v[204:207], v[28:31]
	v_mfma_f32_16x16x32_bf16 v[24:27], v[156:159], v[204:207], v[24:27]
	v_mfma_f32_16x16x32_bf16 v[12:15], v[148:151], v[216:219], v[12:15]
	v_mfma_f32_16x16x32_bf16 v[8:11], v[156:159], v[216:219], v[8:11]
	s_setprio 0
	s_setprio 1
	v_mfma_f32_16x16x32_bf16 v[52:55], v[168:171], v[184:187], v[52:55]
	v_mfma_f32_16x16x32_bf16 v[48:51], v[176:179], v[184:187], v[48:51]
	v_mfma_f32_16x16x32_bf16 v[36:39], v[168:171], v[192:195], v[36:39]
	v_mfma_f32_16x16x32_bf16 v[32:35], v[176:179], v[192:195], v[32:35]
	v_mfma_f32_16x16x32_bf16 v[20:23], v[168:171], v[200:203], v[20:23]
	v_mfma_f32_16x16x32_bf16 v[16:19], v[176:179], v[200:203], v[16:19]
	v_mfma_f32_16x16x32_bf16 v[4:7], v[168:171], v[208:211], v[4:7]
	v_mfma_f32_16x16x32_bf16 v[0:3], v[176:179], v[208:211], v[0:3]
	v_mfma_f32_16x16x32_bf16 v[52:55], v[172:175], v[188:191], v[52:55]
	v_mfma_f32_16x16x32_bf16 v[48:51], v[180:183], v[188:191], v[48:51]
	v_mfma_f32_16x16x32_bf16 v[36:39], v[172:175], v[196:199], v[36:39]
	v_mfma_f32_16x16x32_bf16 v[32:35], v[180:183], v[196:199], v[32:35]
	v_mfma_f32_16x16x32_bf16 v[20:23], v[172:175], v[204:207], v[20:23]
	v_mfma_f32_16x16x32_bf16 v[16:19], v[180:183], v[204:207], v[16:19]
	v_mfma_f32_16x16x32_bf16 v[4:7], v[172:175], v[216:219], v[4:7]
	v_mfma_f32_16x16x32_bf16 v[0:3], v[180:183], v[216:219], v[0:3]
	s_setprio 0
	s_barrier
	s_add_i32 s76, 0, 0x18000
	v_add_u32_e32 v143, s76, v161
	s_add_i32 s77, 0, 0x1c000
	ds_read_b128 v[144:147], v143
	ds_read_b128 v[148:151], v143 offset:1024
	ds_read_b128 v[152:155], v143 offset:2048
	ds_read_b128 v[156:159], v143 offset:3072
	v_add_u32_e32 v143, s77, v161
	ds_read_b128 v[168:171], v143
	ds_read_b128 v[172:175], v143 offset:1024
	ds_read_b128 v[176:179], v143 offset:2048
	ds_read_b128 v[180:183], v143 offset:3072
	s_add_u32 s64, s70, 0xb0000
	s_addc_u32 s65, s71, 0
	s_mov_b32 m0, s18
	v_lshl_add_u64 v[226:227], s[64:65], 0, v[128:129]
	ds_read_b128 v[184:187], v165 offset:32768
	ds_read_b128 v[188:191], v165 offset:33792
	ds_read_b128 v[192:195], v165 offset:34816
	ds_read_b128 v[196:199], v165 offset:35840
	ds_read_b128 v[200:203], v165 offset:36864
	ds_read_b128 v[204:207], v165 offset:37888
	ds_read_b128 v[208:211], v165 offset:38912
	ds_read_b128 v[216:219], v165 offset:39936
	global_load_lds_dwordx4 v[226:227], off
	v_lshl_add_u64 v[226:227], s[64:65], 0, v[130:131]
	s_mov_b32 m0, s19
	s_nop 0
	global_load_lds_dwordx4 v[226:227], off
	s_waitcnt vmcnt(8)
	s_waitcnt lgkmcnt(0)
	v_mfma_f32_16x16x32_bf16 v[124:127], v[144:147], v[184:187], v[124:127]
	v_mfma_f32_16x16x32_bf16 v[120:123], v[152:155], v[184:187], v[120:123]
	s_barrier
	s_setprio 1
	s_waitcnt lgkmcnt(0)
	v_mfma_f32_16x16x32_bf16 v[108:111], v[144:147], v[192:195], v[108:111]
	v_mfma_f32_16x16x32_bf16 v[104:107], v[152:155], v[192:195], v[104:107]
	v_mfma_f32_16x16x32_bf16 v[92:95], v[144:147], v[200:203], v[92:95]
	v_mfma_f32_16x16x32_bf16 v[88:91], v[152:155], v[200:203], v[88:91]
	v_mfma_f32_16x16x32_bf16 v[76:79], v[144:147], v[208:211], v[76:79]
	v_mfma_f32_16x16x32_bf16 v[72:75], v[152:155], v[208:211], v[72:75]
	v_mfma_f32_16x16x32_bf16 v[124:127], v[148:151], v[188:191], v[124:127]
	v_mfma_f32_16x16x32_bf16 v[120:123], v[156:159], v[188:191], v[120:123]
	v_mfma_f32_16x16x32_bf16 v[108:111], v[148:151], v[196:199], v[108:111]
	v_mfma_f32_16x16x32_bf16 v[104:107], v[156:159], v[196:199], v[104:107]
	v_mfma_f32_16x16x32_bf16 v[92:95], v[148:151], v[204:207], v[92:95]
	v_mfma_f32_16x16x32_bf16 v[88:91], v[156:159], v[204:207], v[88:91]
	v_mfma_f32_16x16x32_bf16 v[76:79], v[148:151], v[216:219], v[76:79]
	v_mfma_f32_16x16x32_bf16 v[72:75], v[156:159], v[216:219], v[72:75]
	s_setprio 0
	s_setprio 1
	v_mfma_f32_16x16x32_bf16 v[116:119], v[168:171], v[184:187], v[116:119]
	v_mfma_f32_16x16x32_bf16 v[112:115], v[176:179], v[184:187], v[112:115]
	v_mfma_f32_16x16x32_bf16 v[100:103], v[168:171], v[192:195], v[100:103]
	v_mfma_f32_16x16x32_bf16 v[96:99], v[176:179], v[192:195], v[96:99]
	v_mfma_f32_16x16x32_bf16 v[84:87], v[168:171], v[200:203], v[84:87]
	v_mfma_f32_16x16x32_bf16 v[80:83], v[176:179], v[200:203], v[80:83]
	v_mfma_f32_16x16x32_bf16 v[68:71], v[168:171], v[208:211], v[68:71]
	v_mfma_f32_16x16x32_bf16 v[64:67], v[176:179], v[208:211], v[64:67]
	v_mfma_f32_16x16x32_bf16 v[116:119], v[172:175], v[188:191], v[116:119]
	v_mfma_f32_16x16x32_bf16 v[112:115], v[180:183], v[188:191], v[112:115]
	v_mfma_f32_16x16x32_bf16 v[100:103], v[172:175], v[196:199], v[100:103]
	v_mfma_f32_16x16x32_bf16 v[96:99], v[180:183], v[196:199], v[96:99]
	v_mfma_f32_16x16x32_bf16 v[84:87], v[172:175], v[204:207], v[84:87]
	v_mfma_f32_16x16x32_bf16 v[80:83], v[180:183], v[204:207], v[80:83]
	v_mfma_f32_16x16x32_bf16 v[68:71], v[172:175], v[216:219], v[68:71]
	v_mfma_f32_16x16x32_bf16 v[64:67], v[180:183], v[216:219], v[64:67]
	s_setprio 0
	s_barrier
; #define PG8_STAGE(bufoff, gbase, voff) do { _Pragma("unroll") for (int _i = 0; _i < 2; ++_i) \
;         __builtin_amdgcn_global_load_lds((const unsigned*)((const char*)(gbase) + (voff)[_i]), (PG8_LAS unsigned*)(lds + (bufoff) + ldsw + _i * 8192), 16, 0, 0); } while (0)
; #define PG8_LDA(dst, b, h) do { _Pragma("unroll") for (int m = 0; m < 4; ++m) _Pragma("unroll") for (int k = 0; k < 2; ++k) dst[m][k] = *(const PG8_LAS bf16x8*)(lds + PG8_SA(b, h) + aoff + m * 2048 + k * 1024); } while (0)
; #define PG8_MMA(ai, bj, At, Bt) do { __builtin_amdgcn_s_setprio(1); _Pragma("unroll") for (int m = 0; m < 4; ++m) _Pragma("unroll") for (int n = 0; n < 2; ++n) _Pragma("unroll") for (int k = 0; k < 2; ++k) \
;         acc[ai][bj][m][n] = __builtin_amdgcn_mfma_f32_16x16x32_bf16(Bt[n][k], At[m][k], acc[ai][bj][m][n], 0, 0, 0); __builtin_amdgcn_s_setprio(0); } while (0)
; #define PG8_WAIT_V(n) asm volatile("s_waitcnt vmcnt(" #n ")" ::: "memory")
; #define PG8_WAIT_L(n) asm volatile("s_waitcnt lgkmcnt(" #n ")" ::: "memory")
; #define PG8_BAR __builtin_amdgcn_s_barrier()
; #define PG8_SCHED __builtin_amdgcn_sched_barrier(0)
; template <class Epi, class Sched, bool ALIGN_EPI = false, bool SP2 = false>
; __device__ __forceinline__ void gemm_phase(PG8_LAS unsigned char* lds, const Gemm g, const Sched& S, const Epi& E) {
;     ...
;             PG8_LDA(At, 1, 1); PG8_STAGE(PG8_SB(1, 0), b3, voffB); PG8_STAGE(PG8_SB(1, 1), b3 + hstepB, voffB); PG8_STAGE(PG8_SA(1, 0), a3, voffA);
;             PG8_WAIT_V(8); PG8_WAIT_L(0); PG8_BAR; PG8_MMA(1, 0, At, B0); PG8_MMA(1, 1, At, B1); PG8_BAR; PG8_SCHED;
;     ...
;         if constexpr (ALIGN_EPI) { if (wr == 0) PG8_BAR; }
	s_add_i32 s64, s76, s15
	v_lshl_add_u64 v[212:213], v[212:213], 0, s[40:41]
	s_mov_b32 m0, s64
	ds_read_b128 v[184:187], v165 offset:49152
	ds_read_b128 v[188:191], v165 offset:50176
	ds_read_b128 v[192:195], v165 offset:51200
	ds_read_b128 v[196:199], v165 offset:52224
	ds_read_b128 v[200:203], v165 offset:53248
	ds_read_b128 v[204:207], v165 offset:54272
	ds_read_b128 v[208:211], v165 offset:55296
	ds_read_b128 v[216:219], v165 offset:56320
	global_load_lds_dwordx4 v[212:213], off
	s_add_i32 m0, s64, 0x2000
	s_add_u32 s64, s68, 0xb0080
	v_lshl_add_u64 v[212:213], v[220:221], 0, s[40:41]
	s_addc_u32 s65, s69, 0
	s_add_i32 s68, s77, s15
	global_load_lds_dwordx4 v[212:213], off
	v_lshl_add_u64 v[212:213], s[64:65], 0, v[128:129]
	s_mov_b32 m0, s68
	s_nop 0
	global_load_lds_dwordx4 v[212:213], off
	v_lshl_add_u64 v[212:213], s[64:65], 0, v[130:131]
	s_add_i32 m0, s68, 0x2000
	s_nop 0
	global_load_lds_dwordx4 v[212:213], off
	v_lshl_add_u64 v[212:213], v[222:223], 0, s[40:41]
	s_mov_b32 m0, s20
	s_nop 0
	global_load_lds_dwordx4 v[212:213], off
	v_lshl_add_u64 v[212:213], v[224:225], 0, s[40:41]
	s_mov_b32 m0, s21
	s_nop 0
	global_load_lds_dwordx4 v[212:213], off
	s_waitcnt vmcnt(8)
	s_waitcnt lgkmcnt(0)
	v_mfma_f32_16x16x32_bf16 v[60:63], v[144:147], v[184:187], v[60:63]
	v_mfma_f32_16x16x32_bf16 v[56:59], v[152:155], v[184:187], v[56:59]
	s_barrier
	s_setprio 1
	s_waitcnt lgkmcnt(0)
	v_mfma_f32_16x16x32_bf16 v[44:47], v[144:147], v[192:195], v[44:47]
	v_mfma_f32_16x16x32_bf16 v[40:43], v[152:155], v[192:195], v[40:43]
	v_mfma_f32_16x16x32_bf16 v[28:31], v[144:147], v[200:203], v[28:31]
	v_mfma_f32_16x16x32_bf16 v[24:27], v[152:155], v[200:203], v[24:27]
	v_mfma_f32_16x16x32_bf16 v[12:15], v[144:147], v[208:211], v[12:15]
	v_mfma_f32_16x16x32_bf16 v[8:11], v[152:155], v[208:211], v[8:11]
	v_mfma_f32_16x16x32_bf16 v[60:63], v[148:151], v[188:191], v[60:63]
	v_mfma_f32_16x16x32_bf16 v[56:59], v[156:159], v[188:191], v[56:59]
	v_mfma_f32_16x16x32_bf16 v[44:47], v[148:151], v[196:199], v[44:47]
	v_mfma_f32_16x16x32_bf16 v[40:43], v[156:159], v[196:199], v[40:43]
	v_mfma_f32_16x16x32_bf16 v[28:31], v[148:151], v[204:207], v[28:31]
	v_mfma_f32_16x16x32_bf16 v[24:27], v[156:159], v[204:207], v[24:27]
	v_mfma_f32_16x16x32_bf16 v[12:15], v[148:151], v[216:219], v[12:15]
	v_mfma_f32_16x16x32_bf16 v[8:11], v[156:159], v[216:219], v[8:11]
	s_setprio 0
	s_setprio 1
	v_mfma_f32_16x16x32_bf16 v[52:55], v[168:171], v[184:187], v[52:55]
	v_mfma_f32_16x16x32_bf16 v[48:51], v[176:179], v[184:187], v[48:51]
	v_mfma_f32_16x16x32_bf16 v[36:39], v[168:171], v[192:195], v[36:39]
	v_mfma_f32_16x16x32_bf16 v[32:35], v[176:179], v[192:195], v[32:35]
	v_mfma_f32_16x16x32_bf16 v[20:23], v[168:171], v[200:203], v[20:23]
	v_mfma_f32_16x16x32_bf16 v[16:19], v[176:179], v[200:203], v[16:19]
	v_mfma_f32_16x16x32_bf16 v[4:7], v[168:171], v[208:211], v[4:7]
	v_mfma_f32_16x16x32_bf16 v[0:3], v[176:179], v[208:211], v[0:3]
	v_mfma_f32_16x16x32_bf16 v[52:55], v[172:175], v[188:191], v[52:55]
	v_mfma_f32_16x16x32_bf16 v[48:51], v[180:183], v[188:191], v[48:51]
	v_mfma_f32_16x16x32_bf16 v[36:39], v[172:175], v[196:199], v[36:39]
	v_mfma_f32_16x16x32_bf16 v[32:35], v[180:183], v[196:199], v[32:35]
	v_mfma_f32_16x16x32_bf16 v[20:23], v[172:175], v[204:207], v[20:23]
	v_mfma_f32_16x16x32_bf16 v[16:19], v[180:183], v[204:207], v[16:19]
	v_mfma_f32_16x16x32_bf16 v[4:7], v[172:175], v[216:219], v[4:7]
	v_mfma_f32_16x16x32_bf16 v[0:3], v[180:183], v[216:219], v[0:3]
	s_setprio 0
	s_barrier
	s_add_i32 s75, s75, 2
	s_add_u32 s73, s73, 0x100
	s_addc_u32 s74, s74, 0
	s_cmp_gt_u32 s75, 41
	s_mov_b64 s[64:65], s[66:67]
	s_cbranch_scc0 .LBB0_599
	s_and_b64 vcc, exec, s[42:43]
	s_cbranch_vccz .LBB0_602
	s_barrier

; #define PG8_STAGE(bufoff, gbase, voff) do { _Pragma("unroll") for (int _i = 0; _i < 2; ++_i) \
;         __builtin_amdgcn_global_load_lds((const unsigned*)((const char*)(gbase) + (voff)[_i]), (PG8_LAS unsigned*)(lds + (bufoff) + ldsw + _i * 8192), 16, 0, 0); } while (0)
; #define PG8_LDA(dst, b, h) do { _Pragma("unroll") for (int m = 0; m < 4; ++m) _Pragma("unroll") for (int k = 0; k < 2; ++k) dst[m][k] = *(const PG8_LAS bf16x8*)(lds + PG8_SA(b, h) + aoff + m * 2048 + k * 1024); } while (0)
; #define PG8_LDB(dst, b, h) do { _Pragma("unroll") for (int n = 0; n < 2; ++n) _Pragma("unroll") for (int k = 0; k < 2; ++k) dst[n][k] = *(const PG8_LAS bf16x8*)(lds + PG8_SB(b, h) + boff + n * 2048 + k * 1024); } while (0)
; #define PG8_MMA(ai, bj, At, Bt) do { __builtin_amdgcn_s_setprio(1); _Pragma("unroll") for (int m = 0; m < 4; ++m) _Pragma("unroll") for (int n = 0; n < 2; ++n) _Pragma("unroll") for (int k = 0; k < 2; ++k) \
;         acc[ai][bj][m][n] = __builtin_amdgcn_mfma_f32_16x16x32_bf16(Bt[n][k], At[m][k], acc[ai][bj][m][n], 0, 0, 0); __builtin_amdgcn_s_setprio(0); } while (0)
; #define PG8_WAIT_V(n) asm volatile("s_waitcnt vmcnt(" #n ")" ::: "memory")
; #define PG8_WAIT_L(n) asm volatile("s_waitcnt lgkmcnt(" #n ")" ::: "memory")
; #define PG8_BAR __builtin_amdgcn_s_barrier()
; template <class Epi, class Sched, bool ALIGN_EPI = false, bool SP2 = false>
; __device__ __forceinline__ void gemm_phase(PG8_LAS unsigned char* lds, const Gemm g, const Sched& S, const Epi& E) {
;     ...
;         for (int t = 0; t < nt; t += 2) {
;             const bool last = (t == nt - 2);
;             const char* a1 = cA + (size_t)(t + 1) * kstep;
;             const char* a2 = last ? nA : cA + (size_t)(t + 2) * kstep; const char* b2 = last ? nB : cB + (size_t)(t + 2) * kstep;
;             const char* a3 = a2 + kstep; const char* b3 = b2 + kstep;
;             if (last && has_next) S.a_ready(nxt);
;             if (last) E.pre(lds, cur, wid, tid);
;             if constexpr (SP2) {
;             PG8_LDB(B0, 0, 0); PG8_LDB(B1, 0, 1); PG8_SCHED; PG8_LDA(At, 0, 0); PG8_STAGE(PG8_SA(1, 1), a1 + hstep, voffA);
;             PG8_WAIT_V(8); PG8_WAIT_L(0); PG8_BAR; PG8_MMA(0, 0, At, B0); PG8_MMA(0, 1, At, B1); PG8_BAR; PG8_SCHED;
;             PG8_LDA(At, 0, 1); PG8_STAGE(PG8_SB(0, 0), b2, voffB); PG8_STAGE(PG8_SB(0, 1), b2 + hstepB, voffB); PG8_STAGE(PG8_SA(0, 0), a2, voffA);
.LBB0_688:
	ds_read_b128 v[28:31], v200
	ds_read_b128 v[36:39], v200 offset:1024
	ds_read_b128 v[40:43], v200 offset:2048
	ds_read_b128 v[44:47], v200 offset:3072
	ds_read_b128 v[48:51], v201
	ds_read_b128 v[52:55], v201 offset:1024
	ds_read_b128 v[152:155], v201 offset:2048
	ds_read_b128 v[156:159], v201 offset:3072
	s_add_u32 s12, s10, 0xfffc0080
	s_addc_u32 s13, s11, -1
	s_cmp_eq_u32 s19, 12
	s_cselect_b32 s75, s9, s13
	s_cselect_b32 s74, s14, s12
	s_cselect_b32 s13, s15, s18
	s_cselect_b32 s12, s16, s17
	v_lshl_add_u64 v[190:191], s[10:11], 0, v[180:181]
	s_add_i32 m0, s39, 0xc000
	ds_read_b128 v[160:163], v202
	ds_read_b128 v[164:167], v202 offset:1024
	ds_read_b128 v[210:213], v202 offset:2048
	ds_read_b128 v[216:219], v202 offset:3072
	ds_read_b128 v[220:223], v202 offset:4096
	ds_read_b128 v[224:227], v202 offset:5120
	ds_read_b128 v[228:231], v202 offset:6144
	ds_read_b128 v[232:235], v202 offset:7168
	global_load_lds_dwordx4 v[190:191], off
	v_lshl_add_u64 v[190:191], s[10:11], 0, v[182:183]
	s_add_i32 m0, s39, 0xe000
	s_nop 0
	global_load_lds_dwordx4 v[190:191], off
	s_waitcnt vmcnt(8)
	s_waitcnt lgkmcnt(0)
	v_mfma_f32_16x16x32_bf16 v[148:151], v[28:31], v[160:163], v[148:151]
	v_mfma_f32_16x16x32_bf16 v[144:147], v[40:43], v[160:163], v[144:147]
	s_barrier
	s_setprio 1
	s_waitcnt lgkmcnt(0)
	v_mfma_f32_16x16x32_bf16 v[132:135], v[28:31], v[210:213], v[132:135]
	v_mfma_f32_16x16x32_bf16 v[128:131], v[40:43], v[210:213], v[128:131]
	v_mfma_f32_16x16x32_bf16 v[116:119], v[28:31], v[220:223], v[116:119]
	v_mfma_f32_16x16x32_bf16 v[112:115], v[40:43], v[220:223], v[112:115]
	v_mfma_f32_16x16x32_bf16 v[100:103], v[28:31], v[228:231], v[100:103]
	v_mfma_f32_16x16x32_bf16 v[96:99], v[40:43], v[228:231], v[96:99]
	v_mfma_f32_16x16x32_bf16 v[148:151], v[36:39], v[164:167], v[148:151]
	v_mfma_f32_16x16x32_bf16 v[144:147], v[44:47], v[164:167], v[144:147]
	v_mfma_f32_16x16x32_bf16 v[132:135], v[36:39], v[216:219], v[132:135]
	v_mfma_f32_16x16x32_bf16 v[128:131], v[44:47], v[216:219], v[128:131]
	v_mfma_f32_16x16x32_bf16 v[116:119], v[36:39], v[224:227], v[116:119]
	v_mfma_f32_16x16x32_bf16 v[112:115], v[44:47], v[224:227], v[112:115]
	v_mfma_f32_16x16x32_bf16 v[100:103], v[36:39], v[232:235], v[100:103]
	v_mfma_f32_16x16x32_bf16 v[96:99], v[44:47], v[232:235], v[96:99]
	s_setprio 0
	s_setprio 1
	v_mfma_f32_16x16x32_bf16 v[140:143], v[48:51], v[160:163], v[140:143]
	v_mfma_f32_16x16x32_bf16 v[136:139], v[152:155], v[160:163], v[136:139]
	v_mfma_f32_16x16x32_bf16 v[124:127], v[48:51], v[210:213], v[124:127]
	v_mfma_f32_16x16x32_bf16 v[120:123], v[152:155], v[210:213], v[120:123]
	v_mfma_f32_16x16x32_bf16 v[108:111], v[48:51], v[220:223], v[108:111]
	v_mfma_f32_16x16x32_bf16 v[104:107], v[152:155], v[220:223], v[104:107]
	v_mfma_f32_16x16x32_bf16 v[92:95], v[48:51], v[228:231], v[92:95]
	v_mfma_f32_16x16x32_bf16 v[88:91], v[152:155], v[228:231], v[88:91]
	v_mfma_f32_16x16x32_bf16 v[140:143], v[52:55], v[164:167], v[140:143]
	v_mfma_f32_16x16x32_bf16 v[136:139], v[156:159], v[164:167], v[136:139]
	v_mfma_f32_16x16x32_bf16 v[124:127], v[52:55], v[216:219], v[124:127]
	v_mfma_f32_16x16x32_bf16 v[120:123], v[156:159], v[216:219], v[120:123]
	v_mfma_f32_16x16x32_bf16 v[108:111], v[52:55], v[224:227], v[108:111]
	v_mfma_f32_16x16x32_bf16 v[104:107], v[156:159], v[224:227], v[104:107]
	v_mfma_f32_16x16x32_bf16 v[92:95], v[52:55], v[232:235], v[92:95]
	v_mfma_f32_16x16x32_bf16 v[88:91], v[156:159], v[232:235], v[88:91]
	s_setprio 0
	s_barrier
	s_add_i32 s20, s97, s84
	v_lshl_add_u64 v[190:191], s[12:13], 0, v[170:171]
	s_mov_b32 m0, s20
	ds_read_b128 v[160:163], v202 offset:16384
	ds_read_b128 v[164:167], v202 offset:17408
	ds_read_b128 v[210:213], v202 offset:18432
	ds_read_b128 v[216:219], v202 offset:19456
	ds_read_b128 v[220:223], v202 offset:20480
	ds_read_b128 v[224:227], v202 offset:21504
	ds_read_b128 v[228:231], v202 offset:22528
	ds_read_b128 v[232:235], v202 offset:23552
	global_load_lds_dwordx4 v[190:191], off
	s_add_i32 m0, s20, 0x2000
	s_add_u32 s20, s12, 0x10000
	v_lshl_add_u64 v[236:237], s[12:13], 0, v[174:175]
	s_addc_u32 s21, s13, 0
	s_add_i32 s22, s62, s84
	global_load_lds_dwordx4 v[236:237], off
	v_lshl_add_u64 v[240:241], s[20:21], 0, v[170:171]
	s_mov_b32 m0, s22
	v_lshl_add_u64 v[244:245], s[74:75], 0, v[168:169]
	global_load_lds_dwordx4 v[240:241], off
	v_lshl_add_u64 v[240:241], s[20:21], 0, v[174:175]
	s_add_i32 m0, s22, 0x2000
	v_lshl_add_u64 v[246:247], s[74:75], 0, v[172:173]
	global_load_lds_dwordx4 v[240:241], off
	s_mov_b32 m0, s39
	s_nop 0
	global_load_lds_dwordx4 v[244:245], off
	s_mov_b32 m0, s85
	s_nop 0
	global_load_lds_dwordx4 v[246:247], off
	s_waitcnt vmcnt(8)
	s_waitcnt lgkmcnt(0)
	v_mfma_f32_16x16x32_bf16 v[84:87], v[28:31], v[160:163], v[84:87]
	v_mfma_f32_16x16x32_bf16 v[80:83], v[40:43], v[160:163], v[80:83]
	s_barrier
; #define PG8_STAGE(bufoff, gbase, voff) do { _Pragma("unroll") for (int _i = 0; _i < 2; ++_i) \
;         __builtin_amdgcn_global_load_lds((const unsigned*)((const char*)(gbase) + (voff)[_i]), (PG8_LAS unsigned*)(lds + (bufoff) + ldsw + _i * 8192), 16, 0, 0); } while (0)
; #define PG8_LDA(dst, b, h) do { _Pragma("unroll") for (int m = 0; m < 4; ++m) _Pragma("unroll") for (int k = 0; k < 2; ++k) dst[m][k] = *(const PG8_LAS bf16x8*)(lds + PG8_SA(b, h) + aoff + m * 2048 + k * 1024); } while (0)
; #define PG8_LDB(dst, b, h) do { _Pragma("unroll") for (int n = 0; n < 2; ++n) _Pragma("unroll") for (int k = 0; k < 2; ++k) dst[n][k] = *(const PG8_LAS bf16x8*)(lds + PG8_SB(b, h) + boff + n * 2048 + k * 1024); } while (0)
; #define PG8_MMA(ai, bj, At, Bt) do { __builtin_amdgcn_s_setprio(1); _Pragma("unroll") for (int m = 0; m < 4; ++m) _Pragma("unroll") for (int n = 0; n < 2; ++n) _Pragma("unroll") for (int k = 0; k < 2; ++k) \
;         acc[ai][bj][m][n] = __builtin_amdgcn_mfma_f32_16x16x32_bf16(Bt[n][k], At[m][k], acc[ai][bj][m][n], 0, 0, 0); __builtin_amdgcn_s_setprio(0); } while (0)
; #define PG8_WAIT_V(n) asm volatile("s_waitcnt vmcnt(" #n ")" ::: "memory")
; #define PG8_WAIT_L(n) asm volatile("s_waitcnt lgkmcnt(" #n ")" ::: "memory")
; #define PG8_BAR __builtin_amdgcn_s_barrier()
; #define PG8_SCHED __builtin_amdgcn_sched_barrier(0)
; template <class Epi, class Sched, bool ALIGN_EPI = false, bool SP2 = false>
; __device__ __forceinline__ void gemm_phase(PG8_LAS unsigned char* lds, const Gemm g, const Sched& S, const Epi& E) {
;     ...
;             PG8_WAIT_V(8); PG8_WAIT_L(0); PG8_BAR; PG8_MMA(1, 0, At, B0); PG8_MMA(1, 1, At, B1); PG8_BAR; PG8_SCHED;
;             PG8_LDB(B0, 1, 0); PG8_LDB(B1, 1, 1); PG8_SCHED; PG8_LDA(At, 1, 0); PG8_STAGE(PG8_SA(0, 1), a2 + hstep, voffA);
;             PG8_WAIT_V(8); PG8_WAIT_L(0); PG8_BAR; PG8_MMA(0, 0, At, B0); PG8_MMA(0, 1, At, B1); PG8_BAR; PG8_SCHED;
	s_setprio 1
	s_waitcnt lgkmcnt(0)
	v_mfma_f32_16x16x32_bf16 v[68:71], v[28:31], v[210:213], v[68:71]
	v_mfma_f32_16x16x32_bf16 v[64:67], v[40:43], v[210:213], v[64:67]
	v_mfma_f32_16x16x32_bf16 v[32:35], v[28:31], v[220:223], v[32:35]
	v_mfma_f32_16x16x32_bf16 v[24:27], v[40:43], v[220:223], v[24:27]
	v_mfma_f32_16x16x32_bf16 v[12:15], v[28:31], v[228:231], v[12:15]
	v_mfma_f32_16x16x32_bf16 v[8:11], v[40:43], v[228:231], v[8:11]
	v_mfma_f32_16x16x32_bf16 v[84:87], v[36:39], v[164:167], v[84:87]
	v_mfma_f32_16x16x32_bf16 v[80:83], v[44:47], v[164:167], v[80:83]
	v_mfma_f32_16x16x32_bf16 v[68:71], v[36:39], v[216:219], v[68:71]
	v_mfma_f32_16x16x32_bf16 v[64:67], v[44:47], v[216:219], v[64:67]
	v_mfma_f32_16x16x32_bf16 v[32:35], v[36:39], v[224:227], v[32:35]
	v_mfma_f32_16x16x32_bf16 v[24:27], v[44:47], v[224:227], v[24:27]
	v_mfma_f32_16x16x32_bf16 v[12:15], v[36:39], v[232:235], v[12:15]
	v_mfma_f32_16x16x32_bf16 v[8:11], v[44:47], v[232:235], v[8:11]
	s_setprio 0
	s_setprio 1
	v_mfma_f32_16x16x32_bf16 v[20:23], v[48:51], v[220:223], v[20:23]
	v_mfma_f32_16x16x32_bf16 v[16:19], v[152:155], v[220:223], v[16:19]
	v_mfma_f32_16x16x32_bf16 v[4:7], v[48:51], v[228:231], v[4:7]
	v_mfma_f32_16x16x32_bf16 v[0:3], v[152:155], v[228:231], v[0:3]
	v_mfma_f32_16x16x32_bf16 v[28:31], v[48:51], v[160:163], v[76:79]
	v_mfma_f32_16x16x32_bf16 v[36:39], v[152:155], v[160:163], v[72:75]
	v_mfma_f32_16x16x32_bf16 v[40:43], v[48:51], v[210:213], v[60:63]
	v_mfma_f32_16x16x32_bf16 v[44:47], v[152:155], v[210:213], v[56:59]
	v_mfma_f32_16x16x32_bf16 v[20:23], v[52:55], v[224:227], v[20:23]
	v_mfma_f32_16x16x32_bf16 v[16:19], v[156:159], v[224:227], v[16:19]
	v_mfma_f32_16x16x32_bf16 v[4:7], v[52:55], v[232:235], v[4:7]
	v_mfma_f32_16x16x32_bf16 v[0:3], v[156:159], v[232:235], v[0:3]
	v_mfma_f32_16x16x32_bf16 v[28:31], v[52:55], v[164:167], v[28:31]
	v_mfma_f32_16x16x32_bf16 v[36:39], v[156:159], v[164:167], v[36:39]
	v_mfma_f32_16x16x32_bf16 v[40:43], v[52:55], v[216:219], v[40:43]
	v_mfma_f32_16x16x32_bf16 v[44:47], v[156:159], v[216:219], v[44:47]
	s_setprio 0
	s_barrier
	s_add_i32 s22, 0, 0x18000
	s_add_i32 s23, 0, 0x1c000
	v_add_u32_e32 v60, s22, v192
	v_add_u32_e32 v72, s23, v192
	ds_read_b128 v[48:51], v60
	ds_read_b128 v[52:55], v60 offset:1024
	ds_read_b128 v[56:59], v60 offset:2048
	ds_read_b128 v[60:63], v60 offset:3072
	ds_read_b128 v[152:155], v72
	ds_read_b128 v[156:159], v72 offset:1024
	ds_read_b128 v[160:163], v72 offset:2048
	ds_read_b128 v[164:167], v72 offset:3072
	s_add_u32 s20, s74, 0x40000
	s_addc_u32 s21, s75, 0
	s_mov_b32 m0, s86
	v_lshl_add_u64 v[240:241], s[20:21], 0, v[168:169]
	ds_read_b128 v[72:75], v202 offset:32768
	ds_read_b128 v[76:79], v202 offset:33792
	ds_read_b128 v[210:213], v202 offset:34816
	ds_read_b128 v[216:219], v202 offset:35840
	ds_read_b128 v[220:223], v202 offset:36864
	ds_read_b128 v[224:227], v202 offset:37888
	ds_read_b128 v[228:231], v202 offset:38912
	ds_read_b128 v[232:235], v202 offset:39936
	global_load_lds_dwordx4 v[240:241], off
	v_lshl_add_u64 v[240:241], s[20:21], 0, v[172:173]
	s_mov_b32 m0, s87
	s_nop 0
	global_load_lds_dwordx4 v[240:241], off
	s_waitcnt vmcnt(8)
	s_waitcnt lgkmcnt(0)
	v_mfma_f32_16x16x32_bf16 v[148:151], v[48:51], v[72:75], v[148:151]
	v_mfma_f32_16x16x32_bf16 v[144:147], v[56:59], v[72:75], v[144:147]
	s_barrier
	s_setprio 1
	s_waitcnt lgkmcnt(0)
	v_mfma_f32_16x16x32_bf16 v[132:135], v[48:51], v[210:213], v[132:135]
	v_mfma_f32_16x16x32_bf16 v[128:131], v[56:59], v[210:213], v[128:131]
	v_mfma_f32_16x16x32_bf16 v[116:119], v[48:51], v[220:223], v[116:119]
	v_mfma_f32_16x16x32_bf16 v[112:115], v[56:59], v[220:223], v[112:115]
	v_mfma_f32_16x16x32_bf16 v[100:103], v[48:51], v[228:231], v[100:103]
	v_mfma_f32_16x16x32_bf16 v[96:99], v[56:59], v[228:231], v[96:99]
	v_mfma_f32_16x16x32_bf16 v[148:151], v[52:55], v[76:79], v[148:151]
	v_mfma_f32_16x16x32_bf16 v[144:147], v[60:63], v[76:79], v[144:147]
	v_mfma_f32_16x16x32_bf16 v[132:135], v[52:55], v[216:219], v[132:135]
	v_mfma_f32_16x16x32_bf16 v[128:131], v[60:63], v[216:219], v[128:131]
	v_mfma_f32_16x16x32_bf16 v[116:119], v[52:55], v[224:227], v[116:119]
	v_mfma_f32_16x16x32_bf16 v[112:115], v[60:63], v[224:227], v[112:115]
	v_mfma_f32_16x16x32_bf16 v[100:103], v[52:55], v[232:235], v[100:103]
	v_mfma_f32_16x16x32_bf16 v[96:99], v[60:63], v[232:235], v[96:99]
	s_setprio 0
	s_setprio 1
	v_mfma_f32_16x16x32_bf16 v[140:143], v[152:155], v[72:75], v[140:143]
	v_mfma_f32_16x16x32_bf16 v[72:75], v[160:163], v[72:75], v[136:139]
	v_mfma_f32_16x16x32_bf16 v[136:139], v[164:167], v[76:79], v[72:75]
	v_mfma_f32_16x16x32_bf16 v[72:75], v[152:155], v[210:213], v[124:127]
	v_mfma_f32_16x16x32_bf16 v[124:127], v[156:159], v[216:219], v[72:75]
	v_mfma_f32_16x16x32_bf16 v[72:75], v[160:163], v[210:213], v[120:123]
	v_mfma_f32_16x16x32_bf16 v[120:123], v[164:167], v[216:219], v[72:75]
	v_mfma_f32_16x16x32_bf16 v[72:75], v[152:155], v[220:223], v[108:111]
	v_mfma_f32_16x16x32_bf16 v[108:111], v[156:159], v[224:227], v[72:75]
	v_mfma_f32_16x16x32_bf16 v[72:75], v[160:163], v[220:223], v[104:107]
	v_mfma_f32_16x16x32_bf16 v[104:107], v[164:167], v[224:227], v[72:75]
	v_mfma_f32_16x16x32_bf16 v[72:75], v[152:155], v[228:231], v[92:95]
	v_mfma_f32_16x16x32_bf16 v[92:95], v[156:159], v[232:235], v[72:75]
	v_mfma_f32_16x16x32_bf16 v[72:75], v[160:163], v[228:231], v[88:91]
	v_mfma_f32_16x16x32_bf16 v[140:143], v[156:159], v[76:79], v[140:143]
	v_mfma_f32_16x16x32_bf16 v[88:91], v[164:167], v[232:235], v[72:75]
	s_setprio 0
	s_barrier
; #define PG8_STAGE(bufoff, gbase, voff) do { _Pragma("unroll") for (int _i = 0; _i < 2; ++_i) \
;         __builtin_amdgcn_global_load_lds((const unsigned*)((const char*)(gbase) + (voff)[_i]), (PG8_LAS unsigned*)(lds + (bufoff) + ldsw + _i * 8192), 16, 0, 0); } while (0)
; #define PG8_LDA(dst, b, h) do { _Pragma("unroll") for (int m = 0; m < 4; ++m) _Pragma("unroll") for (int k = 0; k < 2; ++k) dst[m][k] = *(const PG8_LAS bf16x8*)(lds + PG8_SA(b, h) + aoff + m * 2048 + k * 1024); } while (0)
; #define PG8_MMA(ai, bj, At, Bt) do { __builtin_amdgcn_s_setprio(1); _Pragma("unroll") for (int m = 0; m < 4; ++m) _Pragma("unroll") for (int n = 0; n < 2; ++n) _Pragma("unroll") for (int k = 0; k < 2; ++k) \
;         acc[ai][bj][m][n] = __builtin_amdgcn_mfma_f32_16x16x32_bf16(Bt[n][k], At[m][k], acc[ai][bj][m][n], 0, 0, 0); __builtin_amdgcn_s_setprio(0); } while (0)
; #define PG8_WAIT_V(n) asm volatile("s_waitcnt vmcnt(" #n ")" ::: "memory")
; #define PG8_WAIT_L(n) asm volatile("s_waitcnt lgkmcnt(" #n ")" ::: "memory")
; #define PG8_BAR __builtin_amdgcn_s_barrier()
; #define PG8_SCHED __builtin_amdgcn_sched_barrier(0)
; template <class Epi, class Sched, bool ALIGN_EPI = false, bool SP2 = false>
; __device__ __forceinline__ void gemm_phase(PG8_LAS unsigned char* lds, const Gemm g, const Sched& S, const Epi& E) {
;     ...
;             PG8_LDA(At, 1, 1); PG8_STAGE(PG8_SB(1, 0), b3, voffB); PG8_STAGE(PG8_SB(1, 1), b3 + hstepB, voffB); PG8_STAGE(PG8_SA(1, 0), a3, voffA);
;             PG8_WAIT_V(8); PG8_WAIT_L(0); PG8_BAR; PG8_MMA(1, 0, At, B0); PG8_MMA(1, 1, At, B1); PG8_BAR; PG8_SCHED;
;     ...
;         if constexpr (ALIGN_EPI) { if (wr == 0) PG8_BAR; }
	s_add_i32 s20, s22, s84
	v_lshl_add_u64 v[76:77], v[190:191], 0, s[44:45]
	s_mov_b32 m0, s20
	s_nop 0
	ds_read_b128 v[72:75], v202 offset:49152
	ds_read_b128 v[210:213], v202 offset:50176
	ds_read_b128 v[216:219], v202 offset:51200
	ds_read_b128 v[220:223], v202 offset:52224
	ds_read_b128 v[224:227], v202 offset:53248
	ds_read_b128 v[228:231], v202 offset:54272
	ds_read_b128 v[232:235], v202 offset:55296
	ds_read_b128 v[240:243], v202 offset:56320
	global_load_lds_dwordx4 v[76:77], off
	s_add_i32 m0, s20, 0x2000
	s_add_u32 s12, s12, 0x10080
	v_lshl_add_u64 v[76:77], v[236:237], 0, s[44:45]
	s_addc_u32 s13, s13, 0
	s_add_i32 s20, s23, s84
	global_load_lds_dwordx4 v[76:77], off
	v_lshl_add_u64 v[76:77], s[12:13], 0, v[170:171]
	s_mov_b32 m0, s20
	s_nop 0
	global_load_lds_dwordx4 v[76:77], off
	v_lshl_add_u64 v[76:77], s[12:13], 0, v[174:175]
	s_add_i32 m0, s20, 0x2000
	s_nop 0
	global_load_lds_dwordx4 v[76:77], off
	v_lshl_add_u64 v[76:77], v[244:245], 0, s[44:45]
	s_mov_b32 m0, s92
	s_nop 0
	global_load_lds_dwordx4 v[76:77], off
	v_lshl_add_u64 v[76:77], v[246:247], 0, s[44:45]
	s_mov_b32 m0, s93
	s_nop 0
	global_load_lds_dwordx4 v[76:77], off
	s_waitcnt vmcnt(8)
	s_waitcnt lgkmcnt(0)
	v_mfma_f32_16x16x32_bf16 v[76:79], v[48:51], v[72:75], v[84:87]
	v_mfma_f32_16x16x32_bf16 v[84:87], v[52:55], v[210:213], v[76:79]
	s_barrier
	s_setprio 1
	s_waitcnt lgkmcnt(0)
	v_mfma_f32_16x16x32_bf16 v[76:79], v[56:59], v[72:75], v[80:83]
	v_mfma_f32_16x16x32_bf16 v[68:71], v[48:51], v[216:219], v[68:71]
	v_mfma_f32_16x16x32_bf16 v[64:67], v[56:59], v[216:219], v[64:67]
	v_mfma_f32_16x16x32_bf16 v[32:35], v[48:51], v[224:227], v[32:35]
	v_mfma_f32_16x16x32_bf16 v[24:27], v[56:59], v[224:227], v[24:27]
	v_mfma_f32_16x16x32_bf16 v[12:15], v[48:51], v[232:235], v[12:15]
	v_mfma_f32_16x16x32_bf16 v[8:11], v[56:59], v[232:235], v[8:11]
	v_mfma_f32_16x16x32_bf16 v[80:83], v[60:63], v[210:213], v[76:79]
	v_mfma_f32_16x16x32_bf16 v[68:71], v[52:55], v[220:223], v[68:71]
	v_mfma_f32_16x16x32_bf16 v[64:67], v[60:63], v[220:223], v[64:67]
	v_mfma_f32_16x16x32_bf16 v[32:35], v[52:55], v[228:231], v[32:35]
	v_mfma_f32_16x16x32_bf16 v[24:27], v[60:63], v[228:231], v[24:27]
	v_mfma_f32_16x16x32_bf16 v[12:15], v[52:55], v[240:243], v[12:15]
	v_mfma_f32_16x16x32_bf16 v[8:11], v[60:63], v[240:243], v[8:11]
	s_setprio 0
	s_setprio 1
	v_mfma_f32_16x16x32_bf16 v[28:31], v[152:155], v[72:75], v[28:31]
	v_mfma_f32_16x16x32_bf16 v[76:79], v[156:159], v[210:213], v[28:31]
	v_mfma_f32_16x16x32_bf16 v[28:31], v[160:163], v[72:75], v[36:39]
	v_mfma_f32_16x16x32_bf16 v[72:75], v[164:167], v[210:213], v[28:31]
	v_mfma_f32_16x16x32_bf16 v[28:31], v[152:155], v[216:219], v[40:43]
	v_mfma_f32_16x16x32_bf16 v[60:63], v[156:159], v[220:223], v[28:31]
	v_mfma_f32_16x16x32_bf16 v[28:31], v[160:163], v[216:219], v[44:47]
	v_mfma_f32_16x16x32_bf16 v[20:23], v[152:155], v[224:227], v[20:23]
	v_mfma_f32_16x16x32_bf16 v[16:19], v[160:163], v[224:227], v[16:19]
	v_mfma_f32_16x16x32_bf16 v[4:7], v[152:155], v[232:235], v[4:7]
	v_mfma_f32_16x16x32_bf16 v[0:3], v[160:163], v[232:235], v[0:3]
	v_mfma_f32_16x16x32_bf16 v[56:59], v[164:167], v[220:223], v[28:31]
	v_mfma_f32_16x16x32_bf16 v[20:23], v[156:159], v[228:231], v[20:23]
	v_mfma_f32_16x16x32_bf16 v[16:19], v[164:167], v[228:231], v[16:19]
	v_mfma_f32_16x16x32_bf16 v[4:7], v[156:159], v[240:243], v[4:7]
	v_mfma_f32_16x16x32_bf16 v[0:3], v[164:167], v[240:243], v[0:3]
	s_setprio 0
	s_barrier
	s_add_i32 s19, s19, 2
	s_add_u32 s10, s10, 0x100
	s_addc_u32 s11, s11, 0
	s_add_u32 s17, s17, 0x100
	s_addc_u32 s18, s18, 0
	s_cmp_gt_u32 s19, 13
	s_cbranch_scc0 .LBB0_688
	s_and_b64 vcc, exec, s[64:65]
	s_cbranch_vccz .LBB0_691
	s_barrier

; #define PG8_STAGE(bufoff, gbase, voff) do { _Pragma("unroll") for (int _i = 0; _i < 2; ++_i) \
;         __builtin_amdgcn_global_load_lds((const unsigned*)((const char*)(gbase) + (voff)[_i]), (PG8_LAS unsigned*)(lds + (bufoff) + ldsw + _i * 8192), 16, 0, 0); } while (0)
; #define PG8_LDA(dst, b, h) do { _Pragma("unroll") for (int m = 0; m < 4; ++m) _Pragma("unroll") for (int k = 0; k < 2; ++k) dst[m][k] = *(const PG8_LAS bf16x8*)(lds + PG8_SA(b, h) + aoff + m * 2048 + k * 1024); } while (0)
; #define PG8_LDB(dst, b, h) do { _Pragma("unroll") for (int n = 0; n < 2; ++n) _Pragma("unroll") for (int k = 0; k < 2; ++k) dst[n][k] = *(const PG8_LAS bf16x8*)(lds + PG8_SB(b, h) + boff + n * 2048 + k * 1024); } while (0)
; #define PG8_MMA(ai, bj, At, Bt) do { __builtin_amdgcn_s_setprio(1); _Pragma("unroll") for (int m = 0; m < 4; ++m) _Pragma("unroll") for (int n = 0; n < 2; ++n) _Pragma("unroll") for (int k = 0; k < 2; ++k) \
;         acc[ai][bj][m][n] = __builtin_amdgcn_mfma_f32_16x16x32_bf16(Bt[n][k], At[m][k], acc[ai][bj][m][n], 0, 0, 0); __builtin_amdgcn_s_setprio(0); } while (0)
; #define PG8_WAIT_V(n) asm volatile("s_waitcnt vmcnt(" #n ")" ::: "memory")
; #define PG8_WAIT_L(n) asm volatile("s_waitcnt lgkmcnt(" #n ")" ::: "memory")
; #define PG8_BAR __builtin_amdgcn_s_barrier()
; template <class Epi, class Sched, bool ALIGN_EPI = false, bool SP2 = false>
; __device__ __forceinline__ void gemm_phase(PG8_LAS unsigned char* lds, const Gemm g, const Sched& S, const Epi& E) {
;     ...
;         for (int t = 0; t < nt; t += 2) {
;             const bool last = (t == nt - 2);
;             const char* a1 = cA + (size_t)(t + 1) * kstep;
;             const char* a2 = last ? nA : cA + (size_t)(t + 2) * kstep; const char* b2 = last ? nB : cB + (size_t)(t + 2) * kstep;
;             const char* a3 = a2 + kstep; const char* b3 = b2 + kstep;
;             if (last && has_next) S.a_ready(nxt);
;             if (last) E.pre(lds, cur, wid, tid);
;             if constexpr (SP2) {
;             PG8_LDB(B0, 0, 0); PG8_LDB(B1, 0, 1); PG8_SCHED; PG8_LDA(At, 0, 0); PG8_STAGE(PG8_SA(1, 1), a1 + hstep, voffA);
;             PG8_WAIT_V(8); PG8_WAIT_L(0); PG8_BAR; PG8_MMA(0, 0, At, B0); PG8_MMA(0, 1, At, B1); PG8_BAR; PG8_SCHED;
;             PG8_LDA(At, 0, 1); PG8_STAGE(PG8_SB(0, 0), b2, voffB); PG8_STAGE(PG8_SB(0, 1), b2 + hstepB, voffB); PG8_STAGE(PG8_SA(0, 0), a2, voffA);
.LBB0_985:
	ds_read_b128 v[144:147], v163
	ds_read_b128 v[148:151], v163 offset:1024
	ds_read_b128 v[152:155], v163 offset:2048
	ds_read_b128 v[156:159], v163 offset:3072
	ds_read_b128 v[168:171], v164
	ds_read_b128 v[172:175], v164 offset:1024
	ds_read_b128 v[176:179], v164 offset:2048
	ds_read_b128 v[180:183], v164 offset:3072
	s_add_u32 s48, s46, 0x100
	s_addc_u32 s49, s47, 0
	s_cmp_eq_u32 s73, 12
	s_cselect_b32 s65, s23, s49
	s_cselect_b32 s64, s43, s48
	s_cselect_b32 s51, s21, s72
	s_cselect_b32 s50, s45, s71
	v_lshl_add_u64 v[212:213], s[46:47], 0, v[134:135]
	s_add_i32 m0, s30, 0xc000
	ds_read_b128 v[184:187], v165
	ds_read_b128 v[188:191], v165 offset:1024
	ds_read_b128 v[192:195], v165 offset:2048
	ds_read_b128 v[196:199], v165 offset:3072
	ds_read_b128 v[200:203], v165 offset:4096
	ds_read_b128 v[204:207], v165 offset:5120
	ds_read_b128 v[208:211], v165 offset:6144
	ds_read_b128 v[216:219], v165 offset:7168
	global_load_lds_dwordx4 v[212:213], off
	v_lshl_add_u64 v[212:213], s[46:47], 0, v[136:137]
	s_add_i32 m0, s30, 0xe000
	s_nop 0
	global_load_lds_dwordx4 v[212:213], off
	s_waitcnt vmcnt(8)
	s_waitcnt lgkmcnt(0)
	v_mfma_f32_16x16x32_bf16 v[124:127], v[144:147], v[184:187], v[124:127]
	v_mfma_f32_16x16x32_bf16 v[120:123], v[152:155], v[184:187], v[120:123]
	s_barrier
	s_setprio 1
	s_waitcnt lgkmcnt(0)
	v_mfma_f32_16x16x32_bf16 v[108:111], v[144:147], v[192:195], v[108:111]
	v_mfma_f32_16x16x32_bf16 v[104:107], v[152:155], v[192:195], v[104:107]
	v_mfma_f32_16x16x32_bf16 v[92:95], v[144:147], v[200:203], v[92:95]
	v_mfma_f32_16x16x32_bf16 v[88:91], v[152:155], v[200:203], v[88:91]
	v_mfma_f32_16x16x32_bf16 v[76:79], v[144:147], v[208:211], v[76:79]
	v_mfma_f32_16x16x32_bf16 v[72:75], v[152:155], v[208:211], v[72:75]
	v_mfma_f32_16x16x32_bf16 v[124:127], v[148:151], v[188:191], v[124:127]
	v_mfma_f32_16x16x32_bf16 v[120:123], v[156:159], v[188:191], v[120:123]
	v_mfma_f32_16x16x32_bf16 v[108:111], v[148:151], v[196:199], v[108:111]
	v_mfma_f32_16x16x32_bf16 v[104:107], v[156:159], v[196:199], v[104:107]
	v_mfma_f32_16x16x32_bf16 v[92:95], v[148:151], v[204:207], v[92:95]
	v_mfma_f32_16x16x32_bf16 v[88:91], v[156:159], v[204:207], v[88:91]
	v_mfma_f32_16x16x32_bf16 v[76:79], v[148:151], v[216:219], v[76:79]
	v_mfma_f32_16x16x32_bf16 v[72:75], v[156:159], v[216:219], v[72:75]
	s_setprio 0
	s_setprio 1
	v_mfma_f32_16x16x32_bf16 v[116:119], v[168:171], v[184:187], v[116:119]
	v_mfma_f32_16x16x32_bf16 v[112:115], v[176:179], v[184:187], v[112:115]
	v_mfma_f32_16x16x32_bf16 v[100:103], v[168:171], v[192:195], v[100:103]
	v_mfma_f32_16x16x32_bf16 v[96:99], v[176:179], v[192:195], v[96:99]
	v_mfma_f32_16x16x32_bf16 v[84:87], v[168:171], v[200:203], v[84:87]
	v_mfma_f32_16x16x32_bf16 v[80:83], v[176:179], v[200:203], v[80:83]
	v_mfma_f32_16x16x32_bf16 v[68:71], v[168:171], v[208:211], v[68:71]
	v_mfma_f32_16x16x32_bf16 v[64:67], v[176:179], v[208:211], v[64:67]
	v_mfma_f32_16x16x32_bf16 v[116:119], v[172:175], v[188:191], v[116:119]
	v_mfma_f32_16x16x32_bf16 v[112:115], v[180:183], v[188:191], v[112:115]
	v_mfma_f32_16x16x32_bf16 v[100:103], v[172:175], v[196:199], v[100:103]
	v_mfma_f32_16x16x32_bf16 v[96:99], v[180:183], v[196:199], v[96:99]
	v_mfma_f32_16x16x32_bf16 v[84:87], v[172:175], v[204:207], v[84:87]
	v_mfma_f32_16x16x32_bf16 v[80:83], v[180:183], v[204:207], v[80:83]
	v_mfma_f32_16x16x32_bf16 v[68:71], v[172:175], v[216:219], v[68:71]
	v_mfma_f32_16x16x32_bf16 v[64:67], v[180:183], v[216:219], v[64:67]
	s_setprio 0
	s_barrier
	s_add_i32 s46, s68, s15
	v_lshl_add_u64 v[212:213], s[50:51], 0, v[128:129]
	s_mov_b32 m0, s46
	ds_read_b128 v[184:187], v165 offset:16384
	ds_read_b128 v[188:191], v165 offset:17408
	ds_read_b128 v[192:195], v165 offset:18432
	ds_read_b128 v[196:199], v165 offset:19456
	ds_read_b128 v[200:203], v165 offset:20480
	ds_read_b128 v[204:207], v165 offset:21504
	ds_read_b128 v[208:211], v165 offset:22528
	ds_read_b128 v[216:219], v165 offset:23552
	global_load_lds_dwordx4 v[212:213], off
	s_add_i32 m0, s46, 0x2000
	s_add_u32 s46, s50, 0x40000
	v_lshl_add_u64 v[220:221], s[50:51], 0, v[130:131]
	s_addc_u32 s47, s51, 0
	s_add_i32 s74, s69, s15
	global_load_lds_dwordx4 v[220:221], off
	v_lshl_add_u64 v[222:223], s[46:47], 0, v[128:129]
	s_mov_b32 m0, s74
	v_lshl_add_u64 v[224:225], s[64:65], 0, v[130:131]
	global_load_lds_dwordx4 v[222:223], off
	v_lshl_add_u64 v[222:223], s[46:47], 0, v[130:131]
	s_add_i32 m0, s74, 0x2000
	s_nop 0
	global_load_lds_dwordx4 v[222:223], off
	v_lshl_add_u64 v[222:223], s[64:65], 0, v[128:129]
	s_mov_b32 m0, s30
	s_nop 0
	global_load_lds_dwordx4 v[222:223], off
	s_mov_b32 m0, s31
	s_nop 0
	global_load_lds_dwordx4 v[224:225], off
	s_waitcnt vmcnt(8)
	s_waitcnt lgkmcnt(0)
	v_mfma_f32_16x16x32_bf16 v[60:63], v[144:147], v[184:187], v[60:63]
	v_mfma_f32_16x16x32_bf16 v[56:59], v[152:155], v[184:187], v[56:59]
	s_barrier
; #define PG8_STAGE(bufoff, gbase, voff) do { _Pragma("unroll") for (int _i = 0; _i < 2; ++_i) \
;         __builtin_amdgcn_global_load_lds((const unsigned*)((const char*)(gbase) + (voff)[_i]), (PG8_LAS unsigned*)(lds + (bufoff) + ldsw + _i * 8192), 16, 0, 0); } while (0)
; #define PG8_LDA(dst, b, h) do { _Pragma("unroll") for (int m = 0; m < 4; ++m) _Pragma("unroll") for (int k = 0; k < 2; ++k) dst[m][k] = *(const PG8_LAS bf16x8*)(lds + PG8_SA(b, h) + aoff + m * 2048 + k * 1024); } while (0)
; #define PG8_LDB(dst, b, h) do { _Pragma("unroll") for (int n = 0; n < 2; ++n) _Pragma("unroll") for (int k = 0; k < 2; ++k) dst[n][k] = *(const PG8_LAS bf16x8*)(lds + PG8_SB(b, h) + boff + n * 2048 + k * 1024); } while (0)
; #define PG8_MMA(ai, bj, At, Bt) do { __builtin_amdgcn_s_setprio(1); _Pragma("unroll") for (int m = 0; m < 4; ++m) _Pragma("unroll") for (int n = 0; n < 2; ++n) _Pragma("unroll") for (int k = 0; k < 2; ++k) \
;         acc[ai][bj][m][n] = __builtin_amdgcn_mfma_f32_16x16x32_bf16(Bt[n][k], At[m][k], acc[ai][bj][m][n], 0, 0, 0); __builtin_amdgcn_s_setprio(0); } while (0)
; #define PG8_WAIT_V(n) asm volatile("s_waitcnt vmcnt(" #n ")" ::: "memory")
; #define PG8_WAIT_L(n) asm volatile("s_waitcnt lgkmcnt(" #n ")" ::: "memory")
; #define PG8_BAR __builtin_amdgcn_s_barrier()
; #define PG8_SCHED __builtin_amdgcn_sched_barrier(0)
; template <class Epi, class Sched, bool ALIGN_EPI = false, bool SP2 = false>
; __device__ __forceinline__ void gemm_phase(PG8_LAS unsigned char* lds, const Gemm g, const Sched& S, const Epi& E) {
;     ...
;             PG8_WAIT_V(8); PG8_WAIT_L(0); PG8_BAR; PG8_MMA(1, 0, At, B0); PG8_MMA(1, 1, At, B1); PG8_BAR; PG8_SCHED;
;             PG8_LDB(B0, 1, 0); PG8_LDB(B1, 1, 1); PG8_SCHED; PG8_LDA(At, 1, 0); PG8_STAGE(PG8_SA(0, 1), a2 + hstep, voffA);
;             PG8_WAIT_V(8); PG8_WAIT_L(0); PG8_BAR; PG8_MMA(0, 0, At, B0); PG8_MMA(0, 1, At, B1); PG8_BAR; PG8_SCHED;
	s_setprio 1
	s_waitcnt lgkmcnt(0)
	v_mfma_f32_16x16x32_bf16 v[44:47], v[144:147], v[192:195], v[44:47]
	v_mfma_f32_16x16x32_bf16 v[40:43], v[152:155], v[192:195], v[40:43]
	v_mfma_f32_16x16x32_bf16 v[28:31], v[144:147], v[200:203], v[28:31]
	v_mfma_f32_16x16x32_bf16 v[24:27], v[152:155], v[200:203], v[24:27]
	v_mfma_f32_16x16x32_bf16 v[12:15], v[144:147], v[208:211], v[12:15]
	v_mfma_f32_16x16x32_bf16 v[8:11], v[152:155], v[208:211], v[8:11]
	v_mfma_f32_16x16x32_bf16 v[60:63], v[148:151], v[188:191], v[60:63]
	v_mfma_f32_16x16x32_bf16 v[56:59], v[156:159], v[188:191], v[56:59]
	v_mfma_f32_16x16x32_bf16 v[44:47], v[148:151], v[196:199], v[44:47]
	v_mfma_f32_16x16x32_bf16 v[40:43], v[156:159], v[196:199], v[40:43]
	v_mfma_f32_16x16x32_bf16 v[28:31], v[148:151], v[204:207], v[28:31]
	v_mfma_f32_16x16x32_bf16 v[24:27], v[156:159], v[204:207], v[24:27]
	v_mfma_f32_16x16x32_bf16 v[12:15], v[148:151], v[216:219], v[12:15]
	v_mfma_f32_16x16x32_bf16 v[8:11], v[156:159], v[216:219], v[8:11]
	s_setprio 0
	s_setprio 1
	v_mfma_f32_16x16x32_bf16 v[52:55], v[168:171], v[184:187], v[52:55]
	v_mfma_f32_16x16x32_bf16 v[48:51], v[176:179], v[184:187], v[48:51]
	v_mfma_f32_16x16x32_bf16 v[36:39], v[168:171], v[192:195], v[36:39]
	v_mfma_f32_16x16x32_bf16 v[32:35], v[176:179], v[192:195], v[32:35]
	v_mfma_f32_16x16x32_bf16 v[20:23], v[168:171], v[200:203], v[20:23]
	v_mfma_f32_16x16x32_bf16 v[16:19], v[176:179], v[200:203], v[16:19]
	v_mfma_f32_16x16x32_bf16 v[4:7], v[168:171], v[208:211], v[4:7]
	v_mfma_f32_16x16x32_bf16 v[0:3], v[176:179], v[208:211], v[0:3]
	v_mfma_f32_16x16x32_bf16 v[52:55], v[172:175], v[188:191], v[52:55]
	v_mfma_f32_16x16x32_bf16 v[48:51], v[180:183], v[188:191], v[48:51]
	v_mfma_f32_16x16x32_bf16 v[36:39], v[172:175], v[196:199], v[36:39]
	v_mfma_f32_16x16x32_bf16 v[32:35], v[180:183], v[196:199], v[32:35]
	v_mfma_f32_16x16x32_bf16 v[20:23], v[172:175], v[204:207], v[20:23]
	v_mfma_f32_16x16x32_bf16 v[16:19], v[180:183], v[204:207], v[16:19]
	v_mfma_f32_16x16x32_bf16 v[4:7], v[172:175], v[216:219], v[4:7]
	v_mfma_f32_16x16x32_bf16 v[0:3], v[180:183], v[216:219], v[0:3]
	s_setprio 0
	s_barrier
	s_add_i32 s74, 0, 0x18000
	v_add_u32_e32 v143, s74, v161
	s_add_i32 s75, 0, 0x1c000
	ds_read_b128 v[144:147], v143
	ds_read_b128 v[148:151], v143 offset:1024
	ds_read_b128 v[152:155], v143 offset:2048
	ds_read_b128 v[156:159], v143 offset:3072
	v_add_u32_e32 v143, s75, v161
	ds_read_b128 v[168:171], v143
	ds_read_b128 v[172:175], v143 offset:1024
	ds_read_b128 v[176:179], v143 offset:2048
	ds_read_b128 v[180:183], v143 offset:3072
	s_add_u32 s46, s64, 0x40000
	s_addc_u32 s47, s65, 0
	s_mov_b32 m0, s35
	v_lshl_add_u64 v[226:227], s[46:47], 0, v[128:129]
	ds_read_b128 v[184:187], v165 offset:32768
	ds_read_b128 v[188:191], v165 offset:33792
	ds_read_b128 v[192:195], v165 offset:34816
	ds_read_b128 v[196:199], v165 offset:35840
	ds_read_b128 v[200:203], v165 offset:36864
	ds_read_b128 v[204:207], v165 offset:37888
	ds_read_b128 v[208:211], v165 offset:38912
	ds_read_b128 v[216:219], v165 offset:39936
	global_load_lds_dwordx4 v[226:227], off
	v_lshl_add_u64 v[226:227], s[46:47], 0, v[130:131]
	s_mov_b32 m0, s60
	s_nop 0
	global_load_lds_dwordx4 v[226:227], off
	s_waitcnt vmcnt(8)
	s_waitcnt lgkmcnt(0)
	v_mfma_f32_16x16x32_bf16 v[124:127], v[144:147], v[184:187], v[124:127]
	v_mfma_f32_16x16x32_bf16 v[120:123], v[152:155], v[184:187], v[120:123]
	s_barrier
	s_setprio 1
	s_waitcnt lgkmcnt(0)
	v_mfma_f32_16x16x32_bf16 v[108:111], v[144:147], v[192:195], v[108:111]
	v_mfma_f32_16x16x32_bf16 v[104:107], v[152:155], v[192:195], v[104:107]
	v_mfma_f32_16x16x32_bf16 v[92:95], v[144:147], v[200:203], v[92:95]
	v_mfma_f32_16x16x32_bf16 v[88:91], v[152:155], v[200:203], v[88:91]
	v_mfma_f32_16x16x32_bf16 v[76:79], v[144:147], v[208:211], v[76:79]
	v_mfma_f32_16x16x32_bf16 v[72:75], v[152:155], v[208:211], v[72:75]
	v_mfma_f32_16x16x32_bf16 v[124:127], v[148:151], v[188:191], v[124:127]
	v_mfma_f32_16x16x32_bf16 v[120:123], v[156:159], v[188:191], v[120:123]
	v_mfma_f32_16x16x32_bf16 v[108:111], v[148:151], v[196:199], v[108:111]
	v_mfma_f32_16x16x32_bf16 v[104:107], v[156:159], v[196:199], v[104:107]
	v_mfma_f32_16x16x32_bf16 v[92:95], v[148:151], v[204:207], v[92:95]
	v_mfma_f32_16x16x32_bf16 v[88:91], v[156:159], v[204:207], v[88:91]
	v_mfma_f32_16x16x32_bf16 v[76:79], v[148:151], v[216:219], v[76:79]
	v_mfma_f32_16x16x32_bf16 v[72:75], v[156:159], v[216:219], v[72:75]
	s_setprio 0
	s_setprio 1
	v_mfma_f32_16x16x32_bf16 v[116:119], v[168:171], v[184:187], v[116:119]
	v_mfma_f32_16x16x32_bf16 v[112:115], v[176:179], v[184:187], v[112:115]
	v_mfma_f32_16x16x32_bf16 v[100:103], v[168:171], v[192:195], v[100:103]
	v_mfma_f32_16x16x32_bf16 v[96:99], v[176:179], v[192:195], v[96:99]
	v_mfma_f32_16x16x32_bf16 v[84:87], v[168:171], v[200:203], v[84:87]
	v_mfma_f32_16x16x32_bf16 v[80:83], v[176:179], v[200:203], v[80:83]
	v_mfma_f32_16x16x32_bf16 v[68:71], v[168:171], v[208:211], v[68:71]
	v_mfma_f32_16x16x32_bf16 v[64:67], v[176:179], v[208:211], v[64:67]
	v_mfma_f32_16x16x32_bf16 v[116:119], v[172:175], v[188:191], v[116:119]
	v_mfma_f32_16x16x32_bf16 v[112:115], v[180:183], v[188:191], v[112:115]
	v_mfma_f32_16x16x32_bf16 v[100:103], v[172:175], v[196:199], v[100:103]
	v_mfma_f32_16x16x32_bf16 v[96:99], v[180:183], v[196:199], v[96:99]
	v_mfma_f32_16x16x32_bf16 v[84:87], v[172:175], v[204:207], v[84:87]
	v_mfma_f32_16x16x32_bf16 v[80:83], v[180:183], v[204:207], v[80:83]
	v_mfma_f32_16x16x32_bf16 v[68:71], v[172:175], v[216:219], v[68:71]
	v_mfma_f32_16x16x32_bf16 v[64:67], v[180:183], v[216:219], v[64:67]
	s_setprio 0
	s_barrier
; #define PG8_STAGE(bufoff, gbase, voff) do { _Pragma("unroll") for (int _i = 0; _i < 2; ++_i) \
;         __builtin_amdgcn_global_load_lds((const unsigned*)((const char*)(gbase) + (voff)[_i]), (PG8_LAS unsigned*)(lds + (bufoff) + ldsw + _i * 8192), 16, 0, 0); } while (0)
; #define PG8_LDA(dst, b, h) do { _Pragma("unroll") for (int m = 0; m < 4; ++m) _Pragma("unroll") for (int k = 0; k < 2; ++k) dst[m][k] = *(const PG8_LAS bf16x8*)(lds + PG8_SA(b, h) + aoff + m * 2048 + k * 1024); } while (0)
; #define PG8_MMA(ai, bj, At, Bt) do { __builtin_amdgcn_s_setprio(1); _Pragma("unroll") for (int m = 0; m < 4; ++m) _Pragma("unroll") for (int n = 0; n < 2; ++n) _Pragma("unroll") for (int k = 0; k < 2; ++k) \
;         acc[ai][bj][m][n] = __builtin_amdgcn_mfma_f32_16x16x32_bf16(Bt[n][k], At[m][k], acc[ai][bj][m][n], 0, 0, 0); __builtin_amdgcn_s_setprio(0); } while (0)
; #define PG8_WAIT_V(n) asm volatile("s_waitcnt vmcnt(" #n ")" ::: "memory")
; #define PG8_WAIT_L(n) asm volatile("s_waitcnt lgkmcnt(" #n ")" ::: "memory")
; #define PG8_BAR __builtin_amdgcn_s_barrier()
; #define PG8_SCHED __builtin_amdgcn_sched_barrier(0)
; template <class Epi, class Sched, bool ALIGN_EPI = false, bool SP2 = false>
; __device__ __forceinline__ void gemm_phase(PG8_LAS unsigned char* lds, const Gemm g, const Sched& S, const Epi& E) {
;     ...
;             PG8_LDA(At, 1, 1); PG8_STAGE(PG8_SB(1, 0), b3, voffB); PG8_STAGE(PG8_SB(1, 1), b3 + hstepB, voffB); PG8_STAGE(PG8_SA(1, 0), a3, voffA);
;             PG8_WAIT_V(8); PG8_WAIT_L(0); PG8_BAR; PG8_MMA(1, 0, At, B0); PG8_MMA(1, 1, At, B1); PG8_BAR; PG8_SCHED;
;     ...
;         if constexpr (ALIGN_EPI) { if (wr == 0) PG8_BAR; }
	s_add_i32 s46, s74, s15
	v_lshl_add_u64 v[212:213], v[212:213], 0, s[16:17]
	s_mov_b32 m0, s46
	ds_read_b128 v[184:187], v165 offset:49152
	ds_read_b128 v[188:191], v165 offset:50176
	ds_read_b128 v[192:195], v165 offset:51200
	ds_read_b128 v[196:199], v165 offset:52224
	ds_read_b128 v[200:203], v165 offset:53248
	ds_read_b128 v[204:207], v165 offset:54272
	ds_read_b128 v[208:211], v165 offset:55296
	ds_read_b128 v[216:219], v165 offset:56320
	global_load_lds_dwordx4 v[212:213], off
	s_add_i32 m0, s46, 0x2000
	s_add_u32 s46, s50, 0x40080
	v_lshl_add_u64 v[212:213], v[220:221], 0, s[16:17]
	s_addc_u32 s47, s51, 0
	s_add_i32 s50, s75, s15
	global_load_lds_dwordx4 v[212:213], off
	v_lshl_add_u64 v[212:213], s[46:47], 0, v[128:129]
	s_mov_b32 m0, s50
	s_nop 0
	global_load_lds_dwordx4 v[212:213], off
	v_lshl_add_u64 v[212:213], s[46:47], 0, v[130:131]
	s_add_i32 m0, s50, 0x2000
	s_nop 0
	global_load_lds_dwordx4 v[212:213], off
	v_lshl_add_u64 v[212:213], v[222:223], 0, s[16:17]
	s_mov_b32 m0, s61
	s_nop 0
	global_load_lds_dwordx4 v[212:213], off
	v_lshl_add_u64 v[212:213], v[224:225], 0, s[16:17]
	s_mov_b32 m0, s62
	s_nop 0
	global_load_lds_dwordx4 v[212:213], off
	s_waitcnt vmcnt(8)
	s_waitcnt lgkmcnt(0)
	v_mfma_f32_16x16x32_bf16 v[60:63], v[144:147], v[184:187], v[60:63]
	v_mfma_f32_16x16x32_bf16 v[56:59], v[152:155], v[184:187], v[56:59]
	s_barrier
	s_setprio 1
	s_waitcnt lgkmcnt(0)
	v_mfma_f32_16x16x32_bf16 v[44:47], v[144:147], v[192:195], v[44:47]
	v_mfma_f32_16x16x32_bf16 v[40:43], v[152:155], v[192:195], v[40:43]
	v_mfma_f32_16x16x32_bf16 v[28:31], v[144:147], v[200:203], v[28:31]
	v_mfma_f32_16x16x32_bf16 v[24:27], v[152:155], v[200:203], v[24:27]
	v_mfma_f32_16x16x32_bf16 v[12:15], v[144:147], v[208:211], v[12:15]
	v_mfma_f32_16x16x32_bf16 v[8:11], v[152:155], v[208:211], v[8:11]
	v_mfma_f32_16x16x32_bf16 v[60:63], v[148:151], v[188:191], v[60:63]
	v_mfma_f32_16x16x32_bf16 v[56:59], v[156:159], v[188:191], v[56:59]
	v_mfma_f32_16x16x32_bf16 v[44:47], v[148:151], v[196:199], v[44:47]
	v_mfma_f32_16x16x32_bf16 v[40:43], v[156:159], v[196:199], v[40:43]
	v_mfma_f32_16x16x32_bf16 v[28:31], v[148:151], v[204:207], v[28:31]
	v_mfma_f32_16x16x32_bf16 v[24:27], v[156:159], v[204:207], v[24:27]
	v_mfma_f32_16x16x32_bf16 v[12:15], v[148:151], v[216:219], v[12:15]
	v_mfma_f32_16x16x32_bf16 v[8:11], v[156:159], v[216:219], v[8:11]
	s_setprio 0
	s_setprio 1
	v_mfma_f32_16x16x32_bf16 v[52:55], v[168:171], v[184:187], v[52:55]
	v_mfma_f32_16x16x32_bf16 v[48:51], v[176:179], v[184:187], v[48:51]
	v_mfma_f32_16x16x32_bf16 v[36:39], v[168:171], v[192:195], v[36:39]
	v_mfma_f32_16x16x32_bf16 v[32:35], v[176:179], v[192:195], v[32:35]
	v_mfma_f32_16x16x32_bf16 v[20:23], v[168:171], v[200:203], v[20:23]
	v_mfma_f32_16x16x32_bf16 v[16:19], v[176:179], v[200:203], v[16:19]
	v_mfma_f32_16x16x32_bf16 v[4:7], v[168:171], v[208:211], v[4:7]
	v_mfma_f32_16x16x32_bf16 v[0:3], v[176:179], v[208:211], v[0:3]
	v_mfma_f32_16x16x32_bf16 v[52:55], v[172:175], v[188:191], v[52:55]
	v_mfma_f32_16x16x32_bf16 v[48:51], v[180:183], v[188:191], v[48:51]
	v_mfma_f32_16x16x32_bf16 v[36:39], v[172:175], v[196:199], v[36:39]
	v_mfma_f32_16x16x32_bf16 v[32:35], v[180:183], v[196:199], v[32:35]
	v_mfma_f32_16x16x32_bf16 v[20:23], v[172:175], v[204:207], v[20:23]
	v_mfma_f32_16x16x32_bf16 v[16:19], v[180:183], v[204:207], v[16:19]
	v_mfma_f32_16x16x32_bf16 v[4:7], v[172:175], v[216:219], v[4:7]
	v_mfma_f32_16x16x32_bf16 v[0:3], v[180:183], v[216:219], v[0:3]
	s_setprio 0
	s_barrier
	s_add_i32 s73, s73, 2
	s_add_u32 s71, s71, 0x100
	s_addc_u32 s72, s72, 0
	s_cmp_gt_u32 s73, 13
	s_mov_b64 s[46:47], s[48:49]
	s_cbranch_scc0 .LBB0_985
	s_and_b64 vcc, exec, s[18:19]
	s_cbranch_vccz .LBB0_988
	s_barrier

; #define PG8_STAGE(bufoff, gbase, voff) do { _Pragma("unroll") for (int _i = 0; _i < 2; ++_i) \
;         __builtin_amdgcn_global_load_lds((const unsigned*)((const char*)(gbase) + (voff)[_i]), (PG8_LAS unsigned*)(lds + (bufoff) + ldsw + _i * 8192), 16, 0, 0); } while (0)
; #define PG8_LDA(dst, b, h) do { _Pragma("unroll") for (int m = 0; m < 4; ++m) _Pragma("unroll") for (int k = 0; k < 2; ++k) dst[m][k] = *(const PG8_LAS bf16x8*)(lds + PG8_SA(b, h) + aoff + m * 2048 + k * 1024); } while (0)
; #define PG8_LDB(dst, b, h) do { _Pragma("unroll") for (int n = 0; n < 2; ++n) _Pragma("unroll") for (int k = 0; k < 2; ++k) dst[n][k] = *(const PG8_LAS bf16x8*)(lds + PG8_SB(b, h) + boff + n * 2048 + k * 1024); } while (0)
; #define PG8_MMA(ai, bj, At, Bt) do { __builtin_amdgcn_s_setprio(1); _Pragma("unroll") for (int m = 0; m < 4; ++m) _Pragma("unroll") for (int n = 0; n < 2; ++n) _Pragma("unroll") for (int k = 0; k < 2; ++k) \
;         acc[ai][bj][m][n] = __builtin_amdgcn_mfma_f32_16x16x32_bf16(Bt[n][k], At[m][k], acc[ai][bj][m][n], 0, 0, 0); __builtin_amdgcn_s_setprio(0); } while (0)
; #define PG8_WAIT_V(n) asm volatile("s_waitcnt vmcnt(" #n ")" ::: "memory")
; #define PG8_WAIT_L(n) asm volatile("s_waitcnt lgkmcnt(" #n ")" ::: "memory")
; #define PG8_BAR __builtin_amdgcn_s_barrier()
; template <class Epi, class Sched, bool ALIGN_EPI = false, bool SP2 = false>
; __device__ __forceinline__ void gemm_phase(PG8_LAS unsigned char* lds, const Gemm g, const Sched& S, const Epi& E) {
;     ...
;         for (int t = 0; t < nt; t += 2) {
;             const bool last = (t == nt - 2);
;             const char* a1 = cA + (size_t)(t + 1) * kstep;
;             const char* a2 = last ? nA : cA + (size_t)(t + 2) * kstep; const char* b2 = last ? nB : cB + (size_t)(t + 2) * kstep;
;             const char* a3 = a2 + kstep; const char* b3 = b2 + kstep;
;             if (last && has_next) S.a_ready(nxt);
;             if (last) E.pre(lds, cur, wid, tid);
;             if constexpr (SP2) {
;             PG8_LDB(B0, 0, 0); PG8_LDB(B1, 0, 1); PG8_SCHED; PG8_LDA(At, 0, 0); PG8_STAGE(PG8_SA(1, 1), a1 + hstep, voffA);
;             PG8_WAIT_V(8); PG8_WAIT_L(0); PG8_BAR; PG8_MMA(0, 0, At, B0); PG8_MMA(0, 1, At, B1); PG8_BAR; PG8_SCHED;
;             PG8_LDA(At, 0, 1); PG8_STAGE(PG8_SB(0, 0), b2, voffB); PG8_STAGE(PG8_SB(0, 1), b2 + hstepB, voffB); PG8_STAGE(PG8_SA(0, 0), a2, voffA);
.LBB0_1072:
	v_add_u32_e32 v166, s50, v149
	v_add_u32_e32 v182, s51, v149
	ds_read_b128 v[154:157], v166
	ds_read_b128 v[158:161], v166 offset:1024
	ds_read_b128 v[162:165], v166 offset:2048
	ds_read_b128 v[166:169], v166 offset:3072
	ds_read_b128 v[170:173], v182
	ds_read_b128 v[174:177], v182 offset:1024
	ds_read_b128 v[178:181], v182 offset:2048
	ds_read_b128 v[182:185], v182 offset:3072
	s_add_u32 s40, s36, 0xfffc0080
	s_addc_u32 s41, s37, -1
	s_and_b64 s[38:39], s[38:39], exec
	s_cselect_b32 s41, s17, s41
	s_cselect_b32 s40, s62, s40
	s_cselect_b32 s39, s13, s64
	s_cselect_b32 s38, s63, s23
	v_lshl_add_u64 v[220:221], s[36:37], 0, v[138:139]
	s_add_i32 m0, s35, 0xc000
	ds_read_b128 v[186:189], v151
	ds_read_b128 v[190:193], v151 offset:1024
	ds_read_b128 v[194:197], v151 offset:2048
	ds_read_b128 v[198:201], v151 offset:3072
	ds_read_b128 v[202:205], v151 offset:4096
	ds_read_b128 v[206:209], v151 offset:5120
	ds_read_b128 v[210:213], v151 offset:6144
	ds_read_b128 v[216:219], v151 offset:7168
	global_load_lds_dwordx4 v[220:221], off
	v_lshl_add_u64 v[220:221], s[36:37], 0, v[140:141]
	s_add_i32 m0, s35, 0xe000
	s_nop 0
	global_load_lds_dwordx4 v[220:221], off
	s_waitcnt vmcnt(8)
	s_waitcnt lgkmcnt(0)
	v_mfma_f32_16x16x32_bf16 v[124:127], v[154:157], v[186:189], v[124:127]
	v_mfma_f32_16x16x32_bf16 v[116:119], v[162:165], v[186:189], v[116:119]
	s_barrier
	s_setprio 1
	s_waitcnt lgkmcnt(0)
	v_mfma_f32_16x16x32_bf16 v[108:111], v[154:157], v[194:197], v[108:111]
	v_mfma_f32_16x16x32_bf16 v[100:103], v[162:165], v[194:197], v[100:103]
	v_mfma_f32_16x16x32_bf16 v[92:95], v[154:157], v[202:205], v[92:95]
	v_mfma_f32_16x16x32_bf16 v[84:87], v[162:165], v[202:205], v[84:87]
	v_mfma_f32_16x16x32_bf16 v[76:79], v[154:157], v[210:213], v[76:79]
	v_mfma_f32_16x16x32_bf16 v[68:71], v[162:165], v[210:213], v[68:71]
	v_mfma_f32_16x16x32_bf16 v[124:127], v[158:161], v[190:193], v[124:127]
	v_mfma_f32_16x16x32_bf16 v[116:119], v[166:169], v[190:193], v[116:119]
	v_mfma_f32_16x16x32_bf16 v[108:111], v[158:161], v[198:201], v[108:111]
	v_mfma_f32_16x16x32_bf16 v[100:103], v[166:169], v[198:201], v[100:103]
	v_mfma_f32_16x16x32_bf16 v[92:95], v[158:161], v[206:209], v[92:95]
	v_mfma_f32_16x16x32_bf16 v[84:87], v[166:169], v[206:209], v[84:87]
	v_mfma_f32_16x16x32_bf16 v[76:79], v[158:161], v[216:219], v[76:79]
	v_mfma_f32_16x16x32_bf16 v[68:71], v[166:169], v[216:219], v[68:71]
	s_setprio 0
	s_setprio 1
	v_mfma_f32_16x16x32_bf16 v[120:123], v[170:173], v[186:189], v[120:123]
	v_mfma_f32_16x16x32_bf16 v[112:115], v[178:181], v[186:189], v[112:115]
	v_mfma_f32_16x16x32_bf16 v[104:107], v[170:173], v[194:197], v[104:107]
	v_mfma_f32_16x16x32_bf16 v[96:99], v[178:181], v[194:197], v[96:99]
	v_mfma_f32_16x16x32_bf16 v[88:91], v[170:173], v[202:205], v[88:91]
	v_mfma_f32_16x16x32_bf16 v[80:83], v[178:181], v[202:205], v[80:83]
	v_mfma_f32_16x16x32_bf16 v[72:75], v[170:173], v[210:213], v[72:75]
	v_mfma_f32_16x16x32_bf16 v[64:67], v[178:181], v[210:213], v[64:67]
	v_mfma_f32_16x16x32_bf16 v[120:123], v[174:177], v[190:193], v[120:123]
	v_mfma_f32_16x16x32_bf16 v[112:115], v[182:185], v[190:193], v[112:115]
	v_mfma_f32_16x16x32_bf16 v[104:107], v[174:177], v[198:201], v[104:107]
	v_mfma_f32_16x16x32_bf16 v[96:99], v[182:185], v[198:201], v[96:99]
	v_mfma_f32_16x16x32_bf16 v[88:91], v[174:177], v[206:209], v[88:91]
	v_mfma_f32_16x16x32_bf16 v[80:83], v[182:185], v[206:209], v[80:83]
	v_mfma_f32_16x16x32_bf16 v[72:75], v[174:177], v[216:219], v[72:75]
	v_mfma_f32_16x16x32_bf16 v[64:67], v[182:185], v[216:219], v[64:67]
	s_setprio 0
	s_barrier
	s_add_i32 s66, s50, s15
	v_lshl_add_u64 v[220:221], s[38:39], 0, v[132:133]
	s_mov_b32 m0, s66
	ds_read_b128 v[186:189], v151 offset:16384
	ds_read_b128 v[190:193], v151 offset:17408
	ds_read_b128 v[194:197], v151 offset:18432
	ds_read_b128 v[198:201], v151 offset:19456
	ds_read_b128 v[202:205], v151 offset:20480
	ds_read_b128 v[206:209], v151 offset:21504
	ds_read_b128 v[210:213], v151 offset:22528
	ds_read_b128 v[216:219], v151 offset:23552
	global_load_lds_dwordx4 v[220:221], off
	s_add_i32 m0, s66, 0x2000
	s_add_u32 s66, s38, 0x580000
	v_lshl_add_u64 v[222:223], s[38:39], 0, v[128:129]
	s_addc_u32 s67, s39, 0
	s_add_i32 s68, s51, s15
	global_load_lds_dwordx4 v[222:223], off
	v_lshl_add_u64 v[224:225], s[66:67], 0, v[132:133]
	s_mov_b32 m0, s68
	v_lshl_add_u64 v[226:227], s[40:41], 0, v[130:131]
	global_load_lds_dwordx4 v[224:225], off
	v_lshl_add_u64 v[224:225], s[66:67], 0, v[128:129]
	s_add_i32 m0, s68, 0x2000
	s_nop 0
	global_load_lds_dwordx4 v[224:225], off
	v_lshl_add_u64 v[224:225], s[40:41], 0, v[134:135]
	s_mov_b32 m0, s35
	s_nop 0
	global_load_lds_dwordx4 v[224:225], off
	s_mov_b32 m0, s42
	s_nop 0
	global_load_lds_dwordx4 v[226:227], off
	s_waitcnt vmcnt(8)
	s_waitcnt lgkmcnt(0)
	v_mfma_f32_16x16x32_bf16 v[60:63], v[154:157], v[186:189], v[60:63]
	v_mfma_f32_16x16x32_bf16 v[52:55], v[162:165], v[186:189], v[52:55]
	s_barrier
; #define PG8_STAGE(bufoff, gbase, voff) do { _Pragma("unroll") for (int _i = 0; _i < 2; ++_i) \
;         __builtin_amdgcn_global_load_lds((const unsigned*)((const char*)(gbase) + (voff)[_i]), (PG8_LAS unsigned*)(lds + (bufoff) + ldsw + _i * 8192), 16, 0, 0); } while (0)
; #define PG8_LDA(dst, b, h) do { _Pragma("unroll") for (int m = 0; m < 4; ++m) _Pragma("unroll") for (int k = 0; k < 2; ++k) dst[m][k] = *(const PG8_LAS bf16x8*)(lds + PG8_SA(b, h) + aoff + m * 2048 + k * 1024); } while (0)
; #define PG8_LDB(dst, b, h) do { _Pragma("unroll") for (int n = 0; n < 2; ++n) _Pragma("unroll") for (int k = 0; k < 2; ++k) dst[n][k] = *(const PG8_LAS bf16x8*)(lds + PG8_SB(b, h) + boff + n * 2048 + k * 1024); } while (0)
; #define PG8_MMA(ai, bj, At, Bt) do { __builtin_amdgcn_s_setprio(1); _Pragma("unroll") for (int m = 0; m < 4; ++m) _Pragma("unroll") for (int n = 0; n < 2; ++n) _Pragma("unroll") for (int k = 0; k < 2; ++k) \
;         acc[ai][bj][m][n] = __builtin_amdgcn_mfma_f32_16x16x32_bf16(Bt[n][k], At[m][k], acc[ai][bj][m][n], 0, 0, 0); __builtin_amdgcn_s_setprio(0); } while (0)
; #define PG8_WAIT_V(n) asm volatile("s_waitcnt vmcnt(" #n ")" ::: "memory")
; #define PG8_WAIT_L(n) asm volatile("s_waitcnt lgkmcnt(" #n ")" ::: "memory")
; #define PG8_BAR __builtin_amdgcn_s_barrier()
; #define PG8_SCHED __builtin_amdgcn_sched_barrier(0)
; template <class Epi, class Sched, bool ALIGN_EPI = false, bool SP2 = false>
; __device__ __forceinline__ void gemm_phase(PG8_LAS unsigned char* lds, const Gemm g, const Sched& S, const Epi& E) {
;     ...
;             PG8_WAIT_V(8); PG8_WAIT_L(0); PG8_BAR; PG8_MMA(1, 0, At, B0); PG8_MMA(1, 1, At, B1); PG8_BAR; PG8_SCHED;
;             PG8_LDB(B0, 1, 0); PG8_LDB(B1, 1, 1); PG8_SCHED; PG8_LDA(At, 1, 0); PG8_STAGE(PG8_SA(0, 1), a2 + hstep, voffA);
;             PG8_WAIT_V(8); PG8_WAIT_L(0); PG8_BAR; PG8_MMA(0, 0, At, B0); PG8_MMA(0, 1, At, B1); PG8_BAR; PG8_SCHED;
	s_setprio 1
	s_waitcnt lgkmcnt(0)
	v_mfma_f32_16x16x32_bf16 v[44:47], v[154:157], v[194:197], v[44:47]
	v_mfma_f32_16x16x32_bf16 v[36:39], v[162:165], v[194:197], v[36:39]
	v_mfma_f32_16x16x32_bf16 v[28:31], v[154:157], v[202:205], v[28:31]
	v_mfma_f32_16x16x32_bf16 v[20:23], v[162:165], v[202:205], v[20:23]
	v_mfma_f32_16x16x32_bf16 v[12:15], v[154:157], v[210:213], v[12:15]
	v_mfma_f32_16x16x32_bf16 v[4:7], v[162:165], v[210:213], v[4:7]
	v_mfma_f32_16x16x32_bf16 v[60:63], v[158:161], v[190:193], v[60:63]
	v_mfma_f32_16x16x32_bf16 v[52:55], v[166:169], v[190:193], v[52:55]
	v_mfma_f32_16x16x32_bf16 v[44:47], v[158:161], v[198:201], v[44:47]
	v_mfma_f32_16x16x32_bf16 v[36:39], v[166:169], v[198:201], v[36:39]
	v_mfma_f32_16x16x32_bf16 v[28:31], v[158:161], v[206:209], v[28:31]
	v_mfma_f32_16x16x32_bf16 v[20:23], v[166:169], v[206:209], v[20:23]
	v_mfma_f32_16x16x32_bf16 v[12:15], v[158:161], v[216:219], v[12:15]
	v_mfma_f32_16x16x32_bf16 v[4:7], v[166:169], v[216:219], v[4:7]
	s_setprio 0
	s_setprio 1
	v_mfma_f32_16x16x32_bf16 v[56:59], v[170:173], v[186:189], v[56:59]
	v_mfma_f32_16x16x32_bf16 v[48:51], v[178:181], v[186:189], v[48:51]
	v_mfma_f32_16x16x32_bf16 v[40:43], v[170:173], v[194:197], v[40:43]
	v_mfma_f32_16x16x32_bf16 v[32:35], v[178:181], v[194:197], v[32:35]
	v_mfma_f32_16x16x32_bf16 v[24:27], v[170:173], v[202:205], v[24:27]
	v_mfma_f32_16x16x32_bf16 v[16:19], v[178:181], v[202:205], v[16:19]
	v_mfma_f32_16x16x32_bf16 v[8:11], v[170:173], v[210:213], v[8:11]
	v_mfma_f32_16x16x32_bf16 v[0:3], v[178:181], v[210:213], v[0:3]
	v_mfma_f32_16x16x32_bf16 v[56:59], v[174:177], v[190:193], v[56:59]
	v_mfma_f32_16x16x32_bf16 v[48:51], v[182:185], v[190:193], v[48:51]
	v_mfma_f32_16x16x32_bf16 v[40:43], v[174:177], v[198:201], v[40:43]
	v_mfma_f32_16x16x32_bf16 v[32:35], v[182:185], v[198:201], v[32:35]
	v_mfma_f32_16x16x32_bf16 v[24:27], v[174:177], v[206:209], v[24:27]
	v_mfma_f32_16x16x32_bf16 v[16:19], v[182:185], v[206:209], v[16:19]
	v_mfma_f32_16x16x32_bf16 v[8:11], v[174:177], v[216:219], v[8:11]
	v_mfma_f32_16x16x32_bf16 v[0:3], v[182:185], v[216:219], v[0:3]
	s_setprio 0
	s_barrier
	s_add_i32 s66, 0, 0x18000
	s_add_i32 s67, 0, 0x1c000
	v_add_u32_e32 v166, s66, v149
	v_add_u32_e32 v182, s67, v149
	ds_read_b128 v[154:157], v166
	ds_read_b128 v[158:161], v166 offset:1024
	ds_read_b128 v[162:165], v166 offset:2048
	ds_read_b128 v[166:169], v166 offset:3072
	ds_read_b128 v[170:173], v182
	ds_read_b128 v[174:177], v182 offset:1024
	ds_read_b128 v[178:181], v182 offset:2048
	ds_read_b128 v[182:185], v182 offset:3072
	s_add_u32 s40, s40, 0x40000
	s_addc_u32 s41, s41, 0
	s_mov_b32 m0, s43
	v_lshl_add_u64 v[228:229], s[40:41], 0, v[134:135]
	ds_read_b128 v[186:189], v151 offset:32768
	ds_read_b128 v[190:193], v151 offset:33792
	ds_read_b128 v[194:197], v151 offset:34816
	ds_read_b128 v[198:201], v151 offset:35840
	ds_read_b128 v[202:205], v151 offset:36864
	ds_read_b128 v[206:209], v151 offset:37888
	ds_read_b128 v[210:213], v151 offset:38912
	ds_read_b128 v[216:219], v151 offset:39936
	global_load_lds_dwordx4 v[228:229], off
	v_lshl_add_u64 v[228:229], s[40:41], 0, v[130:131]
	s_mov_b32 m0, s44
	s_nop 0
	global_load_lds_dwordx4 v[228:229], off
	s_waitcnt vmcnt(8)
	s_waitcnt lgkmcnt(0)
	v_mfma_f32_16x16x32_bf16 v[124:127], v[154:157], v[186:189], v[124:127]
	v_mfma_f32_16x16x32_bf16 v[116:119], v[162:165], v[186:189], v[116:119]
	s_barrier
	s_setprio 1
	s_waitcnt lgkmcnt(0)
	v_mfma_f32_16x16x32_bf16 v[108:111], v[154:157], v[194:197], v[108:111]
	v_mfma_f32_16x16x32_bf16 v[100:103], v[162:165], v[194:197], v[100:103]
	v_mfma_f32_16x16x32_bf16 v[92:95], v[154:157], v[202:205], v[92:95]
	v_mfma_f32_16x16x32_bf16 v[84:87], v[162:165], v[202:205], v[84:87]
	v_mfma_f32_16x16x32_bf16 v[76:79], v[154:157], v[210:213], v[76:79]
	v_mfma_f32_16x16x32_bf16 v[68:71], v[162:165], v[210:213], v[68:71]
	v_mfma_f32_16x16x32_bf16 v[124:127], v[158:161], v[190:193], v[124:127]
	v_mfma_f32_16x16x32_bf16 v[116:119], v[166:169], v[190:193], v[116:119]
	v_mfma_f32_16x16x32_bf16 v[108:111], v[158:161], v[198:201], v[108:111]
	v_mfma_f32_16x16x32_bf16 v[100:103], v[166:169], v[198:201], v[100:103]
	v_mfma_f32_16x16x32_bf16 v[92:95], v[158:161], v[206:209], v[92:95]
	v_mfma_f32_16x16x32_bf16 v[84:87], v[166:169], v[206:209], v[84:87]
	v_mfma_f32_16x16x32_bf16 v[76:79], v[158:161], v[216:219], v[76:79]
	v_mfma_f32_16x16x32_bf16 v[68:71], v[166:169], v[216:219], v[68:71]
	s_setprio 0
	s_setprio 1
	v_mfma_f32_16x16x32_bf16 v[120:123], v[170:173], v[186:189], v[120:123]
	v_mfma_f32_16x16x32_bf16 v[112:115], v[178:181], v[186:189], v[112:115]
	v_mfma_f32_16x16x32_bf16 v[104:107], v[170:173], v[194:197], v[104:107]
	v_mfma_f32_16x16x32_bf16 v[96:99], v[178:181], v[194:197], v[96:99]
	v_mfma_f32_16x16x32_bf16 v[88:91], v[170:173], v[202:205], v[88:91]
	v_mfma_f32_16x16x32_bf16 v[80:83], v[178:181], v[202:205], v[80:83]
	v_mfma_f32_16x16x32_bf16 v[72:75], v[170:173], v[210:213], v[72:75]
	v_mfma_f32_16x16x32_bf16 v[64:67], v[178:181], v[210:213], v[64:67]
	v_mfma_f32_16x16x32_bf16 v[120:123], v[174:177], v[190:193], v[120:123]
	v_mfma_f32_16x16x32_bf16 v[112:115], v[182:185], v[190:193], v[112:115]
	v_mfma_f32_16x16x32_bf16 v[104:107], v[174:177], v[198:201], v[104:107]
	v_mfma_f32_16x16x32_bf16 v[96:99], v[182:185], v[198:201], v[96:99]
	v_mfma_f32_16x16x32_bf16 v[88:91], v[174:177], v[206:209], v[88:91]
	v_mfma_f32_16x16x32_bf16 v[80:83], v[182:185], v[206:209], v[80:83]
	v_mfma_f32_16x16x32_bf16 v[72:75], v[174:177], v[216:219], v[72:75]
	v_mfma_f32_16x16x32_bf16 v[64:67], v[182:185], v[216:219], v[64:67]
	s_setprio 0
	s_barrier
; #define PG8_STAGE(bufoff, gbase, voff) do { _Pragma("unroll") for (int _i = 0; _i < 2; ++_i) \
;         __builtin_amdgcn_global_load_lds((const unsigned*)((const char*)(gbase) + (voff)[_i]), (PG8_LAS unsigned*)(lds + (bufoff) + ldsw + _i * 8192), 16, 0, 0); } while (0)
; #define PG8_LDA(dst, b, h) do { _Pragma("unroll") for (int m = 0; m < 4; ++m) _Pragma("unroll") for (int k = 0; k < 2; ++k) dst[m][k] = *(const PG8_LAS bf16x8*)(lds + PG8_SA(b, h) + aoff + m * 2048 + k * 1024); } while (0)
; #define PG8_MMA(ai, bj, At, Bt) do { __builtin_amdgcn_s_setprio(1); _Pragma("unroll") for (int m = 0; m < 4; ++m) _Pragma("unroll") for (int n = 0; n < 2; ++n) _Pragma("unroll") for (int k = 0; k < 2; ++k) \
;         acc[ai][bj][m][n] = __builtin_amdgcn_mfma_f32_16x16x32_bf16(Bt[n][k], At[m][k], acc[ai][bj][m][n], 0, 0, 0); __builtin_amdgcn_s_setprio(0); } while (0)
; #define PG8_WAIT_V(n) asm volatile("s_waitcnt vmcnt(" #n ")" ::: "memory")
; #define PG8_WAIT_L(n) asm volatile("s_waitcnt lgkmcnt(" #n ")" ::: "memory")
; #define PG8_BAR __builtin_amdgcn_s_barrier()
; #define PG8_SCHED __builtin_amdgcn_sched_barrier(0)
; template <class Epi, class Sched, bool ALIGN_EPI = false, bool SP2 = false>
; __device__ __forceinline__ void gemm_phase(PG8_LAS unsigned char* lds, const Gemm g, const Sched& S, const Epi& E) {
;     ...
;             PG8_LDA(At, 1, 1); PG8_STAGE(PG8_SB(1, 0), b3, voffB); PG8_STAGE(PG8_SB(1, 1), b3 + hstepB, voffB); PG8_STAGE(PG8_SA(1, 0), a3, voffA);
;             PG8_WAIT_V(8); PG8_WAIT_L(0); PG8_BAR; PG8_MMA(1, 0, At, B0); PG8_MMA(1, 1, At, B1); PG8_BAR; PG8_SCHED;
	s_add_i32 s40, s66, s15
	v_lshl_add_u64 v[220:221], v[220:221], 0, s[8:9]
	s_mov_b32 m0, s40
	ds_read_b128 v[186:189], v151 offset:49152
	ds_read_b128 v[190:193], v151 offset:50176
	ds_read_b128 v[194:197], v151 offset:51200
	ds_read_b128 v[198:201], v151 offset:52224
	ds_read_b128 v[202:205], v151 offset:53248
	ds_read_b128 v[206:209], v151 offset:54272
	ds_read_b128 v[210:213], v151 offset:55296
	ds_read_b128 v[216:219], v151 offset:56320
	global_load_lds_dwordx4 v[220:221], off
	s_add_i32 m0, s40, 0x2000
	s_add_u32 s38, s38, 0x580080
	v_lshl_add_u64 v[220:221], v[222:223], 0, s[8:9]
	s_addc_u32 s39, s39, 0
	s_add_i32 s40, s67, s15
	global_load_lds_dwordx4 v[220:221], off
	v_lshl_add_u64 v[220:221], s[38:39], 0, v[132:133]
	s_mov_b32 m0, s40
	s_nop 0
	global_load_lds_dwordx4 v[220:221], off
	v_lshl_add_u64 v[220:221], s[38:39], 0, v[128:129]
	s_add_i32 m0, s40, 0x2000
	s_nop 0
	global_load_lds_dwordx4 v[220:221], off
	v_lshl_add_u64 v[220:221], v[224:225], 0, s[8:9]
	s_mov_b32 m0, s46
	s_nop 0
	global_load_lds_dwordx4 v[220:221], off
	v_lshl_add_u64 v[220:221], v[226:227], 0, s[8:9]
	s_mov_b32 m0, s47
	s_nop 0
	global_load_lds_dwordx4 v[220:221], off
	s_waitcnt vmcnt(8)
	s_waitcnt lgkmcnt(0)
	v_mfma_f32_16x16x32_bf16 v[60:63], v[154:157], v[186:189], v[60:63]
	v_mfma_f32_16x16x32_bf16 v[52:55], v[162:165], v[186:189], v[52:55]
	s_barrier
	s_setprio 1
	s_waitcnt lgkmcnt(0)
	v_mfma_f32_16x16x32_bf16 v[44:47], v[154:157], v[194:197], v[44:47]
	v_mfma_f32_16x16x32_bf16 v[36:39], v[162:165], v[194:197], v[36:39]
	v_mfma_f32_16x16x32_bf16 v[28:31], v[154:157], v[202:205], v[28:31]
	v_mfma_f32_16x16x32_bf16 v[20:23], v[162:165], v[202:205], v[20:23]
	v_mfma_f32_16x16x32_bf16 v[12:15], v[154:157], v[210:213], v[12:15]
	v_mfma_f32_16x16x32_bf16 v[4:7], v[162:165], v[210:213], v[4:7]
	v_mfma_f32_16x16x32_bf16 v[60:63], v[158:161], v[190:193], v[60:63]
	v_mfma_f32_16x16x32_bf16 v[52:55], v[166:169], v[190:193], v[52:55]
	v_mfma_f32_16x16x32_bf16 v[44:47], v[158:161], v[198:201], v[44:47]
	v_mfma_f32_16x16x32_bf16 v[36:39], v[166:169], v[198:201], v[36:39]
	v_mfma_f32_16x16x32_bf16 v[28:31], v[158:161], v[206:209], v[28:31]
	v_mfma_f32_16x16x32_bf16 v[20:23], v[166:169], v[206:209], v[20:23]
	v_mfma_f32_16x16x32_bf16 v[12:15], v[158:161], v[216:219], v[12:15]
	v_mfma_f32_16x16x32_bf16 v[4:7], v[166:169], v[216:219], v[4:7]
	s_setprio 0
	s_setprio 1
	v_mfma_f32_16x16x32_bf16 v[56:59], v[170:173], v[186:189], v[56:59]
	v_mfma_f32_16x16x32_bf16 v[48:51], v[178:181], v[186:189], v[48:51]
	v_mfma_f32_16x16x32_bf16 v[40:43], v[170:173], v[194:197], v[40:43]
	v_mfma_f32_16x16x32_bf16 v[32:35], v[178:181], v[194:197], v[32:35]
	v_mfma_f32_16x16x32_bf16 v[24:27], v[170:173], v[202:205], v[24:27]
	v_mfma_f32_16x16x32_bf16 v[16:19], v[178:181], v[202:205], v[16:19]
	v_mfma_f32_16x16x32_bf16 v[8:11], v[170:173], v[210:213], v[8:11]
	v_mfma_f32_16x16x32_bf16 v[0:3], v[178:181], v[210:213], v[0:3]
	v_mfma_f32_16x16x32_bf16 v[56:59], v[174:177], v[190:193], v[56:59]
	v_mfma_f32_16x16x32_bf16 v[48:51], v[182:185], v[190:193], v[48:51]
	v_mfma_f32_16x16x32_bf16 v[40:43], v[174:177], v[198:201], v[40:43]
	v_mfma_f32_16x16x32_bf16 v[32:35], v[182:185], v[198:201], v[32:35]
	v_mfma_f32_16x16x32_bf16 v[24:27], v[174:177], v[206:209], v[24:27]
	v_mfma_f32_16x16x32_bf16 v[16:19], v[182:185], v[206:209], v[16:19]
	v_mfma_f32_16x16x32_bf16 v[8:11], v[174:177], v[216:219], v[8:11]
	v_mfma_f32_16x16x32_bf16 v[0:3], v[182:185], v[216:219], v[0:3]
	s_setprio 0
	s_barrier
	s_add_i32 s65, s65, 2
	s_add_u32 s36, s36, 0x100
	s_addc_u32 s37, s37, 0
	s_add_u32 s23, s23, 0x100
	s_addc_u32 s64, s64, 0
	s_cmp_gt_u32 s65, 13
	s_cbranch_scc1 .LBB0_1075

; #define PG8_STAGE(bufoff, gbase, voff) do { _Pragma("unroll") for (int _i = 0; _i < 2; ++_i) \
;         __builtin_amdgcn_global_load_lds((const unsigned*)((const char*)(gbase) + (voff)[_i]), (PG8_LAS unsigned*)(lds + (bufoff) + ldsw + _i * 8192), 16, 0, 0); } while (0)
; #define PG8_LDA(dst, b, h) do { _Pragma("unroll") for (int m = 0; m < 4; ++m) _Pragma("unroll") for (int k = 0; k < 2; ++k) dst[m][k] = *(const PG8_LAS bf16x8*)(lds + PG8_SA(b, h) + aoff + m * 2048 + k * 1024); } while (0)
; #define PG8_LDB(dst, b, h) do { _Pragma("unroll") for (int n = 0; n < 2; ++n) _Pragma("unroll") for (int k = 0; k < 2; ++k) dst[n][k] = *(const PG8_LAS bf16x8*)(lds + PG8_SB(b, h) + boff + n * 2048 + k * 1024); } while (0)
; #define PG8_MMA(ai, bj, At, Bt) do { __builtin_amdgcn_s_setprio(1); _Pragma("unroll") for (int m = 0; m < 4; ++m) _Pragma("unroll") for (int n = 0; n < 2; ++n) _Pragma("unroll") for (int k = 0; k < 2; ++k) \
;         acc[ai][bj][m][n] = __builtin_amdgcn_mfma_f32_16x16x32_bf16(Bt[n][k], At[m][k], acc[ai][bj][m][n], 0, 0, 0); __builtin_amdgcn_s_setprio(0); } while (0)
; #define PG8_WAIT_V(n) asm volatile("s_waitcnt vmcnt(" #n ")" ::: "memory")
; #define PG8_WAIT_L(n) asm volatile("s_waitcnt lgkmcnt(" #n ")" ::: "memory")
; #define PG8_BAR __builtin_amdgcn_s_barrier()
; template <class Epi, class Sched, bool ALIGN_EPI = false, bool SP2 = false>
; __device__ __forceinline__ void gemm_phase(PG8_LAS unsigned char* lds, const Gemm g, const Sched& S, const Epi& E) {
;     ...
;         for (int t = 0; t < nt; t += 2) {
;             const bool last = (t == nt - 2);
;             const char* a1 = cA + (size_t)(t + 1) * kstep;
;             const char* a2 = last ? nA : cA + (size_t)(t + 2) * kstep; const char* b2 = last ? nB : cB + (size_t)(t + 2) * kstep;
;             const char* a3 = a2 + kstep; const char* b3 = b2 + kstep;
;             if (last && has_next) S.a_ready(nxt);
;             if (last) E.pre(lds, cur, wid, tid);
;             if constexpr (SP2) {
;             PG8_LDB(B0, 0, 0); PG8_LDB(B1, 0, 1); PG8_SCHED; PG8_LDA(At, 0, 0); PG8_STAGE(PG8_SA(1, 1), a1 + hstep, voffA);
;             PG8_WAIT_V(8); PG8_WAIT_L(0); PG8_BAR; PG8_MMA(0, 0, At, B0); PG8_MMA(0, 1, At, B1); PG8_BAR; PG8_SCHED;
;             PG8_LDA(At, 0, 1); PG8_STAGE(PG8_SB(0, 0), b2, voffB); PG8_STAGE(PG8_SB(0, 1), b2 + hstepB, voffB); PG8_STAGE(PG8_SA(0, 0), a2, voffA);
.LBB0_1151:
	ds_read_b128 v[144:147], v163
	ds_read_b128 v[148:151], v163 offset:1024
	ds_read_b128 v[152:155], v163 offset:2048
	ds_read_b128 v[156:159], v163 offset:3072
	ds_read_b128 v[168:171], v164
	ds_read_b128 v[172:175], v164 offset:1024
	ds_read_b128 v[176:179], v164 offset:2048
	ds_read_b128 v[180:183], v164 offset:3072
	s_add_u32 s38, s36, 0x100
	s_addc_u32 s39, s37, 0
	s_cmp_eq_u32 s67, 40
	s_cselect_b32 s43, s1, s39
	s_cselect_b32 s42, s0, s38
	s_cselect_b32 s41, s23, s66
	s_cselect_b32 s40, s22, s65
	v_lshl_add_u64 v[212:213], s[36:37], 0, v[134:135]
	s_add_i32 m0, s30, 0xc000
	ds_read_b128 v[184:187], v165
	ds_read_b128 v[188:191], v165 offset:1024
	ds_read_b128 v[192:195], v165 offset:2048
	ds_read_b128 v[196:199], v165 offset:3072
	ds_read_b128 v[200:203], v165 offset:4096
	ds_read_b128 v[204:207], v165 offset:5120
	ds_read_b128 v[208:211], v165 offset:6144
	ds_read_b128 v[216:219], v165 offset:7168
	global_load_lds_dwordx4 v[212:213], off
	v_lshl_add_u64 v[212:213], s[36:37], 0, v[136:137]
	s_add_i32 m0, s30, 0xe000
	s_nop 0
	global_load_lds_dwordx4 v[212:213], off
	s_waitcnt vmcnt(8)
	s_waitcnt lgkmcnt(0)
	v_mfma_f32_16x16x32_bf16 v[124:127], v[144:147], v[184:187], v[124:127]
	v_mfma_f32_16x16x32_bf16 v[120:123], v[152:155], v[184:187], v[120:123]
	s_barrier
	s_setprio 1
	s_waitcnt lgkmcnt(0)
	v_mfma_f32_16x16x32_bf16 v[108:111], v[144:147], v[192:195], v[108:111]
	v_mfma_f32_16x16x32_bf16 v[104:107], v[152:155], v[192:195], v[104:107]
	v_mfma_f32_16x16x32_bf16 v[92:95], v[144:147], v[200:203], v[92:95]
	v_mfma_f32_16x16x32_bf16 v[88:91], v[152:155], v[200:203], v[88:91]
	v_mfma_f32_16x16x32_bf16 v[76:79], v[144:147], v[208:211], v[76:79]
	v_mfma_f32_16x16x32_bf16 v[72:75], v[152:155], v[208:211], v[72:75]
	v_mfma_f32_16x16x32_bf16 v[124:127], v[148:151], v[188:191], v[124:127]
	v_mfma_f32_16x16x32_bf16 v[120:123], v[156:159], v[188:191], v[120:123]
	v_mfma_f32_16x16x32_bf16 v[108:111], v[148:151], v[196:199], v[108:111]
	v_mfma_f32_16x16x32_bf16 v[104:107], v[156:159], v[196:199], v[104:107]
	v_mfma_f32_16x16x32_bf16 v[92:95], v[148:151], v[204:207], v[92:95]
	v_mfma_f32_16x16x32_bf16 v[88:91], v[156:159], v[204:207], v[88:91]
	v_mfma_f32_16x16x32_bf16 v[76:79], v[148:151], v[216:219], v[76:79]
	v_mfma_f32_16x16x32_bf16 v[72:75], v[156:159], v[216:219], v[72:75]
	s_setprio 0
	s_setprio 1
	v_mfma_f32_16x16x32_bf16 v[116:119], v[168:171], v[184:187], v[116:119]
	v_mfma_f32_16x16x32_bf16 v[112:115], v[176:179], v[184:187], v[112:115]
	v_mfma_f32_16x16x32_bf16 v[100:103], v[168:171], v[192:195], v[100:103]
	v_mfma_f32_16x16x32_bf16 v[96:99], v[176:179], v[192:195], v[96:99]
	v_mfma_f32_16x16x32_bf16 v[84:87], v[168:171], v[200:203], v[84:87]
	v_mfma_f32_16x16x32_bf16 v[80:83], v[176:179], v[200:203], v[80:83]
	v_mfma_f32_16x16x32_bf16 v[68:71], v[168:171], v[208:211], v[68:71]
	v_mfma_f32_16x16x32_bf16 v[64:67], v[176:179], v[208:211], v[64:67]
	v_mfma_f32_16x16x32_bf16 v[116:119], v[172:175], v[188:191], v[116:119]
	v_mfma_f32_16x16x32_bf16 v[112:115], v[180:183], v[188:191], v[112:115]
	v_mfma_f32_16x16x32_bf16 v[100:103], v[172:175], v[196:199], v[100:103]
	v_mfma_f32_16x16x32_bf16 v[96:99], v[180:183], v[196:199], v[96:99]
	v_mfma_f32_16x16x32_bf16 v[84:87], v[172:175], v[204:207], v[84:87]
	v_mfma_f32_16x16x32_bf16 v[80:83], v[180:183], v[204:207], v[80:83]
	v_mfma_f32_16x16x32_bf16 v[68:71], v[172:175], v[216:219], v[68:71]
	v_mfma_f32_16x16x32_bf16 v[64:67], v[180:183], v[216:219], v[64:67]
	s_setprio 0
	s_barrier
	s_add_i32 s36, s50, s15
	v_lshl_add_u64 v[212:213], s[40:41], 0, v[128:129]
	s_mov_b32 m0, s36
	ds_read_b128 v[184:187], v165 offset:16384
	ds_read_b128 v[188:191], v165 offset:17408
	ds_read_b128 v[192:195], v165 offset:18432
	ds_read_b128 v[196:199], v165 offset:19456
	ds_read_b128 v[200:203], v165 offset:20480
	ds_read_b128 v[204:207], v165 offset:21504
	ds_read_b128 v[208:211], v165 offset:22528
	ds_read_b128 v[216:219], v165 offset:23552
	global_load_lds_dwordx4 v[212:213], off
	s_add_i32 m0, s36, 0x2000
	s_add_u32 s36, s40, 0xb0000
	v_lshl_add_u64 v[220:221], s[40:41], 0, v[130:131]
	s_addc_u32 s37, s41, 0
	s_add_i32 s68, s51, s15
	global_load_lds_dwordx4 v[220:221], off
	v_lshl_add_u64 v[222:223], s[36:37], 0, v[128:129]
	s_mov_b32 m0, s68
	v_lshl_add_u64 v[224:225], s[42:43], 0, v[130:131]
	global_load_lds_dwordx4 v[222:223], off
	v_lshl_add_u64 v[222:223], s[36:37], 0, v[130:131]
	s_add_i32 m0, s68, 0x2000
	s_nop 0
	global_load_lds_dwordx4 v[222:223], off
	v_lshl_add_u64 v[222:223], s[42:43], 0, v[128:129]
	s_mov_b32 m0, s30
	s_nop 0
	global_load_lds_dwordx4 v[222:223], off
	s_mov_b32 m0, s31
	s_nop 0
	global_load_lds_dwordx4 v[224:225], off
	s_waitcnt vmcnt(8)
	s_waitcnt lgkmcnt(0)
	v_mfma_f32_16x16x32_bf16 v[60:63], v[144:147], v[184:187], v[60:63]
	v_mfma_f32_16x16x32_bf16 v[56:59], v[152:155], v[184:187], v[56:59]
	s_barrier
; #define PG8_STAGE(bufoff, gbase, voff) do { _Pragma("unroll") for (int _i = 0; _i < 2; ++_i) \
;         __builtin_amdgcn_global_load_lds((const unsigned*)((const char*)(gbase) + (voff)[_i]), (PG8_LAS unsigned*)(lds + (bufoff) + ldsw + _i * 8192), 16, 0, 0); } while (0)
; #define PG8_LDA(dst, b, h) do { _Pragma("unroll") for (int m = 0; m < 4; ++m) _Pragma("unroll") for (int k = 0; k < 2; ++k) dst[m][k] = *(const PG8_LAS bf16x8*)(lds + PG8_SA(b, h) + aoff + m * 2048 + k * 1024); } while (0)
; #define PG8_LDB(dst, b, h) do { _Pragma("unroll") for (int n = 0; n < 2; ++n) _Pragma("unroll") for (int k = 0; k < 2; ++k) dst[n][k] = *(const PG8_LAS bf16x8*)(lds + PG8_SB(b, h) + boff + n * 2048 + k * 1024); } while (0)
; #define PG8_MMA(ai, bj, At, Bt) do { __builtin_amdgcn_s_setprio(1); _Pragma("unroll") for (int m = 0; m < 4; ++m) _Pragma("unroll") for (int n = 0; n < 2; ++n) _Pragma("unroll") for (int k = 0; k < 2; ++k) \
;         acc[ai][bj][m][n] = __builtin_amdgcn_mfma_f32_16x16x32_bf16(Bt[n][k], At[m][k], acc[ai][bj][m][n], 0, 0, 0); __builtin_amdgcn_s_setprio(0); } while (0)
; #define PG8_WAIT_V(n) asm volatile("s_waitcnt vmcnt(" #n ")" ::: "memory")
; #define PG8_WAIT_L(n) asm volatile("s_waitcnt lgkmcnt(" #n ")" ::: "memory")
; #define PG8_BAR __builtin_amdgcn_s_barrier()
; #define PG8_SCHED __builtin_amdgcn_sched_barrier(0)
; template <class Epi, class Sched, bool ALIGN_EPI = false, bool SP2 = false>
; __device__ __forceinline__ void gemm_phase(PG8_LAS unsigned char* lds, const Gemm g, const Sched& S, const Epi& E) {
;     ...
;             PG8_WAIT_V(8); PG8_WAIT_L(0); PG8_BAR; PG8_MMA(1, 0, At, B0); PG8_MMA(1, 1, At, B1); PG8_BAR; PG8_SCHED;
;             PG8_LDB(B0, 1, 0); PG8_LDB(B1, 1, 1); PG8_SCHED; PG8_LDA(At, 1, 0); PG8_STAGE(PG8_SA(0, 1), a2 + hstep, voffA);
;             PG8_WAIT_V(8); PG8_WAIT_L(0); PG8_BAR; PG8_MMA(0, 0, At, B0); PG8_MMA(0, 1, At, B1); PG8_BAR; PG8_SCHED;
	s_setprio 1
	s_waitcnt lgkmcnt(0)
	v_mfma_f32_16x16x32_bf16 v[44:47], v[144:147], v[192:195], v[44:47]
	v_mfma_f32_16x16x32_bf16 v[40:43], v[152:155], v[192:195], v[40:43]
	v_mfma_f32_16x16x32_bf16 v[28:31], v[144:147], v[200:203], v[28:31]
	v_mfma_f32_16x16x32_bf16 v[24:27], v[152:155], v[200:203], v[24:27]
	v_mfma_f32_16x16x32_bf16 v[12:15], v[144:147], v[208:211], v[12:15]
	v_mfma_f32_16x16x32_bf16 v[8:11], v[152:155], v[208:211], v[8:11]
	v_mfma_f32_16x16x32_bf16 v[60:63], v[148:151], v[188:191], v[60:63]
	v_mfma_f32_16x16x32_bf16 v[56:59], v[156:159], v[188:191], v[56:59]
	v_mfma_f32_16x16x32_bf16 v[44:47], v[148:151], v[196:199], v[44:47]
	v_mfma_f32_16x16x32_bf16 v[40:43], v[156:159], v[196:199], v[40:43]
	v_mfma_f32_16x16x32_bf16 v[28:31], v[148:151], v[204:207], v[28:31]
	v_mfma_f32_16x16x32_bf16 v[24:27], v[156:159], v[204:207], v[24:27]
	v_mfma_f32_16x16x32_bf16 v[12:15], v[148:151], v[216:219], v[12:15]
	v_mfma_f32_16x16x32_bf16 v[8:11], v[156:159], v[216:219], v[8:11]
	s_setprio 0
	s_setprio 1
	v_mfma_f32_16x16x32_bf16 v[52:55], v[168:171], v[184:187], v[52:55]
	v_mfma_f32_16x16x32_bf16 v[48:51], v[176:179], v[184:187], v[48:51]
	v_mfma_f32_16x16x32_bf16 v[36:39], v[168:171], v[192:195], v[36:39]
	v_mfma_f32_16x16x32_bf16 v[32:35], v[176:179], v[192:195], v[32:35]
	v_mfma_f32_16x16x32_bf16 v[20:23], v[168:171], v[200:203], v[20:23]
	v_mfma_f32_16x16x32_bf16 v[16:19], v[176:179], v[200:203], v[16:19]
	v_mfma_f32_16x16x32_bf16 v[4:7], v[168:171], v[208:211], v[4:7]
	v_mfma_f32_16x16x32_bf16 v[0:3], v[176:179], v[208:211], v[0:3]
	v_mfma_f32_16x16x32_bf16 v[52:55], v[172:175], v[188:191], v[52:55]
	v_mfma_f32_16x16x32_bf16 v[48:51], v[180:183], v[188:191], v[48:51]
	v_mfma_f32_16x16x32_bf16 v[36:39], v[172:175], v[196:199], v[36:39]
	v_mfma_f32_16x16x32_bf16 v[32:35], v[180:183], v[196:199], v[32:35]
	v_mfma_f32_16x16x32_bf16 v[20:23], v[172:175], v[204:207], v[20:23]
	v_mfma_f32_16x16x32_bf16 v[16:19], v[180:183], v[204:207], v[16:19]
	v_mfma_f32_16x16x32_bf16 v[4:7], v[172:175], v[216:219], v[4:7]
	v_mfma_f32_16x16x32_bf16 v[0:3], v[180:183], v[216:219], v[0:3]
	s_setprio 0
	s_barrier
	s_add_i32 s68, 0, 0x18000
	v_add_u32_e32 v143, s68, v161
	s_add_i32 s69, 0, 0x1c000
	ds_read_b128 v[144:147], v143
	ds_read_b128 v[148:151], v143 offset:1024
	ds_read_b128 v[152:155], v143 offset:2048
	ds_read_b128 v[156:159], v143 offset:3072
	v_add_u32_e32 v143, s69, v161
	ds_read_b128 v[168:171], v143
	ds_read_b128 v[172:175], v143 offset:1024
	ds_read_b128 v[176:179], v143 offset:2048
	ds_read_b128 v[180:183], v143 offset:3072
	s_add_u32 s36, s42, 0xb0000
	s_addc_u32 s37, s43, 0
	s_mov_b32 m0, s35
	v_lshl_add_u64 v[226:227], s[36:37], 0, v[128:129]
	ds_read_b128 v[184:187], v165 offset:32768
	ds_read_b128 v[188:191], v165 offset:33792
	ds_read_b128 v[192:195], v165 offset:34816
	ds_read_b128 v[196:199], v165 offset:35840
	ds_read_b128 v[200:203], v165 offset:36864
	ds_read_b128 v[204:207], v165 offset:37888
	ds_read_b128 v[208:211], v165 offset:38912
	ds_read_b128 v[216:219], v165 offset:39936
	global_load_lds_dwordx4 v[226:227], off
	v_lshl_add_u64 v[226:227], s[36:37], 0, v[130:131]
	s_mov_b32 m0, s44
	s_nop 0
	global_load_lds_dwordx4 v[226:227], off
	s_waitcnt vmcnt(8)
	s_waitcnt lgkmcnt(0)
	v_mfma_f32_16x16x32_bf16 v[124:127], v[144:147], v[184:187], v[124:127]
	v_mfma_f32_16x16x32_bf16 v[120:123], v[152:155], v[184:187], v[120:123]
	s_barrier
	s_setprio 1
	s_waitcnt lgkmcnt(0)
	v_mfma_f32_16x16x32_bf16 v[108:111], v[144:147], v[192:195], v[108:111]
	v_mfma_f32_16x16x32_bf16 v[104:107], v[152:155], v[192:195], v[104:107]
	v_mfma_f32_16x16x32_bf16 v[92:95], v[144:147], v[200:203], v[92:95]
	v_mfma_f32_16x16x32_bf16 v[88:91], v[152:155], v[200:203], v[88:91]
	v_mfma_f32_16x16x32_bf16 v[76:79], v[144:147], v[208:211], v[76:79]
	v_mfma_f32_16x16x32_bf16 v[72:75], v[152:155], v[208:211], v[72:75]
	v_mfma_f32_16x16x32_bf16 v[124:127], v[148:151], v[188:191], v[124:127]
	v_mfma_f32_16x16x32_bf16 v[120:123], v[156:159], v[188:191], v[120:123]
	v_mfma_f32_16x16x32_bf16 v[108:111], v[148:151], v[196:199], v[108:111]
	v_mfma_f32_16x16x32_bf16 v[104:107], v[156:159], v[196:199], v[104:107]
	v_mfma_f32_16x16x32_bf16 v[92:95], v[148:151], v[204:207], v[92:95]
	v_mfma_f32_16x16x32_bf16 v[88:91], v[156:159], v[204:207], v[88:91]
	v_mfma_f32_16x16x32_bf16 v[76:79], v[148:151], v[216:219], v[76:79]
	v_mfma_f32_16x16x32_bf16 v[72:75], v[156:159], v[216:219], v[72:75]
	s_setprio 0
	s_setprio 1
	v_mfma_f32_16x16x32_bf16 v[116:119], v[168:171], v[184:187], v[116:119]
	v_mfma_f32_16x16x32_bf16 v[112:115], v[176:179], v[184:187], v[112:115]
	v_mfma_f32_16x16x32_bf16 v[100:103], v[168:171], v[192:195], v[100:103]
	v_mfma_f32_16x16x32_bf16 v[96:99], v[176:179], v[192:195], v[96:99]
	v_mfma_f32_16x16x32_bf16 v[84:87], v[168:171], v[200:203], v[84:87]
	v_mfma_f32_16x16x32_bf16 v[80:83], v[176:179], v[200:203], v[80:83]
	v_mfma_f32_16x16x32_bf16 v[68:71], v[168:171], v[208:211], v[68:71]
	v_mfma_f32_16x16x32_bf16 v[64:67], v[176:179], v[208:211], v[64:67]
	v_mfma_f32_16x16x32_bf16 v[116:119], v[172:175], v[188:191], v[116:119]
	v_mfma_f32_16x16x32_bf16 v[112:115], v[180:183], v[188:191], v[112:115]
	v_mfma_f32_16x16x32_bf16 v[100:103], v[172:175], v[196:199], v[100:103]
	v_mfma_f32_16x16x32_bf16 v[96:99], v[180:183], v[196:199], v[96:99]
	v_mfma_f32_16x16x32_bf16 v[84:87], v[172:175], v[204:207], v[84:87]
	v_mfma_f32_16x16x32_bf16 v[80:83], v[180:183], v[204:207], v[80:83]
	v_mfma_f32_16x16x32_bf16 v[68:71], v[172:175], v[216:219], v[68:71]
	v_mfma_f32_16x16x32_bf16 v[64:67], v[180:183], v[216:219], v[64:67]
	s_setprio 0
	s_barrier
; #define PG8_STAGE(bufoff, gbase, voff) do { _Pragma("unroll") for (int _i = 0; _i < 2; ++_i) \
;         __builtin_amdgcn_global_load_lds((const unsigned*)((const char*)(gbase) + (voff)[_i]), (PG8_LAS unsigned*)(lds + (bufoff) + ldsw + _i * 8192), 16, 0, 0); } while (0)
; #define PG8_LDA(dst, b, h) do { _Pragma("unroll") for (int m = 0; m < 4; ++m) _Pragma("unroll") for (int k = 0; k < 2; ++k) dst[m][k] = *(const PG8_LAS bf16x8*)(lds + PG8_SA(b, h) + aoff + m * 2048 + k * 1024); } while (0)
; #define PG8_MMA(ai, bj, At, Bt) do { __builtin_amdgcn_s_setprio(1); _Pragma("unroll") for (int m = 0; m < 4; ++m) _Pragma("unroll") for (int n = 0; n < 2; ++n) _Pragma("unroll") for (int k = 0; k < 2; ++k) \
;         acc[ai][bj][m][n] = __builtin_amdgcn_mfma_f32_16x16x32_bf16(Bt[n][k], At[m][k], acc[ai][bj][m][n], 0, 0, 0); __builtin_amdgcn_s_setprio(0); } while (0)
; #define PG8_WAIT_V(n) asm volatile("s_waitcnt vmcnt(" #n ")" ::: "memory")
; #define PG8_WAIT_L(n) asm volatile("s_waitcnt lgkmcnt(" #n ")" ::: "memory")
; #define PG8_BAR __builtin_amdgcn_s_barrier()
; #define PG8_SCHED __builtin_amdgcn_sched_barrier(0)
; template <class Epi, class Sched, bool ALIGN_EPI = false, bool SP2 = false>
; __device__ __forceinline__ void gemm_phase(PG8_LAS unsigned char* lds, const Gemm g, const Sched& S, const Epi& E) {
;     ...
;             PG8_LDA(At, 1, 1); PG8_STAGE(PG8_SB(1, 0), b3, voffB); PG8_STAGE(PG8_SB(1, 1), b3 + hstepB, voffB); PG8_STAGE(PG8_SA(1, 0), a3, voffA);
;             PG8_WAIT_V(8); PG8_WAIT_L(0); PG8_BAR; PG8_MMA(1, 0, At, B0); PG8_MMA(1, 1, At, B1); PG8_BAR; PG8_SCHED;
;     ...
;         if constexpr (ALIGN_EPI) { if (wr == 0) PG8_BAR; }
	s_add_i32 s36, s68, s15
	v_lshl_add_u64 v[212:213], v[212:213], 0, s[18:19]
	s_mov_b32 m0, s36
	ds_read_b128 v[184:187], v165 offset:49152
	ds_read_b128 v[188:191], v165 offset:50176
	ds_read_b128 v[192:195], v165 offset:51200
	ds_read_b128 v[196:199], v165 offset:52224
	ds_read_b128 v[200:203], v165 offset:53248
	ds_read_b128 v[204:207], v165 offset:54272
	ds_read_b128 v[208:211], v165 offset:55296
	ds_read_b128 v[216:219], v165 offset:56320
	global_load_lds_dwordx4 v[212:213], off
	s_add_i32 m0, s36, 0x2000
	s_add_u32 s36, s40, 0xb0080
	v_lshl_add_u64 v[212:213], v[220:221], 0, s[18:19]
	s_addc_u32 s37, s41, 0
	s_add_i32 s40, s69, s15
	global_load_lds_dwordx4 v[212:213], off
	v_lshl_add_u64 v[212:213], s[36:37], 0, v[128:129]
	s_mov_b32 m0, s40
	s_nop 0
	global_load_lds_dwordx4 v[212:213], off
	v_lshl_add_u64 v[212:213], s[36:37], 0, v[130:131]
	s_add_i32 m0, s40, 0x2000
	s_nop 0
	global_load_lds_dwordx4 v[212:213], off
	v_lshl_add_u64 v[212:213], v[222:223], 0, s[18:19]
	s_mov_b32 m0, s45
	s_nop 0
	global_load_lds_dwordx4 v[212:213], off
	v_lshl_add_u64 v[212:213], v[224:225], 0, s[18:19]
	s_mov_b32 m0, s46
	s_nop 0
	global_load_lds_dwordx4 v[212:213], off
	s_waitcnt vmcnt(8)
	s_waitcnt lgkmcnt(0)
	v_mfma_f32_16x16x32_bf16 v[60:63], v[144:147], v[184:187], v[60:63]
	v_mfma_f32_16x16x32_bf16 v[56:59], v[152:155], v[184:187], v[56:59]
	s_barrier
	s_setprio 1
	s_waitcnt lgkmcnt(0)
	v_mfma_f32_16x16x32_bf16 v[44:47], v[144:147], v[192:195], v[44:47]
	v_mfma_f32_16x16x32_bf16 v[40:43], v[152:155], v[192:195], v[40:43]
	v_mfma_f32_16x16x32_bf16 v[28:31], v[144:147], v[200:203], v[28:31]
	v_mfma_f32_16x16x32_bf16 v[24:27], v[152:155], v[200:203], v[24:27]
	v_mfma_f32_16x16x32_bf16 v[12:15], v[144:147], v[208:211], v[12:15]
	v_mfma_f32_16x16x32_bf16 v[8:11], v[152:155], v[208:211], v[8:11]
	v_mfma_f32_16x16x32_bf16 v[60:63], v[148:151], v[188:191], v[60:63]
	v_mfma_f32_16x16x32_bf16 v[56:59], v[156:159], v[188:191], v[56:59]
	v_mfma_f32_16x16x32_bf16 v[44:47], v[148:151], v[196:199], v[44:47]
	v_mfma_f32_16x16x32_bf16 v[40:43], v[156:159], v[196:199], v[40:43]
	v_mfma_f32_16x16x32_bf16 v[28:31], v[148:151], v[204:207], v[28:31]
	v_mfma_f32_16x16x32_bf16 v[24:27], v[156:159], v[204:207], v[24:27]
	v_mfma_f32_16x16x32_bf16 v[12:15], v[148:151], v[216:219], v[12:15]
	v_mfma_f32_16x16x32_bf16 v[8:11], v[156:159], v[216:219], v[8:11]
	s_setprio 0
	s_setprio 1
	v_mfma_f32_16x16x32_bf16 v[52:55], v[168:171], v[184:187], v[52:55]
	v_mfma_f32_16x16x32_bf16 v[48:51], v[176:179], v[184:187], v[48:51]
	v_mfma_f32_16x16x32_bf16 v[36:39], v[168:171], v[192:195], v[36:39]
	v_mfma_f32_16x16x32_bf16 v[32:35], v[176:179], v[192:195], v[32:35]
	v_mfma_f32_16x16x32_bf16 v[20:23], v[168:171], v[200:203], v[20:23]
	v_mfma_f32_16x16x32_bf16 v[16:19], v[176:179], v[200:203], v[16:19]
	v_mfma_f32_16x16x32_bf16 v[4:7], v[168:171], v[208:211], v[4:7]
	v_mfma_f32_16x16x32_bf16 v[0:3], v[176:179], v[208:211], v[0:3]
	v_mfma_f32_16x16x32_bf16 v[52:55], v[172:175], v[188:191], v[52:55]
	v_mfma_f32_16x16x32_bf16 v[48:51], v[180:183], v[188:191], v[48:51]
	v_mfma_f32_16x16x32_bf16 v[36:39], v[172:175], v[196:199], v[36:39]
	v_mfma_f32_16x16x32_bf16 v[32:35], v[180:183], v[196:199], v[32:35]
	v_mfma_f32_16x16x32_bf16 v[20:23], v[172:175], v[204:207], v[20:23]
	v_mfma_f32_16x16x32_bf16 v[16:19], v[180:183], v[204:207], v[16:19]
	v_mfma_f32_16x16x32_bf16 v[4:7], v[172:175], v[216:219], v[4:7]
	v_mfma_f32_16x16x32_bf16 v[0:3], v[180:183], v[216:219], v[0:3]
	s_setprio 0
	s_barrier
	s_add_i32 s67, s67, 2
	s_add_u32 s65, s65, 0x100
	s_addc_u32 s66, s66, 0
	s_cmp_gt_u32 s67, 41
	s_mov_b64 s[36:37], s[38:39]
	s_cbranch_scc0 .LBB0_1151
	s_and_b64 vcc, exec, s[20:21]
	s_cbranch_vccz .LBB0_1154
	s_barrier
